# write-through (sc1) for the 16-byte stores of the norm phases and of the GEMM phases (weight conversion, ACT); no L2 write-back at barriers that follow phases whose stores are all write-through
# speedup vs baseline: 1.0121x; 1.0121x over previous
.LBB0_479:
	v_add_u32_e32 v35, 0x400, v42
	ds_read2_b32 v[60:61], v35 offset1:65
	ds_read2_b32 v[62:63], v35 offset0:130 offset1:195
	v_add_u32_e32 v35, 0x800, v42
	s_ashr_i32 s8, s19, 31
	ds_read2_b32 v[64:65], v35 offset0:4 offset1:69
	ds_read2_b32 v[66:67], v35 offset0:134 offset1:199
	s_lshr_b32 s8, s8, 28
	s_add_i32 s8, s19, s8
	s_ashr_i32 s9, s8, 4
	s_waitcnt lgkmcnt(3)
	v_cvt_pk_bf16_f32 v60, v60, v61
	s_waitcnt lgkmcnt(2)
	v_cvt_pk_bf16_f32 v61, v62, v63
	s_waitcnt lgkmcnt(1)
	v_cvt_pk_bf16_f32 v62, v64, v65
	v_lshl_or_b32 v64, s9, 6, v41
	s_lshl_b32 s8, s9, 10
	v_ashrrev_i32_e32 v65, 31, v64
	s_sub_i32 s8, s21, s8
	v_lshlrev_b64 v[64:65], 11, v[64:65]
	v_lshl_add_u64 v[64:65], s[2:3], 0, v[64:65]
	s_ashr_i32 s9, s8, 31
	v_lshl_add_u64 v[64:65], s[8:9], 1, v[64:65]
	s_add_i32 s8, s56, s19
	s_waitcnt lgkmcnt(0)
	v_cvt_pk_bf16_f32 v63, v66, v67
	v_lshl_add_u64 v[64:65], v[64:65], 0, v[36:37]
	s_cmpk_gt_i32 s8, 0xff
	global_store_dwordx4 v[64:65], v[60:63], off sc1
	s_cbranch_scc0 .LBB0_482
	s_add_i32 s8, s23, s19
	s_cmpk_gt_i32 s8, 0xff
	s_cbranch_scc0 .LBB0_483

.LBB0_482:
	v_add_u32_e32 v35, 0x4400, v42
	ds_read2_b32 v[60:61], v35 offset0:64 offset1:129
	v_add_u32_e32 v35, 0x4600, v42
	ds_read2_b32 v[62:63], v35 offset0:66 offset1:131
	v_add_u32_e32 v35, 0x4800, v42
	s_ashr_i32 s9, s8, 31
	ds_read2_b32 v[64:65], v35 offset0:68 offset1:133
	s_lshr_b32 s9, s9, 28
	s_add_i32 s9, s8, s9
	s_and_b32 s10, s9, 0x3fffff0
	s_lshl_b32 s9, s9, 2
	v_add_u32_e32 v35, 0x4a00, v42
	s_andn2_b32 s9, s9, 63
	ds_read2_b32 v[66:67], v35 offset0:70 offset1:135
	s_waitcnt lgkmcnt(3)
	v_cvt_pk_bf16_f32 v60, v60, v61
	s_waitcnt lgkmcnt(2)
	v_cvt_pk_bf16_f32 v61, v62, v63
	s_waitcnt lgkmcnt(1)
	v_cvt_pk_bf16_f32 v62, v64, v65
	v_or_b32_e32 v64, s9, v41
	s_sub_i32 s8, s8, s10
	v_ashrrev_i32_e32 v65, 31, v64
	s_lshl_b32 s8, s8, 6
	v_lshlrev_b64 v[64:65], 11, v[64:65]
	v_lshl_add_u64 v[64:65], s[2:3], 0, v[64:65]
	s_ashr_i32 s9, s8, 31
	v_lshl_add_u64 v[64:65], s[8:9], 1, v[64:65]
	s_waitcnt lgkmcnt(0)
	v_cvt_pk_bf16_f32 v63, v66, v67
	v_lshl_add_u64 v[64:65], v[64:65], 0, v[36:37]
	global_store_dwordx4 v[64:65], v[60:63], off sc1
	s_add_i32 s8, s23, s19
	s_cmpk_gt_i32 s8, 0xff
	s_cbranch_scc1 .LBB0_481
.LBB0_483:
	v_add_u32_e32 v35, 0x8400, v42
	ds_read2_b32 v[60:61], v35 offset0:128 offset1:193
	v_add_u32_e32 v35, 0x8800, v42
	s_ashr_i32 s9, s8, 31
	ds_read2_b32 v[62:63], v35 offset0:2 offset1:67
	ds_read2_b32 v[64:65], v35 offset0:132 offset1:197
	s_lshr_b32 s9, s9, 28
	s_add_i32 s9, s8, s9
	s_and_b32 s10, s9, 0x3fffff0
	s_lshl_b32 s9, s9, 2
	v_add_u32_e32 v35, 0x8c00, v42
	s_andn2_b32 s9, s9, 63
	ds_read2_b32 v[66:67], v35 offset0:6 offset1:71
	s_waitcnt lgkmcnt(3)
	v_cvt_pk_bf16_f32 v60, v60, v61
	s_waitcnt lgkmcnt(2)
	v_cvt_pk_bf16_f32 v61, v62, v63
	s_waitcnt lgkmcnt(1)
	v_cvt_pk_bf16_f32 v62, v64, v65
	v_or_b32_e32 v64, s9, v41
	s_sub_i32 s8, s8, s10
	v_ashrrev_i32_e32 v65, 31, v64
	s_lshl_b32 s8, s8, 6
	v_lshlrev_b64 v[64:65], 11, v[64:65]
	v_lshl_add_u64 v[64:65], s[2:3], 0, v[64:65]
	s_ashr_i32 s9, s8, 31
	v_lshl_add_u64 v[64:65], s[8:9], 1, v[64:65]
	s_waitcnt lgkmcnt(0)
	v_cvt_pk_bf16_f32 v63, v66, v67
	v_lshl_add_u64 v[64:65], v[64:65], 0, v[36:37]
	global_store_dwordx4 v[64:65], v[60:63], off sc1
	s_add_i32 s8, s24, s19
	s_cmpk_gt_i32 s8, 0xff
	s_cbranch_scc1 .LBB0_446
.LBB0_484:
	v_add_u32_e32 v35, 0xc600, v42
	ds_read2_b32 v[60:61], v35 offset0:64 offset1:129
	v_add_u32_e32 v35, 0xc800, v42
	ds_read2_b32 v[62:63], v35 offset0:66 offset1:131
	v_add_u32_e32 v35, 0xca00, v42
	s_ashr_i32 s9, s8, 31
	ds_read2_b32 v[64:65], v35 offset0:68 offset1:133
	s_lshr_b32 s9, s9, 28
	s_add_i32 s9, s8, s9
	s_and_b32 s10, s9, 0x3fffff0
	s_lshl_b32 s9, s9, 2
	v_add_u32_e32 v35, 0xcc00, v42
	s_andn2_b32 s9, s9, 63
	ds_read2_b32 v[66:67], v35 offset0:70 offset1:135
	s_waitcnt lgkmcnt(3)
	v_cvt_pk_bf16_f32 v60, v60, v61
	s_waitcnt lgkmcnt(2)
	v_cvt_pk_bf16_f32 v61, v62, v63
	s_waitcnt lgkmcnt(1)
	v_cvt_pk_bf16_f32 v62, v64, v65
	v_or_b32_e32 v64, s9, v41
	s_sub_i32 s8, s8, s10
	v_ashrrev_i32_e32 v65, 31, v64
	s_lshl_b32 s8, s8, 6
	v_lshlrev_b64 v[64:65], 11, v[64:65]
	v_lshl_add_u64 v[64:65], s[2:3], 0, v[64:65]
	s_ashr_i32 s9, s8, 31
	v_lshl_add_u64 v[64:65], s[8:9], 1, v[64:65]
	s_waitcnt lgkmcnt(0)
	v_cvt_pk_bf16_f32 v63, v66, v67
	v_lshl_add_u64 v[64:65], v[64:65], 0, v[36:37]
	global_store_dwordx4 v[64:65], v[60:63], off sc1
	s_branch .LBB0_446

.LBB0_552:
	s_ashr_i32 s8, s16, 31
	s_lshr_b32 s8, s8, 28
	s_add_i32 s8, s16, s8
	s_ashr_i32 s9, s8, 4
	v_add_u32_e32 v35, 0x400, v42
	s_lshl_b32 s8, s9, 10
	ds_read2_b32 v[60:61], v35 offset1:65
	ds_read2_b32 v[62:63], v35 offset0:130 offset1:195
	v_add_u32_e32 v35, 0x800, v42
	s_lshl_b32 s10, s9, 6
	s_lshl_b32 s9, s9, 7
	ds_read2_b32 v[64:65], v35 offset0:4 offset1:69
	ds_read2_b32 v[66:67], v35 offset0:134 offset1:199
	s_or_b32 s11, s9, 0x80
	s_sub_i32 s8, s15, s8
	s_addk_i32 s11, 0xea00
	s_and_b32 s9, s9, 0xffffff00
	s_cmpk_lt_i32 s16, 0x2c0
	s_cselect_b32 s9, s9, s11
	v_and_or_b32 v35, s10, 64, v41
	s_waitcnt lgkmcnt(3)
	v_cvt_pk_bf16_f32 v60, v60, v61
	s_waitcnt lgkmcnt(2)
	v_cvt_pk_bf16_f32 v61, v62, v63
	s_waitcnt lgkmcnt(1)
	v_cvt_pk_bf16_f32 v62, v64, v65
	v_or_b32_e32 v64, s9, v35
	v_ashrrev_i32_e32 v65, 31, v64
	v_lshlrev_b64 v[64:65], 11, v[64:65]
	v_lshl_add_u64 v[64:65], s[2:3], 0, v[64:65]
	s_ashr_i32 s9, s8, 31
	v_lshl_add_u64 v[64:65], s[8:9], 1, v[64:65]
	s_add_i32 s8, s56, s16
	s_waitcnt lgkmcnt(0)
	v_cvt_pk_bf16_f32 v63, v66, v67
	v_lshl_add_u64 v[64:65], v[64:65], 0, v[36:37]
	s_cmpk_gt_i32 s8, 0x57f
	global_store_dwordx4 v[64:65], v[60:63], off sc1
	s_cbranch_scc0 .LBB0_555
	s_add_i32 s8, s18, s16
	s_cmpk_gt_i32 s8, 0x57f
	s_cbranch_scc0 .LBB0_556

.LBB0_555:
	s_ashr_i32 s9, s8, 31
	s_lshr_b32 s9, s9, 28
	s_add_i32 s9, s8, s9
	v_add_u32_e32 v35, 0x4400, v42
	s_ashr_i32 s11, s9, 4
	s_and_b32 s9, s9, 0x3fffff0
	ds_read2_b32 v[60:61], v35 offset0:64 offset1:129
	v_add_u32_e32 v35, 0x4600, v42
	s_sub_i32 s9, s8, s9
	ds_read2_b32 v[62:63], v35 offset0:66 offset1:131
	v_add_u32_e32 v35, 0x4800, v42
	s_lshl_b32 s10, s9, 6
	ds_read2_b32 v[64:65], v35 offset0:68 offset1:133
	s_lshl_b32 s9, s11, 6
	s_lshl_b32 s11, s11, 7
	s_and_b32 s12, s11, 0xffffff00
	s_bitset1_b32 s11, 7
	s_addk_i32 s11, 0xea00
	v_add_u32_e32 v35, 0x4a00, v42
	s_cmpk_lt_i32 s8, 0x2c0
	ds_read2_b32 v[66:67], v35 offset0:70 offset1:135
	s_cselect_b32 s8, s12, s11
	v_and_or_b32 v35, s9, 64, v41
	s_waitcnt lgkmcnt(3)
	v_cvt_pk_bf16_f32 v60, v60, v61
	s_waitcnt lgkmcnt(2)
	v_cvt_pk_bf16_f32 v61, v62, v63
	s_waitcnt lgkmcnt(1)
	v_cvt_pk_bf16_f32 v62, v64, v65
	v_or_b32_e32 v64, s8, v35
	v_ashrrev_i32_e32 v65, 31, v64
	v_lshlrev_b64 v[64:65], 11, v[64:65]
	v_lshl_add_u64 v[64:65], s[2:3], 0, v[64:65]
	s_ashr_i32 s11, s10, 31
	v_lshl_add_u64 v[64:65], s[10:11], 1, v[64:65]
	s_waitcnt lgkmcnt(0)
	v_cvt_pk_bf16_f32 v63, v66, v67
	v_lshl_add_u64 v[64:65], v[64:65], 0, v[36:37]
	global_store_dwordx4 v[64:65], v[60:63], off sc1
	s_add_i32 s8, s18, s16
	s_cmpk_gt_i32 s8, 0x57f
	s_cbranch_scc1 .LBB0_554
.LBB0_556:
	s_ashr_i32 s9, s8, 31
	s_lshr_b32 s9, s9, 28
	s_add_i32 s9, s8, s9
	s_ashr_i32 s11, s9, 4
	s_and_b32 s9, s9, 0x3fffff0
	v_add_u32_e32 v35, 0x8400, v42
	s_sub_i32 s9, s8, s9
	ds_read2_b32 v[60:61], v35 offset0:128 offset1:193
	v_add_u32_e32 v35, 0x8800, v42
	s_lshl_b32 s10, s9, 6
	ds_read2_b32 v[62:63], v35 offset0:2 offset1:67
	ds_read2_b32 v[64:65], v35 offset0:132 offset1:197
	s_lshl_b32 s9, s11, 6
	s_lshl_b32 s11, s11, 7
	s_and_b32 s12, s11, 0xffffff00
	s_bitset1_b32 s11, 7
	s_addk_i32 s11, 0xea00
	v_add_u32_e32 v35, 0x8c00, v42
	s_cmpk_lt_i32 s8, 0x2c0
	ds_read2_b32 v[66:67], v35 offset0:6 offset1:71
	s_cselect_b32 s8, s12, s11
	v_and_or_b32 v35, s9, 64, v41
	s_waitcnt lgkmcnt(3)
	v_cvt_pk_bf16_f32 v60, v60, v61
	s_waitcnt lgkmcnt(2)
	v_cvt_pk_bf16_f32 v61, v62, v63
	s_waitcnt lgkmcnt(1)
	v_cvt_pk_bf16_f32 v62, v64, v65
	v_or_b32_e32 v64, s8, v35
	v_ashrrev_i32_e32 v65, 31, v64
	v_lshlrev_b64 v[64:65], 11, v[64:65]
	v_lshl_add_u64 v[64:65], s[2:3], 0, v[64:65]
	s_ashr_i32 s11, s10, 31
	v_lshl_add_u64 v[64:65], s[10:11], 1, v[64:65]
	s_waitcnt lgkmcnt(0)
	v_cvt_pk_bf16_f32 v63, v66, v67
	v_lshl_add_u64 v[64:65], v[64:65], 0, v[36:37]
	global_store_dwordx4 v[64:65], v[60:63], off sc1
	s_add_i32 s8, s19, s16
	s_cmpk_gt_i32 s8, 0x57f
	s_cbranch_scc1 .LBB0_519
.LBB0_557:
	s_ashr_i32 s9, s8, 31
	s_lshr_b32 s9, s9, 28
	s_add_i32 s9, s8, s9
	v_add_u32_e32 v35, 0xc600, v42
	s_ashr_i32 s11, s9, 4
	s_and_b32 s9, s9, 0x3fffff0
	ds_read2_b32 v[60:61], v35 offset0:64 offset1:129
	v_add_u32_e32 v35, 0xc800, v42
	s_sub_i32 s9, s8, s9
	ds_read2_b32 v[62:63], v35 offset0:66 offset1:131
	v_add_u32_e32 v35, 0xca00, v42
	s_lshl_b32 s10, s9, 6
	ds_read2_b32 v[64:65], v35 offset0:68 offset1:133
	s_lshl_b32 s9, s11, 6
	s_lshl_b32 s11, s11, 7
	s_and_b32 s12, s11, 0xffffff00
	s_bitset1_b32 s11, 7
	s_addk_i32 s11, 0xea00
	v_add_u32_e32 v35, 0xcc00, v42
	s_cmpk_lt_i32 s8, 0x2c0
	ds_read2_b32 v[66:67], v35 offset0:70 offset1:135
	s_cselect_b32 s8, s12, s11
	v_and_or_b32 v35, s9, 64, v41
	s_waitcnt lgkmcnt(3)
	v_cvt_pk_bf16_f32 v60, v60, v61
	s_waitcnt lgkmcnt(2)
	v_cvt_pk_bf16_f32 v61, v62, v63
	s_waitcnt lgkmcnt(1)
	v_cvt_pk_bf16_f32 v62, v64, v65
	v_or_b32_e32 v64, s8, v35
	v_ashrrev_i32_e32 v65, 31, v64
	v_lshlrev_b64 v[64:65], 11, v[64:65]
	v_lshl_add_u64 v[64:65], s[2:3], 0, v[64:65]
	s_ashr_i32 s11, s10, 31
	v_lshl_add_u64 v[64:65], s[10:11], 1, v[64:65]
	s_waitcnt lgkmcnt(0)
	v_cvt_pk_bf16_f32 v63, v66, v67
	v_lshl_add_u64 v[64:65], v[64:65], 0, v[36:37]
	global_store_dwordx4 v[64:65], v[60:63], off sc1
	s_branch .LBB0_519

.LBB0_559:
	s_and_b32 s2, s30, 0xffffffc0
	s_cmpk_lg_i32 s2, 0xc0
	s_cbranch_scc1 .LBB0_587
	v_mov_b32_e32 v35, 0
	s_waitcnt vmcnt(0)
	ds_read_b64 v[2:3], v35 offset:416
	ds_read_b64 v[4:5], v35 offset:176
	s_mov_b32 s3, 0
	v_and_b32_e32 v36, 60, v1
	v_or_b32_e32 v1, 32, v199
	s_waitcnt lgkmcnt(1)
	v_readfirstlane_b32 s12, v2
	v_readfirstlane_b32 s13, v3
	s_add_u32 s4, s12, 0x4c8000
	s_addc_u32 s5, s13, 0
	s_lshl_b32 s15, s30, 6
	s_add_i32 s14, s30, 0xffffff40
	s_and_b32 s8, s15, 0x3c0
	s_lshl_b32 s2, s14, 2
	v_or_b32_e32 v51, s8, v199
	s_waitcnt lgkmcnt(0)
	v_readfirstlane_b32 s6, v4
	v_readfirstlane_b32 s7, v5
	s_and_b32 s17, s2, 0xc0
	v_lshlrev_b32_e32 v34, 12, v51
	v_lshl_add_u64 v[26:27], s[6:7], 0, v[34:35]
	s_lshl_b32 s2, s17, 2
	v_lshl_add_u64 v[2:3], v[26:27], 0, s[2:3]
	v_lshlrev_b32_e32 v34, 2, v36
	v_or_b32_e32 v53, s8, v1
	v_lshl_add_u64 v[10:11], v[2:3], 0, v[34:35]
	v_lshlrev_b32_e32 v2, 12, v53
	v_mov_b32_e32 v3, v35
	v_lshl_add_u64 v[30:31], s[6:7], 0, v[2:3]
	s_lshl_b32 s16, s30, 2
	s_lshl_b32 s10, s30, 4
	v_lshl_add_u64 v[2:3], v[30:31], 0, s[2:3]
	s_and_b32 s6, s10, 0x700
	s_mov_b32 s7, s3
	s_add_i32 s8, s16, 0x300
	v_lshl_add_u64 v[12:13], v[2:3], 0, v[34:35]
	global_load_dwordx4 v[2:5], v[10:11], off
	global_load_dwordx4 v[6:9], v[12:13], off
	v_lshl_add_u64 v[10:11], v[26:27], 0, s[6:7]
	s_and_b32 s8, s8, 0x2c0
	v_lshl_add_u64 v[18:19], v[10:11], 0, v[34:35]
	v_lshl_add_u64 v[10:11], v[30:31], 0, s[6:7]
	s_lshl_b32 s8, s8, 2
	s_mov_b32 s9, s3
	v_lshl_add_u64 v[20:21], v[10:11], 0, v[34:35]
	global_load_dwordx4 v[10:13], v[18:19], off
	global_load_dwordx4 v[14:17], v[20:21], off
	v_lshl_add_u64 v[18:19], v[26:27], 0, s[8:9]
	v_lshl_add_u64 v[28:29], v[18:19], 0, v[34:35]
	v_lshl_add_u64 v[18:19], v[30:31], 0, s[8:9]
	v_lshl_add_u64 v[32:33], v[18:19], 0, v[34:35]
	global_load_dwordx4 v[18:21], v[28:29], off
	global_load_dwordx4 v[22:25], v[32:33], off
	s_and_b32 s10, s10, 0xf00
	s_mov_b32 s11, s3
	v_lshl_add_u64 v[26:27], v[26:27], 0, s[10:11]
	v_lshl_add_u64 v[26:27], v[26:27], 0, v[34:35]
	global_load_dwordx4 v[26:29], v[26:27], off
	v_lshl_add_u64 v[30:31], v[30:31], 0, s[10:11]
	v_lshl_add_u64 v[30:31], v[30:31], 0, v[34:35]
	global_load_dwordx4 v[30:33], v[30:31], off
	s_movk_i32 s18, 0x104
	v_add_u32_e32 v58, 0, v34
	v_mad_u32_u24 v37, v199, s18, v58
	v_add_u32_e32 v38, 0x400, v37
	v_add_u32_e32 v39, 0x408, v37
	v_add_u32_e32 v40, 0x2480, v37
	v_add_u32_e32 v41, 0x2488, v37
	v_add_u32_e32 v42, 0x4500, v37
	v_add_u32_e32 v43, 0x4508, v37
	v_add_u32_e32 v44, 0x6580, v37
	v_add_u32_e32 v45, 0x6588, v37
	v_add_u32_e32 v46, 0x8600, v37
	v_add_u32_e32 v47, 0x8608, v37
	v_add_u32_e32 v48, 0xa680, v37
	v_add_u32_e32 v49, 0xa688, v37
	v_add_u32_e32 v50, 0xc700, v37
	v_add_u32_e32 v52, 0xc708, v37
	v_add_u32_e32 v54, 0xe780, v37
	v_add_u32_e32 v37, 0xe788, v37
	s_mov_b32 s19, s3
	s_waitcnt vmcnt(7)
	ds_write2_b32 v38, v2, v3 offset1:1
	ds_write2_b32 v39, v4, v5 offset1:1
	s_waitcnt vmcnt(6)
	ds_write2_b32 v40, v6, v7 offset1:1
	ds_write2_b32 v41, v8, v9 offset1:1
	s_waitcnt vmcnt(5)
	ds_write2_b32 v42, v10, v11 offset1:1
	ds_write2_b32 v43, v12, v13 offset1:1
	s_waitcnt vmcnt(4)
	ds_write2_b32 v44, v14, v15 offset1:1
	ds_write2_b32 v45, v16, v17 offset1:1
	s_waitcnt vmcnt(3)
	ds_write2_b32 v46, v18, v19 offset1:1
	ds_write2_b32 v47, v20, v21 offset1:1
	s_waitcnt vmcnt(2)
	ds_write2_b32 v48, v22, v23 offset1:1
	ds_write2_b32 v49, v24, v25 offset1:1
	s_waitcnt vmcnt(1)
	ds_write2_b32 v50, v26, v27 offset1:1
	ds_write2_b32 v52, v28, v29 offset1:1
	s_waitcnt vmcnt(0)
	ds_write2_b32 v54, v30, v31 offset1:1
	ds_write2_b32 v37, v32, v33 offset1:1
	v_lshlrev_b32_e32 v2, 3, v0
	v_lshrrev_b32_e32 v37, 3, v0
	v_and_b32_e32 v52, 56, v2
	v_mul_u32_u24_e32 v2, 0x104, v52
	v_lshlrev_b32_e32 v3, 2, v37
	v_add3_u32 v20, 0, v2, v3
	v_add_u32_e32 v38, 0x400, v20
	s_waitcnt lgkmcnt(0)
	s_barrier
	ds_read2_b32 v[2:3], v38 offset1:65
	ds_read2_b32 v[4:5], v38 offset0:130 offset1:195
	v_add_u32_e32 v39, 0x800, v20
	ds_read2_b32 v[6:7], v39 offset0:4 offset1:69
	ds_read2_b32 v[8:9], v39 offset0:134 offset1:199
	v_add_u32_e32 v40, 0x4400, v20
	s_waitcnt lgkmcnt(3)
	v_cvt_pk_bf16_f32 v2, v2, v3
	s_waitcnt lgkmcnt(2)
	v_cvt_pk_bf16_f32 v3, v4, v5
	s_waitcnt lgkmcnt(1)
	v_cvt_pk_bf16_f32 v4, v6, v7
	v_or_b32_e32 v6, s17, v37
	v_add_u32_e32 v41, 0x4600, v20
	v_add_u32_e32 v42, 0x4800, v20
	v_add_u32_e32 v43, 0x4a00, v20
	v_lshlrev_b32_e32 v6, 11, v6
	v_mov_b32_e32 v7, v35
	s_lshl_b32 s17, s14, 7
	ds_read2_b32 v[12:13], v40 offset0:64 offset1:129
	ds_read2_b32 v[14:15], v41 offset0:66 offset1:131
	ds_read2_b32 v[16:17], v42 offset0:68 offset1:133
	ds_read2_b32 v[18:19], v43 offset0:70 offset1:135
	s_waitcnt lgkmcnt(4)
	v_cvt_pk_bf16_f32 v5, v8, v9
	v_lshl_add_u64 v[8:9], s[4:5], 0, v[6:7]
	s_and_b32 s18, s17, 0x780
	v_lshl_add_u64 v[8:9], v[8:9], 0, s[18:19]
	v_lshlrev_b32_e32 v10, 1, v52
	v_mov_b32_e32 v11, v35
	v_lshl_add_u64 v[8:9], v[8:9], 0, v[10:11]
	global_store_dwordx4 v[8:9], v[2:5], off sc1
	v_add_u32_e32 v44, 0x8400, v20
	v_add_u32_e32 v45, 0x8800, v20
	v_add_u32_e32 v46, 0x8c00, v20
	s_waitcnt lgkmcnt(3)
	v_cvt_pk_bf16_f32 v2, v12, v13
	s_waitcnt lgkmcnt(2)
	v_cvt_pk_bf16_f32 v3, v14, v15
	s_waitcnt lgkmcnt(1)
	v_cvt_pk_bf16_f32 v4, v16, v17
	s_waitcnt lgkmcnt(0)
	v_cvt_pk_bf16_f32 v5, v18, v19
	ds_read2_b32 v[12:13], v44 offset0:128 offset1:193
	ds_read2_b32 v[14:15], v45 offset0:2 offset1:67
	ds_read2_b32 v[16:17], v45 offset0:132 offset1:197
	ds_read2_b32 v[18:19], v46 offset0:6 offset1:71
	v_or_b32_e32 v8, 0x80000, v6
	v_mov_b32_e32 v9, v35
	v_lshl_add_u64 v[8:9], s[4:5], 0, v[8:9]
	v_lshl_add_u64 v[8:9], v[8:9], 0, s[18:19]
	v_lshl_add_u64 v[8:9], v[8:9], 0, v[10:11]
	v_add_u32_e32 v47, 0xc600, v20
	v_add_u32_e32 v48, 0xc800, v20
	v_add_u32_e32 v49, 0xca00, v20
	v_add_u32_e32 v50, 0xcc00, v20
	global_store_dwordx4 v[8:9], v[2:5], off sc1
	v_or_b32_e32 v8, 0x100000, v6
	v_mov_b32_e32 v9, v35
	s_waitcnt lgkmcnt(3)
	v_cvt_pk_bf16_f32 v2, v12, v13
	s_waitcnt lgkmcnt(2)
	v_cvt_pk_bf16_f32 v3, v14, v15
	s_waitcnt lgkmcnt(1)
	v_cvt_pk_bf16_f32 v4, v16, v17
	s_waitcnt lgkmcnt(0)
	v_cvt_pk_bf16_f32 v5, v18, v19
	ds_read2_b32 v[12:13], v47 offset0:64 offset1:129
	ds_read2_b32 v[14:15], v48 offset0:66 offset1:131
	ds_read2_b32 v[16:17], v49 offset0:68 offset1:133
	ds_read2_b32 v[18:19], v50 offset0:70 offset1:135
	v_lshl_add_u64 v[8:9], s[4:5], 0, v[8:9]
	v_or_b32_e32 v6, 0x180000, v6
	v_lshl_add_u64 v[8:9], v[8:9], 0, s[18:19]
	v_lshl_add_u64 v[6:7], s[4:5], 0, v[6:7]
	v_lshl_add_u64 v[8:9], v[8:9], 0, v[10:11]
	v_lshl_add_u64 v[6:7], v[6:7], 0, s[18:19]
	global_store_dwordx4 v[8:9], v[2:5], off sc1
	v_lshl_add_u64 v[6:7], v[6:7], 0, v[10:11]
	s_movk_i32 s17, 0x5800
	s_waitcnt lgkmcnt(3)
	v_cvt_pk_bf16_f32 v2, v12, v13
	s_waitcnt lgkmcnt(2)
	v_cvt_pk_bf16_f32 v3, v14, v15
	s_waitcnt lgkmcnt(1)
	v_cvt_pk_bf16_f32 v4, v16, v17
	s_waitcnt lgkmcnt(0)
	v_cvt_pk_bf16_f32 v5, v18, v19
	global_store_dwordx4 v[6:7], v[2:5], off sc1
	s_barrier
	ds_read_b64 v[2:3], v35 offset:184
	s_waitcnt lgkmcnt(0)
	v_readfirstlane_b32 s4, v2
	v_readfirstlane_b32 s5, v3
	s_nop 1
	v_mov_b64_e32 v[2:3], s[4:5]
	v_mad_u64_u32 v[26:27], s[18:19], v51, s17, v[2:3]
	v_lshl_add_u64 v[4:5], v[26:27], 0, s[2:3]
	v_mad_u64_u32 v[2:3], s[18:19], v53, s17, v[2:3]
	v_lshl_add_u64 v[10:11], v[4:5], 0, v[34:35]
	v_lshl_add_u64 v[2:3], v[2:3], 0, s[2:3]
	v_lshl_add_u64 v[12:13], v[2:3], 0, v[34:35]
	global_load_dwordx4 v[2:5], v[10:11], off
	global_load_dwordx4 v[6:9], v[12:13], off
	v_lshl_add_u64 v[10:11], v[26:27], 0, s[6:7]
	v_lshl_add_u64 v[18:19], v[10:11], 0, v[34:35]
	v_mul_u32_u24_e32 v10, 0x5800, v53
	v_mov_b32_e32 v11, v35
	v_lshl_add_u64 v[28:29], s[4:5], 0, v[10:11]
	v_lshl_add_u64 v[10:11], v[28:29], 0, s[6:7]
	v_lshl_add_u64 v[20:21], v[10:11], 0, v[34:35]
	global_load_dwordx4 v[10:13], v[18:19], off
	global_load_dwordx4 v[14:17], v[20:21], off
	v_lshl_add_u64 v[18:19], v[26:27], 0, s[8:9]
	v_lshl_add_u64 v[30:31], v[18:19], 0, v[34:35]
	v_lshl_add_u64 v[18:19], v[28:29], 0, s[8:9]
	v_lshl_add_u64 v[26:27], v[26:27], 0, s[10:11]
	v_lshl_add_u64 v[32:33], v[18:19], 0, v[34:35]
	v_lshl_add_u64 v[54:55], v[26:27], 0, v[34:35]
	v_lshl_add_u64 v[26:27], v[28:29], 0, s[10:11]
	global_load_dwordx4 v[18:21], v[30:31], off
	global_load_dwordx4 v[22:25], v[32:33], off
	v_lshl_add_u64 v[56:57], v[26:27], 0, v[34:35]
	global_load_dwordx4 v[26:29], v[54:55], off
	global_load_dwordx4 v[30:33], v[56:57], off
	s_add_u32 s6, s12, 0x8c8000
	v_mul_u32_u24_e32 v34, 0x104, v199
	s_addc_u32 s7, s13, 0
	s_lshr_b32 s2, s14, 4
	s_add_i32 s10, s15, 0xffffd000
	s_lshl_b32 s11, s2, 7
	s_lshl_b32 s12, s2, 6
	s_add_i32 s13, s16, 0x400
	v_add_u32_e32 v51, v58, v34
	v_lshlrev_b32_e32 v34, 1, v52
	s_mov_b32 s14, s30
	s_branch .LBB0_562

.LBB0_581:
	s_or_b32 s8, s11, 0x80
	ds_read2_b32 v[52:53], v38 offset1:65
	ds_read2_b32 v[54:55], v38 offset0:130 offset1:195
	ds_read2_b32 v[56:57], v39 offset0:4 offset1:69
	ds_read2_b32 v[58:59], v39 offset0:134 offset1:199
	s_addk_i32 s8, 0xea00
	s_and_b32 s9, s11, 0xffffff00
	s_cmpk_lt_i32 s15, 0x2c0
	s_cselect_b32 s8, s9, s8
	s_and_b32 s9, s12, 64
	s_add_i32 s8, s8, s9
	s_waitcnt lgkmcnt(3)
	v_cvt_pk_bf16_f32 v52, v52, v53
	s_waitcnt lgkmcnt(2)
	v_cvt_pk_bf16_f32 v53, v54, v55
	s_waitcnt lgkmcnt(1)
	v_cvt_pk_bf16_f32 v54, v56, v57
	v_add_u32_e32 v56, s8, v37
	v_ashrrev_i32_e32 v57, 31, v56
	v_lshlrev_b64 v[56:57], 11, v[56:57]
	v_lshl_add_u64 v[56:57], s[6:7], 0, v[56:57]
	v_lshl_add_u64 v[56:57], s[2:3], 1, v[56:57]
	s_waitcnt lgkmcnt(0)
	v_cvt_pk_bf16_f32 v55, v58, v59
	v_lshl_add_u64 v[56:57], v[56:57], 0, v[34:35]
	s_cmpk_gt_i32 s15, 0x53f
	global_store_dwordx4 v[56:57], v[52:55], off sc1
	s_cbranch_scc0 .LBB0_584
	s_cmpk_gt_i32 s15, 0x4ff
	s_cbranch_scc0 .LBB0_585

.LBB0_584:
	s_add_i32 s8, s14, 0xffffff80
	ds_read2_b32 v[52:53], v40 offset0:64 offset1:129
	ds_read2_b32 v[54:55], v41 offset0:66 offset1:131
	ds_read2_b32 v[56:57], v42 offset0:68 offset1:133
	ds_read2_b32 v[58:59], v43 offset0:70 offset1:135
	s_lshl_b32 s9, s8, 2
	s_lshl_b32 s8, s8, 3
	s_and_b32 s8, s8, 0xffffff00
	s_add_i32 s16, s8, 0xffffea80
	s_cmpk_lt_i32 s15, 0x280
	s_waitcnt lgkmcnt(3)
	v_cvt_pk_bf16_f32 v52, v52, v53
	s_waitcnt lgkmcnt(2)
	v_cvt_pk_bf16_f32 v53, v54, v55
	s_waitcnt lgkmcnt(1)
	v_cvt_pk_bf16_f32 v54, v56, v57
	s_cselect_b32 s8, s8, s16
	v_and_or_b32 v56, s9, 64, v37
	v_or_b32_e32 v56, s8, v56
	v_ashrrev_i32_e32 v57, 31, v56
	v_lshlrev_b64 v[56:57], 11, v[56:57]
	v_lshl_add_u64 v[56:57], s[6:7], 0, v[56:57]
	v_lshl_add_u64 v[56:57], s[2:3], 1, v[56:57]
	s_waitcnt lgkmcnt(0)
	v_cvt_pk_bf16_f32 v55, v58, v59
	v_lshl_add_u64 v[56:57], v[56:57], 0, v[34:35]
	global_store_dwordx4 v[56:57], v[52:55], off sc1
	s_cmpk_gt_i32 s15, 0x4ff
	s_cbranch_scc1 .LBB0_583
.LBB0_585:
	s_sub_i32 s8, s14, 64
	ds_read2_b32 v[52:53], v44 offset0:128 offset1:193
	ds_read2_b32 v[54:55], v45 offset0:2 offset1:67
	ds_read2_b32 v[56:57], v45 offset0:132 offset1:197
	ds_read2_b32 v[58:59], v46 offset0:6 offset1:71
	s_lshl_b32 s9, s8, 2
	s_lshl_b32 s8, s8, 3
	s_and_b32 s8, s8, 0xffffff00
	s_add_i32 s16, s8, 0xffffea80
	s_cmpk_lt_i32 s15, 0x240
	s_waitcnt lgkmcnt(3)
	v_cvt_pk_bf16_f32 v52, v52, v53
	s_waitcnt lgkmcnt(2)
	v_cvt_pk_bf16_f32 v53, v54, v55
	s_waitcnt lgkmcnt(1)
	v_cvt_pk_bf16_f32 v54, v56, v57
	s_cselect_b32 s8, s8, s16
	v_and_or_b32 v56, s9, 64, v37
	v_or_b32_e32 v56, s8, v56
	v_ashrrev_i32_e32 v57, 31, v56
	v_lshlrev_b64 v[56:57], 11, v[56:57]
	v_lshl_add_u64 v[56:57], s[6:7], 0, v[56:57]
	v_lshl_add_u64 v[56:57], s[2:3], 1, v[56:57]
	s_waitcnt lgkmcnt(0)
	v_cvt_pk_bf16_f32 v55, v58, v59
	v_lshl_add_u64 v[56:57], v[56:57], 0, v[34:35]
	global_store_dwordx4 v[56:57], v[52:55], off sc1
	s_cmpk_gt_i32 s15, 0x4bf
	s_cbranch_scc1 .LBB0_561
.LBB0_586:
	ds_read2_b32 v[52:53], v47 offset0:64 offset1:129
	ds_read2_b32 v[54:55], v48 offset0:66 offset1:131
	ds_read2_b32 v[56:57], v49 offset0:68 offset1:133
	ds_read2_b32 v[58:59], v50 offset0:70 offset1:135
	s_lshl_b32 s9, s14, 3
	s_and_b32 s9, s9, 0xffffff00
	s_lshl_b32 s8, s14, 2
	s_add_i32 s16, s9, 0xffffea80
	s_cmpk_lt_i32 s15, 0x200
	s_waitcnt lgkmcnt(3)
	v_cvt_pk_bf16_f32 v52, v52, v53
	s_waitcnt lgkmcnt(2)
	v_cvt_pk_bf16_f32 v53, v54, v55
	s_waitcnt lgkmcnt(1)
	v_cvt_pk_bf16_f32 v54, v56, v57
	s_cselect_b32 s9, s9, s16
	v_and_or_b32 v56, s8, 64, v37
	v_or_b32_e32 v56, s9, v56
	v_ashrrev_i32_e32 v57, 31, v56
	v_lshlrev_b64 v[56:57], 11, v[56:57]
	v_lshl_add_u64 v[56:57], s[6:7], 0, v[56:57]
	v_lshl_add_u64 v[56:57], s[2:3], 1, v[56:57]
	s_waitcnt lgkmcnt(0)
	v_cvt_pk_bf16_f32 v55, v58, v59
	v_lshl_add_u64 v[56:57], v[56:57], 0, v[34:35]
	global_store_dwordx4 v[56:57], v[52:55], off sc1
	s_branch .LBB0_561

.Lxb2_go:
	v_add_u32_e32 v246, 0x1400, v245
	global_atomic_add v248, v246, v247, s[60:61] sc0
	v_add_u32_e32 v249, 1, v244
	ds_write_b32 v241, v249 offset:8
	v_mul_lo_u32 v250, v249, v242
	v_mul_lo_u32 v251, v249, v243
	v_add_u32_e32 v253, 0x2400, v245
	v_mov_b32_e32 v252, 0
	s_waitcnt vmcnt(0)
	buffer_inv sc1
	v_add_u32_e32 v248, 1, v248
	v_cmp_eq_u32_e32 vcc, v248, v250
	s_cbranch_vccz .Lxb2_wait
	s_waitcnt vmcnt(0)
	v_mov_b32_e32 v246, 0x3400
	global_atomic_add v248, v246, v247, s[60:61] sc0
	s_waitcnt vmcnt(0)
	v_add_u32_e32 v248, 1, v248

.LBB0_1249:
	v_add_u32_e32 v37, 0x400, v40
	ds_read2_b32 v[60:61], v37 offset1:65
	ds_read2_b32 v[62:63], v37 offset0:130 offset1:195
	v_add_u32_e32 v37, 0x800, v40
	s_mul_hi_i32 s8, s14, 0x2e8ba2e9
	ds_read2_b32 v[64:65], v37 offset0:4 offset1:69
	ds_read2_b32 v[66:67], v37 offset0:134 offset1:199
	s_lshr_b32 s9, s8, 31
	s_ashr_i32 s8, s8, 3
	s_add_i32 s9, s8, s9
	s_mul_i32 s8, s9, 0xfffff500
	s_add_i32 s8, s16, s8
	s_waitcnt lgkmcnt(3)
	v_cvt_pk_bf16_f32 v60, v60, v61
	s_waitcnt lgkmcnt(2)
	v_cvt_pk_bf16_f32 v61, v62, v63
	s_waitcnt lgkmcnt(1)
	v_cvt_pk_bf16_f32 v62, v64, v65
	v_lshl_or_b32 v37, s9, 6, v39
	v_mov_b64_e32 v[64:65], s[2:3]
	v_mad_i64_i32 v[64:65], s[10:11], v37, s24, v[64:65]
	s_ashr_i32 s9, s8, 31
	v_lshl_add_u64 v[64:65], s[8:9], 1, v[64:65]
	s_add_i32 s8, s56, s14
	s_waitcnt lgkmcnt(0)
	v_cvt_pk_bf16_f32 v63, v66, v67
	v_lshl_add_u64 v[64:65], v[64:65], 0, v[34:35]
	s_cmpk_gt_i32 s8, 0x2bf
	global_store_dwordx4 v[64:65], v[60:63], off sc1
	s_cbranch_scc0 .LBB0_1252
	s_add_i32 s8, s18, s14
	s_cmpk_gt_i32 s8, 0x2bf
	s_cbranch_scc0 .LBB0_1253

.LBB0_1252:
	v_add_u32_e32 v37, 0x4400, v40
	ds_read2_b32 v[60:61], v37 offset0:64 offset1:129
	v_add_u32_e32 v37, 0x4600, v40
	ds_read2_b32 v[62:63], v37 offset0:66 offset1:131
	v_add_u32_e32 v37, 0x4800, v40
	s_mul_hi_i32 s9, s8, 0x2e8ba2e9
	ds_read2_b32 v[64:65], v37 offset0:68 offset1:133
	s_lshr_b32 s10, s9, 31
	s_ashr_i32 s9, s9, 3
	s_add_i32 s9, s9, s10
	v_add_u32_e32 v37, 0x4a00, v40
	s_mul_i32 s10, s9, 44
	ds_read2_b32 v[66:67], v37 offset0:70 offset1:135
	s_sub_i32 s8, s8, s10
	s_lshl_b32 s8, s8, 6
	s_waitcnt lgkmcnt(3)
	v_cvt_pk_bf16_f32 v60, v60, v61
	s_waitcnt lgkmcnt(2)
	v_cvt_pk_bf16_f32 v61, v62, v63
	s_waitcnt lgkmcnt(1)
	v_cvt_pk_bf16_f32 v62, v64, v65
	v_lshl_or_b32 v37, s9, 6, v39
	v_mov_b64_e32 v[64:65], s[2:3]
	v_mad_i64_i32 v[64:65], s[10:11], v37, s24, v[64:65]
	s_ashr_i32 s9, s8, 31
	v_lshl_add_u64 v[64:65], s[8:9], 1, v[64:65]
	s_waitcnt lgkmcnt(0)
	v_cvt_pk_bf16_f32 v63, v66, v67
	v_lshl_add_u64 v[64:65], v[64:65], 0, v[34:35]
	global_store_dwordx4 v[64:65], v[60:63], off sc1
	s_add_i32 s8, s18, s14
	s_cmpk_gt_i32 s8, 0x2bf
	s_cbranch_scc1 .LBB0_1251
.LBB0_1253:
	v_add_u32_e32 v37, 0x8400, v40
	ds_read2_b32 v[60:61], v37 offset0:128 offset1:193
	v_add_u32_e32 v37, 0x8800, v40
	s_mul_hi_i32 s9, s8, 0x2e8ba2e9
	ds_read2_b32 v[62:63], v37 offset0:2 offset1:67
	ds_read2_b32 v[64:65], v37 offset0:132 offset1:197
	s_lshr_b32 s10, s9, 31
	s_ashr_i32 s9, s9, 3
	s_add_i32 s9, s9, s10
	v_add_u32_e32 v37, 0x8c00, v40
	s_mul_i32 s10, s9, 44
	ds_read2_b32 v[66:67], v37 offset0:6 offset1:71
	s_sub_i32 s8, s8, s10
	s_lshl_b32 s8, s8, 6
	s_waitcnt lgkmcnt(3)
	v_cvt_pk_bf16_f32 v60, v60, v61
	s_waitcnt lgkmcnt(2)
	v_cvt_pk_bf16_f32 v61, v62, v63
	s_waitcnt lgkmcnt(1)
	v_cvt_pk_bf16_f32 v62, v64, v65
	v_lshl_or_b32 v37, s9, 6, v39
	v_mov_b64_e32 v[64:65], s[2:3]
	v_mad_i64_i32 v[64:65], s[10:11], v37, s24, v[64:65]
	s_ashr_i32 s9, s8, 31
	v_lshl_add_u64 v[64:65], s[8:9], 1, v[64:65]
	s_waitcnt lgkmcnt(0)
	v_cvt_pk_bf16_f32 v63, v66, v67
	v_lshl_add_u64 v[64:65], v[64:65], 0, v[34:35]
	global_store_dwordx4 v[64:65], v[60:63], off sc1
	s_add_i32 s8, s19, s14
	s_cmpk_gt_i32 s8, 0x2bf
	s_cbranch_scc1 .LBB0_1216
.LBB0_1254:
	v_add_u32_e32 v37, 0xc600, v40
	ds_read2_b32 v[60:61], v37 offset0:64 offset1:129
	v_add_u32_e32 v37, 0xc800, v40
	ds_read2_b32 v[62:63], v37 offset0:66 offset1:131
	v_add_u32_e32 v37, 0xca00, v40
	s_mul_hi_i32 s9, s8, 0x2e8ba2e9
	ds_read2_b32 v[64:65], v37 offset0:68 offset1:133
	s_lshr_b32 s10, s9, 31
	s_ashr_i32 s9, s9, 3
	s_add_i32 s9, s9, s10
	v_add_u32_e32 v37, 0xcc00, v40
	s_mul_i32 s10, s9, 44
	ds_read2_b32 v[66:67], v37 offset0:70 offset1:135
	s_sub_i32 s8, s8, s10
	s_lshl_b32 s8, s8, 6
	s_waitcnt lgkmcnt(3)
	v_cvt_pk_bf16_f32 v60, v60, v61
	s_waitcnt lgkmcnt(2)
	v_cvt_pk_bf16_f32 v61, v62, v63
	s_waitcnt lgkmcnt(1)
	v_cvt_pk_bf16_f32 v62, v64, v65
	v_lshl_or_b32 v37, s9, 6, v39
	v_mov_b64_e32 v[64:65], s[2:3]
	v_mad_i64_i32 v[64:65], s[10:11], v37, s24, v[64:65]
	s_ashr_i32 s9, s8, 31
	v_lshl_add_u64 v[64:65], s[8:9], 1, v[64:65]
	s_waitcnt lgkmcnt(0)
	v_cvt_pk_bf16_f32 v63, v66, v67
	v_lshl_add_u64 v[64:65], v[64:65], 0, v[34:35]
	global_store_dwordx4 v[64:65], v[60:63], off sc1
	s_branch .LBB0_1216

.LBB0_1279:
	v_add_u32_e32 v43, 0x400, v37
	ds_read2_b32 v[44:45], v43 offset1:65
	ds_read2_b32 v[46:47], v43 offset0:130 offset1:195
	v_add_u32_e32 v43, 0x800, v37
	ds_read2_b32 v[48:49], v43 offset0:4 offset1:69
	ds_read2_b32 v[50:51], v43 offset0:134 offset1:199
	s_mul_hi_u32 s2, s12, 0xba2e8ba3
	s_lshr_b32 s10, s2, 5
	s_mul_i32 s2, s10, 0xb00
	s_waitcnt lgkmcnt(3)
	v_cvt_pk_bf16_f32 v44, v44, v45
	s_waitcnt lgkmcnt(2)
	v_cvt_pk_bf16_f32 v45, v46, v47
	s_waitcnt lgkmcnt(1)
	v_cvt_pk_bf16_f32 v46, v48, v49
	v_lshl_or_b32 v43, s10, 6, v1
	v_mov_b64_e32 v[48:49], s[6:7]
	s_sub_i32 s2, s13, s2
	v_mad_u64_u32 v[48:49], s[10:11], v43, s18, v[48:49]
	v_lshl_add_u64 v[48:49], s[2:3], 1, v[48:49]
	s_waitcnt lgkmcnt(0)
	v_cvt_pk_bf16_f32 v47, v50, v51
	v_lshl_add_u64 v[48:49], v[48:49], 0, v[34:35]
	s_cmpk_gt_i32 s12, 0x27f
	global_store_dwordx4 v[48:49], v[44:47], off sc1
	s_cbranch_scc0 .LBB0_1282
	s_cmpk_gt_i32 s12, 0x23f
	s_cbranch_scc0 .LBB0_1283

.LBB0_1282:
	v_add_u32_e32 v43, 0x4400, v37
	ds_read2_b32 v[44:45], v43 offset0:64 offset1:129
	v_add_u32_e32 v43, 0x4600, v37
	ds_read2_b32 v[46:47], v43 offset0:66 offset1:131
	v_add_u32_e32 v43, 0x4800, v37
	ds_read2_b32 v[48:49], v43 offset0:68 offset1:133
	s_add_i32 s2, s12, 64
	s_mul_hi_u32 s10, s2, 0xba2e8ba3
	v_add_u32_e32 v43, 0x4a00, v37
	s_lshr_b32 s10, s10, 5
	ds_read2_b32 v[50:51], v43 offset0:70 offset1:135
	s_mul_i32 s11, s10, 44
	s_sub_i32 s2, s2, s11
	s_waitcnt lgkmcnt(3)
	v_cvt_pk_bf16_f32 v44, v44, v45
	s_waitcnt lgkmcnt(2)
	v_cvt_pk_bf16_f32 v45, v46, v47
	s_waitcnt lgkmcnt(1)
	v_cvt_pk_bf16_f32 v46, v48, v49
	v_lshl_or_b32 v43, s10, 6, v1
	v_mov_b64_e32 v[48:49], s[6:7]
	v_mad_u64_u32 v[48:49], s[10:11], v43, s18, v[48:49]
	s_lshl_b32 s2, s2, 7
	v_lshl_add_u64 v[48:49], v[48:49], 0, s[2:3]
	s_waitcnt lgkmcnt(0)
	v_cvt_pk_bf16_f32 v47, v50, v51
	v_lshl_add_u64 v[48:49], v[48:49], 0, v[34:35]
	global_store_dwordx4 v[48:49], v[44:47], off sc1
	s_cmpk_gt_i32 s12, 0x23f
	s_cbranch_scc1 .LBB0_1281
.LBB0_1283:
	v_add_u32_e32 v43, 0x8400, v37
	ds_read2_b32 v[44:45], v43 offset0:128 offset1:193
	v_add_u32_e32 v43, 0x8800, v37
	ds_read2_b32 v[46:47], v43 offset0:2 offset1:67
	ds_read2_b32 v[48:49], v43 offset0:132 offset1:197
	s_add_i32 s2, s12, 0x80
	s_mul_hi_u32 s10, s2, 0xba2e8ba3
	v_add_u32_e32 v43, 0x8c00, v37
	s_lshr_b32 s10, s10, 5
	ds_read2_b32 v[50:51], v43 offset0:6 offset1:71
	s_mul_i32 s11, s10, 44
	s_sub_i32 s2, s2, s11
	s_waitcnt lgkmcnt(3)
	v_cvt_pk_bf16_f32 v44, v44, v45
	s_waitcnt lgkmcnt(2)
	v_cvt_pk_bf16_f32 v45, v46, v47
	s_waitcnt lgkmcnt(1)
	v_cvt_pk_bf16_f32 v46, v48, v49
	v_lshl_or_b32 v43, s10, 6, v1
	v_mov_b64_e32 v[48:49], s[6:7]
	v_mad_u64_u32 v[48:49], s[10:11], v43, s18, v[48:49]
	s_lshl_b32 s2, s2, 7
	v_lshl_add_u64 v[48:49], v[48:49], 0, s[2:3]
	s_waitcnt lgkmcnt(0)
	v_cvt_pk_bf16_f32 v47, v50, v51
	v_lshl_add_u64 v[48:49], v[48:49], 0, v[34:35]
	global_store_dwordx4 v[48:49], v[44:47], off sc1
	s_cmpk_gt_i32 s12, 0x1ff
	s_cbranch_scc1 .LBB0_1258
.LBB0_1284:
	v_add_u32_e32 v43, 0xc600, v37
	ds_read2_b32 v[44:45], v43 offset0:64 offset1:129
	v_add_u32_e32 v43, 0xc800, v37
	ds_read2_b32 v[46:47], v43 offset0:66 offset1:131
	v_add_u32_e32 v43, 0xca00, v37
	ds_read2_b32 v[48:49], v43 offset0:68 offset1:133
	s_add_i32 s2, s12, 0xc0
	s_mul_hi_u32 s10, s2, 0xba2e8ba3
	v_add_u32_e32 v43, 0xcc00, v37
	s_lshr_b32 s10, s10, 5
	ds_read2_b32 v[50:51], v43 offset0:70 offset1:135
	s_mul_i32 s11, s10, 44
	s_sub_i32 s2, s2, s11
	s_waitcnt lgkmcnt(3)
	v_cvt_pk_bf16_f32 v44, v44, v45
	s_waitcnt lgkmcnt(2)
	v_cvt_pk_bf16_f32 v45, v46, v47
	s_waitcnt lgkmcnt(1)
	v_cvt_pk_bf16_f32 v46, v48, v49
	v_lshl_or_b32 v43, s10, 6, v1
	v_mov_b64_e32 v[48:49], s[6:7]
	v_mad_u64_u32 v[48:49], s[10:11], v43, s18, v[48:49]
	s_lshl_b32 s2, s2, 7
	v_lshl_add_u64 v[48:49], v[48:49], 0, s[2:3]
	s_waitcnt lgkmcnt(0)
	v_cvt_pk_bf16_f32 v47, v50, v51
	v_lshl_add_u64 v[48:49], v[48:49], 0, v[34:35]
	global_store_dwordx4 v[48:49], v[44:47], off sc1
	s_branch .LBB0_1258

.LBB0_1342:
	s_lshr_b32 s2, s2, 10
	s_mulk_i32 s2, 0x1800
	s_addk_i32 s2, 0x1800
	s_and_b64 s[12:13], s[12:13], exec
	s_cselect_b32 s2, 0, s2
	s_lshl_b64 s[12:13], s[18:19], 11
	v_lshl_add_u64 v[40:41], v[8:9], 0, s[12:13]
	global_load_dwordx2 v[28:29], v[40:41], off
	v_lshl_add_u64 v[42:43], v[10:11], 0, s[12:13]
	s_lshl_b64 s[16:17], s[2:3], 2
	global_load_dwordx2 v[30:31], v[42:43], off
	global_load_dwordx4 v[2:5], v1, s[14:15]
	v_lshl_add_u64 v[44:45], v[12:13], 0, s[16:17]
	global_load_dwordx4 v[24:27], v[44:45], off
	s_lshl_b64 s[18:19], s[18:19], 12
	v_lshl_add_u64 v[46:47], v[14:15], 0, s[18:19]
	v_lshl_add_u64 v[52:53], v[16:17], 0, s[16:17]
	s_add_u32 s4, s4, s6
	s_addc_u32 s5, s5, s7
	s_add_u32 s8, s8, s10
	s_addc_u32 s9, s9, s11
	s_cmpk_lt_i32 s4, 0x1800
	s_waitcnt vmcnt(3)
	v_lshlrev_b32_e32 v32, 16, v28
	v_and_b32_e32 v33, 0xffff0000, v28
	s_waitcnt vmcnt(2)
	v_lshlrev_b32_e32 v34, 16, v30
	v_and_b32_e32 v35, 0xffff0000, v30
	v_lshlrev_b32_e32 v28, 16, v29
	v_and_b32_e32 v29, 0xffff0000, v29
	v_lshlrev_b32_e32 v30, 16, v31
	v_and_b32_e32 v31, 0xffff0000, v31
	v_pk_add_f32 v[32:33], v[32:33], v[34:35]
	v_pk_add_f32 v[28:29], v[28:29], v[30:31]
	s_waitcnt vmcnt(0)
	v_pk_fma_f32 v[2:3], v[24:25], v[32:33], v[2:3]
	v_pk_fma_f32 v[4:5], v[26:27], v[28:29], v[4:5]
	global_store_dwordx4 v[46:47], v[2:5], off sc1
	global_load_dwordx2 v[32:33], v[40:41], off offset:512
	global_load_dwordx2 v[34:35], v[42:43], off offset:512
	global_load_dwordx4 v[24:27], v1, s[14:15] offset:1024
	global_load_dwordx4 v[28:31], v[44:45], off offset:1024
	v_mov_b32_e32 v54, v3
	v_mov_b32_e32 v56, v4
	v_mov_b32_e32 v58, v5
	s_waitcnt vmcnt(3)
	v_lshlrev_b32_e32 v36, 16, v32
	v_and_b32_e32 v37, 0xffff0000, v32
	s_waitcnt vmcnt(2)
	v_lshlrev_b32_e32 v38, 16, v34
	v_and_b32_e32 v39, 0xffff0000, v34
	v_lshlrev_b32_e32 v32, 16, v33
	v_and_b32_e32 v33, 0xffff0000, v33
	v_lshlrev_b32_e32 v34, 16, v35
	v_and_b32_e32 v35, 0xffff0000, v35
	v_pk_add_f32 v[36:37], v[36:37], v[38:39]
	v_pk_add_f32 v[32:33], v[32:33], v[34:35]
	s_waitcnt vmcnt(0)
	v_pk_fma_f32 v[24:25], v[28:29], v[36:37], v[24:25]
	v_pk_fma_f32 v[26:27], v[30:31], v[32:33], v[26:27]
	global_store_dwordx4 v[46:47], v[24:27], off offset:1024 sc1
	global_load_dwordx2 v[36:37], v[40:41], off offset:1024
	global_load_dwordx2 v[38:39], v[42:43], off offset:1024
	global_load_dwordx4 v[28:31], v1, s[14:15] offset:2048
	global_load_dwordx4 v[32:35], v[44:45], off offset:2048
	v_mov_b32_e32 v55, v25
	v_pk_mul_f32 v[54:55], v[54:55], v[54:55]
	v_mov_b32_e32 v57, v26
	v_mov_b32_e32 v59, v27
	s_waitcnt vmcnt(3)
	v_lshlrev_b32_e32 v48, 16, v36
	v_and_b32_e32 v49, 0xffff0000, v36
	s_waitcnt vmcnt(2)
	v_lshlrev_b32_e32 v50, 16, v38
	v_and_b32_e32 v51, 0xffff0000, v38
	v_lshlrev_b32_e32 v36, 16, v37
	v_and_b32_e32 v37, 0xffff0000, v37
	v_lshlrev_b32_e32 v38, 16, v39
	v_and_b32_e32 v39, 0xffff0000, v39
	v_pk_add_f32 v[48:49], v[48:49], v[50:51]
	v_pk_add_f32 v[36:37], v[36:37], v[38:39]
	s_waitcnt vmcnt(0)
	v_pk_fma_f32 v[28:29], v[32:33], v[48:49], v[28:29]
	v_pk_fma_f32 v[30:31], v[34:35], v[36:37], v[30:31]
	global_store_dwordx4 v[46:47], v[28:31], off offset:2048 sc1
	global_load_dwordx2 v[48:49], v[40:41], off offset:1536
	global_load_dwordx2 v[50:51], v[42:43], off offset:1536
	global_load_dwordx4 v[32:35], v1, s[14:15] offset:3072
	global_load_dwordx4 v[36:39], v[44:45], off offset:3072
	s_waitcnt vmcnt(3)
	v_lshlrev_b32_e32 v40, 16, v48
	v_and_b32_e32 v41, 0xffff0000, v48
	s_waitcnt vmcnt(2)
	v_lshlrev_b32_e32 v42, 16, v50
	v_and_b32_e32 v43, 0xffff0000, v50
	v_lshlrev_b32_e32 v44, 16, v49
	v_and_b32_e32 v45, 0xffff0000, v49
	v_lshlrev_b32_e32 v48, 16, v51
	v_and_b32_e32 v49, 0xffff0000, v51
	v_pk_add_f32 v[40:41], v[40:41], v[42:43]
	v_pk_add_f32 v[42:43], v[44:45], v[48:49]
	s_waitcnt vmcnt(0)
	v_pk_fma_f32 v[32:33], v[36:37], v[40:41], v[32:33]
	v_pk_fma_f32 v[34:35], v[38:39], v[42:43], v[34:35]
	global_store_dwordx4 v[46:47], v[32:35], off offset:3072 sc1
	global_load_dwordx4 v[36:39], v[6:7], off
	global_load_dwordx4 v[40:43], v[52:53], off
	v_lshl_add_u64 v[48:49], v[18:19], 0, s[16:17]
	global_load_dwordx4 v[44:47], v[48:49], off
	v_mov_b32_e32 v50, v2
	v_mov_b32_e32 v51, v24
	v_pk_fma_f32 v[50:51], v[50:51], v[50:51], v[54:55]
	v_mov_b32_e32 v54, v30
	v_pk_fma_f32 v[50:51], v[56:57], v[56:57], v[50:51]
	v_mov_b32_e32 v56, v28
	v_pk_fma_f32 v[50:51], v[58:59], v[58:59], v[50:51]
	v_mov_b32_e32 v58, v29
	v_mov_b32_e32 v59, v33
	v_mov_b32_e32 v57, v32
	v_pk_mul_f32 v[58:59], v[58:59], v[58:59]
	v_mov_b32_e32 v55, v34
	v_pk_fma_f32 v[56:57], v[56:57], v[56:57], v[58:59]
	v_add_f32_e32 v23, v50, v51
	v_mov_b32_e32 v50, v31
	v_mov_b32_e32 v51, v35
	v_pk_fma_f32 v[54:55], v[54:55], v[54:55], v[56:57]
	s_nop 0
	v_pk_fma_f32 v[50:51], v[50:51], v[50:51], v[54:55]
	s_nop 0
	v_add_f32_e32 v23, v23, v50
	v_add_f32_e32 v23, v23, v51
	s_nop 1
	v_add_f32_dpp v23, v23, v23 quad_perm:[1,0,3,2] row_mask:0xf bank_mask:0xf bound_ctrl:1
	s_nop 1
	v_add_f32_dpp v23, v23, v23 quad_perm:[2,3,0,1] row_mask:0xf bank_mask:0xf bound_ctrl:1
	s_nop 1
	v_add_f32_dpp v23, v23, v23 row_half_mirror row_mask:0xf bank_mask:0xf bound_ctrl:1
	s_nop 1
	v_add_f32_dpp v23, v23, v23 row_mirror row_mask:0xf bank_mask:0xf bound_ctrl:1
	s_nop 0
	v_readlane_b32 s2, v23, 16
	v_readlane_b32 s16, v23, 48
	v_readlane_b32 s14, v23, 0
	v_readlane_b32 s15, v23, 32
	v_mov_b32_e32 v50, s2
	v_mov_b32_e32 v51, s16
	v_pk_add_f32 v[50:51], s[14:15], v[50:51]
	s_nop 0
	v_add_f32_e32 v23, v50, v51
	v_fmamk_f32 v23, v23, 0x3a800000, v22
	v_mul_f32_e32 v50, 0x4b800000, v23
	v_cmp_gt_f32_e32 vcc, s22, v23
	s_nop 1
	v_cndmask_b32_e32 v23, v23, v50, vcc
	v_rsq_f32_e32 v23, v23
	v_lshl_add_u64 v[50:51], v[20:21], 0, s[12:13]
	v_mul_f32_e32 v54, 0x45800000, v23
	v_cndmask_b32_e32 v54, v23, v54, vcc
	v_pk_mul_f32 v[2:3], v[2:3], v[54:55] op_sel_hi:[1,0]
	v_pk_mul_f32 v[4:5], v[4:5], v[54:55] op_sel_hi:[1,0]
	v_pk_mul_f32 v[24:25], v[24:25], v[54:55] op_sel_hi:[1,0]
	v_pk_mul_f32 v[26:27], v[26:27], v[54:55] op_sel_hi:[1,0]
	v_pk_mul_f32 v[28:29], v[28:29], v[54:55] op_sel_hi:[1,0]
	v_pk_mul_f32 v[30:31], v[30:31], v[54:55] op_sel_hi:[1,0]
	v_pk_mul_f32 v[32:33], v[32:33], v[54:55] op_sel_hi:[1,0]
	v_pk_mul_f32 v[34:35], v[34:35], v[54:55] op_sel_hi:[1,0]
	s_waitcnt vmcnt(2)
	v_pk_mul_f32 v[2:3], v[36:37], v[2:3]
	s_waitcnt vmcnt(1)
	v_pk_add_f32 v[36:37], v[40:41], 1.0 op_sel_hi:[1,0]
	v_pk_mul_f32 v[4:5], v[38:39], v[4:5]
	v_pk_add_f32 v[38:39], v[42:43], 1.0 op_sel_hi:[1,0]
	s_waitcnt vmcnt(0)
	v_pk_fma_f32 v[2:3], v[36:37], v[2:3], v[44:45]
	v_pk_fma_f32 v[4:5], v[38:39], v[4:5], v[46:47]
	v_cvt_pk_bf16_f32 v2, v2, v3
	v_cvt_pk_bf16_f32 v3, v4, v5
	global_store_dwordx2 v[50:51], v[2:3], off
	global_load_dwordx4 v[2:5], v[6:7], off offset:1024
	s_nop 0
	global_load_dwordx4 v[36:39], v[52:53], off offset:1024
	global_load_dwordx4 v[40:43], v[48:49], off offset:1024
	s_waitcnt vmcnt(2)
	v_pk_mul_f32 v[2:3], v[2:3], v[24:25]
	s_waitcnt vmcnt(1)
	v_pk_add_f32 v[24:25], v[36:37], 1.0 op_sel_hi:[1,0]
	v_pk_mul_f32 v[4:5], v[4:5], v[26:27]
	v_pk_add_f32 v[26:27], v[38:39], 1.0 op_sel_hi:[1,0]
	s_waitcnt vmcnt(0)
	v_pk_fma_f32 v[2:3], v[24:25], v[2:3], v[40:41]
	v_pk_fma_f32 v[4:5], v[26:27], v[4:5], v[42:43]
	v_cvt_pk_bf16_f32 v2, v2, v3
	v_cvt_pk_bf16_f32 v3, v4, v5
	global_store_dwordx2 v[50:51], v[2:3], off offset:512
	global_load_dwordx4 v[2:5], v[6:7], off offset:2048
	s_nop 0
	global_load_dwordx4 v[24:27], v[52:53], off offset:2048
	global_load_dwordx4 v[36:39], v[48:49], off offset:2048
	s_waitcnt vmcnt(2)
	v_pk_mul_f32 v[2:3], v[2:3], v[28:29]
	s_waitcnt vmcnt(1)
	v_pk_add_f32 v[24:25], v[24:25], 1.0 op_sel_hi:[1,0]
	v_pk_mul_f32 v[4:5], v[4:5], v[30:31]
	v_pk_add_f32 v[26:27], v[26:27], 1.0 op_sel_hi:[1,0]
	s_waitcnt vmcnt(0)
	v_pk_fma_f32 v[2:3], v[2:3], v[24:25], v[36:37]
	v_pk_fma_f32 v[4:5], v[4:5], v[26:27], v[38:39]
	v_cvt_pk_bf16_f32 v2, v2, v3
	v_cvt_pk_bf16_f32 v3, v4, v5
	global_store_dwordx2 v[50:51], v[2:3], off offset:1024
	global_load_dwordx4 v[2:5], v[6:7], off offset:3072
	s_nop 0
	global_load_dwordx4 v[24:27], v[52:53], off offset:3072
	global_load_dwordx4 v[28:31], v[48:49], off offset:3072
	s_waitcnt vmcnt(2)
	v_pk_mul_f32 v[2:3], v[32:33], v[2:3]
	s_waitcnt vmcnt(1)
	v_pk_add_f32 v[24:25], v[24:25], 1.0 op_sel_hi:[1,0]
	v_pk_mul_f32 v[4:5], v[34:35], v[4:5]
	v_pk_add_f32 v[26:27], v[26:27], 1.0 op_sel_hi:[1,0]
	s_waitcnt vmcnt(0)
	v_pk_fma_f32 v[2:3], v[2:3], v[24:25], v[28:29]
	v_pk_fma_f32 v[4:5], v[4:5], v[26:27], v[30:31]
	v_cvt_pk_bf16_f32 v2, v2, v3
	v_cvt_pk_bf16_f32 v3, v4, v5
	global_store_dwordx2 v[50:51], v[2:3], off offset:1536
	s_cbranch_scc0 .LBB0_1347

.LBB0_1469:
	v_add_u32_e32 v3, s5, v146
	v_cmp_gt_u32_e32 vcc, s74, v3
	v_mov_b32_e32 v102, 0
	v_mov_b32_e32 v106, 0
	v_mov_b32_e32 v107, 0
	v_mov_b32_e32 v108, 0
	v_mov_b32_e32 v109, 0
	s_and_saveexec_b64 s[2:3], vcc
	ds_read_b128 v[106:109], v149
	s_or_b64 exec, exec, s[2:3]
	v_mov_b32_e32 v103, 0
	v_mov_b32_e32 v104, 0
	v_mov_b32_e32 v105, 0
	s_and_saveexec_b64 s[2:3], vcc
	ds_read_b128 v[102:105], v148
	s_or_b64 exec, exec, s[2:3]
	v_cmp_le_u32_e32 vcc, s39, v3
	v_cmp_ge_u32_e64 s[2:3], s35, v3
	s_and_b64 s[40:41], vcc, s[2:3]
	s_waitcnt lgkmcnt(0)
	v_and_b32_e32 v143, 0xffff0000, v94
	v_lshlrev_b32_e32 v142, 16, v94
	s_waitcnt lgkmcnt(0)
	v_and_b32_e32 v123, 0xffff0000, v106
	v_lshlrev_b32_e32 v122, 16, v106
	v_and_b32_e32 v141, 0xffff0000, v98
	v_lshlrev_b32_e32 v140, 16, v98
	v_and_b32_e32 v119, 0xffff0000, v102
	v_lshlrev_b32_e32 v118, 16, v102
	v_and_b32_e32 v139, 0xffff0000, v95
	v_lshlrev_b32_e32 v138, 16, v95
	v_and_b32_e32 v117, 0xffff0000, v107
	v_lshlrev_b32_e32 v116, 16, v107
	v_and_b32_e32 v137, 0xffff0000, v99
	v_lshlrev_b32_e32 v136, 16, v99
	v_and_b32_e32 v113, 0xffff0000, v103
	v_lshlrev_b32_e32 v112, 16, v103
	v_and_b32_e32 v135, 0xffff0000, v96
	v_lshlrev_b32_e32 v134, 16, v96
	v_and_b32_e32 v107, 0xffff0000, v108
	v_lshlrev_b32_e32 v106, 16, v108
	v_and_b32_e32 v133, 0xffff0000, v100
	v_lshlrev_b32_e32 v132, 16, v100
	v_and_b32_e32 v99, 0xffff0000, v104
	v_lshlrev_b32_e32 v98, 16, v104
	v_and_b32_e32 v131, 0xffff0000, v97
	v_lshlrev_b32_e32 v130, 16, v97
	v_and_b32_e32 v95, 0xffff0000, v109
	v_lshlrev_b32_e32 v94, 16, v109
	v_and_b32_e32 v97, 0xffff0000, v101
	v_lshlrev_b32_e32 v96, 16, v101
	v_and_b32_e32 v5, 0xffff0000, v105
	v_lshlrev_b32_e32 v4, 16, v105
	s_and_saveexec_b64 s[2:3], s[40:41]
	s_cbranch_execz .LBB0_1475
	v_and_b32_e32 v101, 0xffff0000, v90
	v_lshlrev_b32_e32 v100, 16, v90
	v_pk_mul_f32 v[100:101], v[26:27], v[100:101]
	v_and_b32_e32 v103, 0xffff0000, v86
	v_pk_fma_f32 v[100:101], v[42:43], v[142:143], v[100:101]
	v_lshlrev_b32_e32 v102, 16, v86
	v_pk_fma_f32 v[100:101], v[58:59], v[122:123], v[100:101]
	v_and_b32_e32 v109, 0xffff0000, v91
	v_pk_add_f32 v[100:101], v[74:75], v[100:101]
	v_lshlrev_b32_e32 v108, 16, v91
	v_mul_f32_e32 v90, 0xbfb8aa3b, v100
	v_exp_f32_e32 v90, v90
	v_pk_mul_f32 v[102:103], v[30:31], v[102:103]
	v_add_f32_e32 v86, 1.0, v90
	v_rcp_f32_e32 v104, v86
	v_mul_f32_e32 v86, 0xbfb8aa3b, v101
	v_exp_f32_e32 v86, v86
	v_pk_mul_f32 v[90:91], v[28:29], v[108:109]
	v_pk_fma_f32 v[102:103], v[46:47], v[140:141], v[102:103]
	v_pk_fma_f32 v[90:91], v[44:45], v[138:139], v[90:91]
	v_add_f32_e32 v86, 1.0, v86
	v_rcp_f32_e32 v105, v86
	v_pk_fma_f32 v[102:103], v[62:63], v[118:119], v[102:103]
	v_pk_fma_f32 v[90:91], v[60:61], v[116:117], v[90:91]
	v_pk_add_f32 v[102:103], v[78:79], v[102:103]
	v_pk_add_f32 v[90:91], v[76:77], v[90:91]
	v_pk_mul_f32 v[100:101], v[100:101], v[104:105]
	v_mul_f32_e32 v86, 0xbfb8aa3b, v90
	v_pk_mul_f32 v[100:101], v[100:101], v[102:103]
	v_and_b32_e32 v103, 0xffff0000, v87
	v_lshlrev_b32_e32 v102, 16, v87
	v_mul_f32_e32 v87, 0xbfb8aa3b, v91
	v_exp_f32_e32 v86, v86
	v_exp_f32_e32 v87, v87
	v_and_b32_e32 v105, 0xffff0000, v92
	v_lshlrev_b32_e32 v104, 16, v92
	v_add_f32_e32 v86, 1.0, v86
	v_add_f32_e32 v87, 1.0, v87
	v_rcp_f32_e32 v86, v86
	v_rcp_f32_e32 v87, v87
	v_pk_mul_f32 v[102:103], v[32:33], v[102:103]
	v_pk_mul_f32 v[104:105], v[22:23], v[104:105]
	v_pk_fma_f32 v[102:103], v[48:49], v[136:137], v[102:103]
	v_pk_fma_f32 v[104:105], v[38:39], v[134:135], v[104:105]
	v_pk_fma_f32 v[102:103], v[64:65], v[112:113], v[102:103]
	v_pk_fma_f32 v[104:105], v[54:55], v[106:107], v[104:105]
	v_pk_add_f32 v[102:103], v[80:81], v[102:103]
	v_pk_add_f32 v[104:105], v[70:71], v[104:105]
	v_pk_mul_f32 v[86:87], v[90:91], v[86:87]
	v_mul_f32_e32 v92, 0xbfb8aa3b, v104
	v_pk_mul_f32 v[90:91], v[86:87], v[102:103]
	v_mul_f32_e32 v87, 0xbfb8aa3b, v105
	v_exp_f32_e32 v92, v92
	v_exp_f32_e32 v87, v87
	v_and_b32_e32 v103, 0xffff0000, v88
	v_lshlrev_b32_e32 v102, 16, v88
	v_add_f32_e32 v86, 1.0, v92
	v_add_f32_e32 v87, 1.0, v87
	v_rcp_f32_e32 v86, v86
	v_rcp_f32_e32 v87, v87
	v_and_b32_e32 v109, 0xffff0000, v93
	v_lshlrev_b32_e32 v108, 16, v93
	v_pk_mul_f32 v[102:103], v[34:35], v[102:103]
	v_pk_mul_f32 v[92:93], v[24:25], v[108:109]
	v_pk_fma_f32 v[102:103], v[50:51], v[132:133], v[102:103]
	v_pk_fma_f32 v[92:93], v[40:41], v[130:131], v[92:93]
	v_pk_fma_f32 v[102:103], v[66:67], v[98:99], v[102:103]
	v_pk_fma_f32 v[92:93], v[56:57], v[94:95], v[92:93]
	v_pk_add_f32 v[102:103], v[82:83], v[102:103]
	v_pk_add_f32 v[92:93], v[72:73], v[92:93]
	v_pk_mul_f32 v[86:87], v[104:105], v[86:87]
	v_mul_f32_e32 v88, 0xbfb8aa3b, v92
	v_pk_mul_f32 v[102:103], v[86:87], v[102:103]
	v_mul_f32_e32 v87, 0xbfb8aa3b, v93
	v_exp_f32_e32 v88, v88
	v_exp_f32_e32 v87, v87
	v_and_b32_e32 v105, 0xffff0000, v89
	v_lshlrev_b32_e32 v104, 16, v89
	v_add_f32_e32 v86, 1.0, v88
	v_add_f32_e32 v87, 1.0, v87
	v_rcp_f32_e32 v86, v86
	v_rcp_f32_e32 v87, v87
	v_pk_mul_f32 v[88:89], v[36:37], v[104:105]
	v_pk_mul_f32 v[86:87], v[92:93], v[86:87]
	v_pk_fma_f32 v[88:89], v[52:53], v[96:97], v[88:89]
	s_nop 0
	v_pk_fma_f32 v[88:89], v[68:69], v[4:5], v[88:89]
	s_nop 0
	v_pk_add_f32 v[88:89], v[84:85], v[88:89]
	s_nop 0
	v_pk_mul_f32 v[92:93], v[86:87], v[88:89]
	v_cvt_pk_bf16_f32 v87, v90, v91
	v_add_u32_e32 v90, s5, v147
	v_cvt_pk_bf16_f32 v86, v100, v101
	v_cvt_pk_bf16_f32 v88, v102, v103
	v_cvt_pk_bf16_f32 v89, v92, v93
	v_mad_i64_i32 v[90:91], s[40:41], v90, s77, v[110:111]
	global_store_dwordx4 v[90:91], v[86:89], off sc1
.LBB0_1475:
	s_or_b64 exec, exec, s[2:3]
	v_add_u32_e32 v100, 1, v3
	v_cmp_gt_u32_e32 vcc, s74, v100
	v_mov_b32_e32 v86, 0
	v_mov_b32_e32 v90, 0
	v_mov_b32_e32 v91, 0
	v_mov_b32_e32 v92, 0
	v_mov_b32_e32 v93, 0
	s_and_saveexec_b64 s[2:3], vcc
	ds_read_b128 v[90:93], v149 offset:528
	s_or_b64 exec, exec, s[2:3]
	v_mov_b32_e32 v87, 0
	v_mov_b32_e32 v88, 0
	v_mov_b32_e32 v89, 0
	s_and_saveexec_b64 s[2:3], vcc
	ds_read_b128 v[86:89], v148 offset:528
	s_or_b64 exec, exec, s[2:3]
	v_cmp_le_i32_e32 vcc, s39, v100
	v_cmp_ge_u32_e64 s[2:3], s35, v100
	s_and_b64 s[40:41], vcc, s[2:3]
	s_waitcnt lgkmcnt(0)
	v_and_b32_e32 v129, 0xffff0000, v90
	v_lshlrev_b32_e32 v128, 16, v90
	v_and_b32_e32 v127, 0xffff0000, v86
	v_lshlrev_b32_e32 v126, 16, v86
	v_and_b32_e32 v125, 0xffff0000, v91
	v_lshlrev_b32_e32 v124, 16, v91
	v_and_b32_e32 v121, 0xffff0000, v87
	v_lshlrev_b32_e32 v120, 16, v87
	v_and_b32_e32 v115, 0xffff0000, v92
	v_lshlrev_b32_e32 v114, 16, v92
	v_and_b32_e32 v109, 0xffff0000, v88
	v_lshlrev_b32_e32 v108, 16, v88
	v_and_b32_e32 v105, 0xffff0000, v93
	v_lshlrev_b32_e32 v104, 16, v93
	v_and_b32_e32 v103, 0xffff0000, v89
	v_lshlrev_b32_e32 v102, 16, v89
	s_and_saveexec_b64 s[2:3], s[40:41]
	s_cbranch_execz .LBB0_1481
	v_pk_mul_f32 v[86:87], v[42:43], v[122:123]
	s_nop 0
	v_pk_fma_f32 v[86:87], v[26:27], v[142:143], v[86:87]
	s_nop 0
	v_pk_fma_f32 v[86:87], v[58:59], v[128:129], v[86:87]
	s_nop 0
	v_pk_add_f32 v[86:87], v[74:75], v[86:87]
	s_nop 0
	v_mul_f32_e32 v88, 0xbfb8aa3b, v86
	v_exp_f32_e32 v90, v88
	v_mul_f32_e32 v88, 0xbfb8aa3b, v87
	v_exp_f32_e32 v91, v88
	v_pk_mul_f32 v[88:89], v[46:47], v[118:119]
	v_add_f32_e32 v90, 1.0, v90
	v_rcp_f32_e32 v90, v90
	v_add_f32_e32 v91, 1.0, v91
	v_rcp_f32_e32 v91, v91
	v_pk_fma_f32 v[88:89], v[30:31], v[140:141], v[88:89]
	v_pk_mul_f32 v[86:87], v[86:87], v[90:91]
	v_pk_mul_f32 v[90:91], v[44:45], v[116:117]
	v_pk_fma_f32 v[88:89], v[62:63], v[126:127], v[88:89]
	v_pk_fma_f32 v[90:91], v[28:29], v[138:139], v[90:91]
	v_pk_add_f32 v[88:89], v[78:79], v[88:89]
	v_pk_fma_f32 v[90:91], v[60:61], v[124:125], v[90:91]
	v_pk_mul_f32 v[86:87], v[86:87], v[88:89]
	v_pk_add_f32 v[90:91], v[76:77], v[90:91]
	v_cvt_pk_bf16_f32 v86, v86, v87
	v_mul_f32_e32 v92, 0xbfb8aa3b, v90
	v_mul_f32_e32 v88, 0xbfb8aa3b, v91
	v_exp_f32_e32 v92, v92
	v_exp_f32_e32 v89, v88
	v_add_f32_e32 v88, 1.0, v92
	v_add_f32_e32 v89, 1.0, v89
	v_rcp_f32_e32 v88, v88
	v_rcp_f32_e32 v89, v89
	v_pk_mul_f32 v[92:93], v[48:49], v[112:113]
	v_pk_mul_f32 v[88:89], v[90:91], v[88:89]
	v_pk_mul_f32 v[90:91], v[38:39], v[106:107]
	v_pk_fma_f32 v[92:93], v[32:33], v[136:137], v[92:93]
	v_pk_fma_f32 v[90:91], v[22:23], v[134:135], v[90:91]
	v_pk_fma_f32 v[92:93], v[64:65], v[120:121], v[92:93]
	v_pk_fma_f32 v[90:91], v[54:55], v[114:115], v[90:91]
	v_pk_add_f32 v[92:93], v[80:81], v[92:93]
	v_pk_add_f32 v[90:91], v[70:71], v[90:91]
	v_pk_mul_f32 v[88:89], v[88:89], v[92:93]
	v_mul_f32_e32 v100, 0xbfb8aa3b, v90
	v_mul_f32_e32 v92, 0xbfb8aa3b, v91
	v_exp_f32_e32 v100, v100
	v_exp_f32_e32 v93, v92
	v_cvt_pk_bf16_f32 v87, v88, v89
	v_add_f32_e32 v92, 1.0, v100
	v_add_f32_e32 v93, 1.0, v93
	v_rcp_f32_e32 v92, v92
	v_rcp_f32_e32 v93, v93
	v_pk_mul_f32 v[100:101], v[50:51], v[98:99]
	v_pk_mul_f32 v[90:91], v[90:91], v[92:93]
	v_pk_mul_f32 v[92:93], v[40:41], v[94:95]
	v_pk_fma_f32 v[100:101], v[34:35], v[132:133], v[100:101]
	v_pk_fma_f32 v[92:93], v[24:25], v[130:131], v[92:93]
	v_pk_fma_f32 v[100:101], v[66:67], v[108:109], v[100:101]
	v_pk_fma_f32 v[92:93], v[56:57], v[104:105], v[92:93]
	v_pk_add_f32 v[100:101], v[82:83], v[100:101]
	v_pk_add_f32 v[92:93], v[72:73], v[92:93]
	v_pk_mul_f32 v[90:91], v[90:91], v[100:101]
	v_mul_f32_e32 v130, 0xbfb8aa3b, v92
	v_mul_f32_e32 v100, 0xbfb8aa3b, v93
	v_exp_f32_e32 v130, v130
	v_exp_f32_e32 v101, v100
	v_cvt_pk_bf16_f32 v88, v90, v91
	v_add3_u32 v90, v147, s5, 1
	v_add_f32_e32 v100, 1.0, v130
	v_add_f32_e32 v101, 1.0, v101
	v_rcp_f32_e32 v100, v100
	v_rcp_f32_e32 v101, v101
	v_pk_mul_f32 v[130:131], v[52:53], v[4:5]
	v_mad_i64_i32 v[90:91], s[40:41], v90, s77, v[110:111]
	v_pk_fma_f32 v[96:97], v[36:37], v[96:97], v[130:131]
	v_pk_mul_f32 v[92:93], v[92:93], v[100:101]
	v_pk_fma_f32 v[96:97], v[68:69], v[102:103], v[96:97]
	s_nop 0
	v_pk_add_f32 v[96:97], v[84:85], v[96:97]
	s_nop 0
	v_pk_mul_f32 v[92:93], v[92:93], v[96:97]
	s_nop 0
	v_cvt_pk_bf16_f32 v89, v92, v93
	global_store_dwordx4 v[90:91], v[86:89], off sc1
.LBB0_1481:
	s_or_b64 exec, exec, s[2:3]
	v_add_u32_e32 v96, 2, v3
	v_cmp_gt_u32_e32 vcc, s74, v96
	v_mov_b32_e32 v86, 0
	v_mov_b32_e32 v90, 0
	v_mov_b32_e32 v91, 0
	v_mov_b32_e32 v92, 0
	v_mov_b32_e32 v93, 0
	s_and_saveexec_b64 s[2:3], vcc
	ds_read_b128 v[90:93], v149 offset:1056
	s_or_b64 exec, exec, s[2:3]
	v_mov_b32_e32 v87, 0
	v_mov_b32_e32 v88, 0
	v_mov_b32_e32 v89, 0
	s_and_saveexec_b64 s[2:3], vcc
	ds_read_b128 v[86:89], v148 offset:1056
	s_or_b64 exec, exec, s[2:3]
	v_cmp_le_i32_e32 vcc, s39, v96
	v_cmp_ge_u32_e64 s[2:3], s35, v96
	s_and_b64 s[40:41], vcc, s[2:3]
	s_waitcnt lgkmcnt(0)
	v_and_b32_e32 v145, 0xffff0000, v90
	v_lshlrev_b32_e32 v144, 16, v90
	v_and_b32_e32 v143, 0xffff0000, v86
	v_lshlrev_b32_e32 v142, 16, v86
	v_and_b32_e32 v141, 0xffff0000, v91
	v_lshlrev_b32_e32 v140, 16, v91
	v_and_b32_e32 v139, 0xffff0000, v87
	v_lshlrev_b32_e32 v138, 16, v87
	v_and_b32_e32 v137, 0xffff0000, v92
	v_lshlrev_b32_e32 v136, 16, v92
	v_and_b32_e32 v135, 0xffff0000, v88
	v_lshlrev_b32_e32 v134, 16, v88
	v_and_b32_e32 v133, 0xffff0000, v93
	v_lshlrev_b32_e32 v132, 16, v93
	v_and_b32_e32 v131, 0xffff0000, v89
	v_lshlrev_b32_e32 v130, 16, v89
	s_and_saveexec_b64 s[2:3], s[40:41]
	s_cbranch_execz .LBB0_1487
	v_pk_mul_f32 v[96:97], v[42:43], v[128:129]
	s_nop 0
	v_pk_fma_f32 v[96:97], v[26:27], v[122:123], v[96:97]
	s_nop 0
	v_pk_fma_f32 v[96:97], v[58:59], v[144:145], v[96:97]
	s_nop 0
	v_pk_add_f32 v[96:97], v[74:75], v[96:97]
	s_nop 0
	v_mul_f32_e32 v100, 0xbfb8aa3b, v96
	v_exp_f32_e32 v122, v100
	v_mul_f32_e32 v100, 0xbfb8aa3b, v97
	v_exp_f32_e32 v123, v100
	v_pk_mul_f32 v[100:101], v[46:47], v[126:127]
	v_add_f32_e32 v122, 1.0, v122
	v_rcp_f32_e32 v122, v122
	v_add_f32_e32 v123, 1.0, v123
	v_rcp_f32_e32 v123, v123
	v_pk_fma_f32 v[100:101], v[30:31], v[118:119], v[100:101]
	v_pk_mul_f32 v[118:119], v[44:45], v[124:125]
	v_pk_fma_f32 v[100:101], v[62:63], v[142:143], v[100:101]
	v_pk_fma_f32 v[116:117], v[28:29], v[116:117], v[118:119]
	v_pk_add_f32 v[100:101], v[78:79], v[100:101]
	v_pk_fma_f32 v[116:117], v[60:61], v[140:141], v[116:117]
	v_pk_mul_f32 v[96:97], v[96:97], v[122:123]
	v_pk_add_f32 v[116:117], v[76:77], v[116:117]
	v_pk_mul_f32 v[96:97], v[96:97], v[100:101]
	v_mul_f32_e32 v118, 0xbfb8aa3b, v116
	v_mul_f32_e32 v100, 0xbfb8aa3b, v117
	v_exp_f32_e32 v118, v118
	v_exp_f32_e32 v101, v100
	v_add_f32_e32 v100, 1.0, v118
	v_add_f32_e32 v101, 1.0, v101
	v_rcp_f32_e32 v100, v100
	v_rcp_f32_e32 v101, v101
	v_pk_mul_f32 v[118:119], v[48:49], v[120:121]
	v_pk_mul_f32 v[100:101], v[116:117], v[100:101]
	v_pk_mul_f32 v[116:117], v[38:39], v[114:115]
	v_pk_fma_f32 v[112:113], v[32:33], v[112:113], v[118:119]
	v_pk_fma_f32 v[106:107], v[22:23], v[106:107], v[116:117]
	v_pk_fma_f32 v[112:113], v[64:65], v[138:139], v[112:113]
	v_pk_fma_f32 v[106:107], v[54:55], v[136:137], v[106:107]
	v_pk_add_f32 v[112:113], v[80:81], v[112:113]
	v_pk_add_f32 v[106:107], v[70:71], v[106:107]
	v_pk_mul_f32 v[100:101], v[100:101], v[112:113]
	v_mul_f32_e32 v116, 0xbfb8aa3b, v106
	v_mul_f32_e32 v112, 0xbfb8aa3b, v107
	v_exp_f32_e32 v116, v116
	v_exp_f32_e32 v113, v112
	v_add_f32_e32 v112, 1.0, v116
	v_add_f32_e32 v113, 1.0, v113
	v_rcp_f32_e32 v112, v112
	v_rcp_f32_e32 v113, v113
	v_pk_mul_f32 v[116:117], v[50:51], v[108:109]
	v_pk_mul_f32 v[106:107], v[106:107], v[112:113]
	v_pk_mul_f32 v[112:113], v[40:41], v[104:105]
	v_pk_fma_f32 v[98:99], v[34:35], v[98:99], v[116:117]
	v_pk_fma_f32 v[94:95], v[24:25], v[94:95], v[112:113]
	v_pk_fma_f32 v[98:99], v[66:67], v[134:135], v[98:99]
	v_pk_fma_f32 v[94:95], v[56:57], v[132:133], v[94:95]
	v_pk_add_f32 v[98:99], v[82:83], v[98:99]
	v_pk_add_f32 v[94:95], v[72:73], v[94:95]
	v_pk_mul_f32 v[98:99], v[106:107], v[98:99]
	v_mul_f32_e32 v112, 0xbfb8aa3b, v94
	v_mul_f32_e32 v106, 0xbfb8aa3b, v95
	v_exp_f32_e32 v112, v112
	v_exp_f32_e32 v107, v106
	v_add_f32_e32 v106, 1.0, v112
	v_add_f32_e32 v107, 1.0, v107
	v_rcp_f32_e32 v106, v106
	v_rcp_f32_e32 v107, v107
	v_pk_mul_f32 v[112:113], v[52:53], v[102:103]
	v_pk_mul_f32 v[94:95], v[94:95], v[106:107]
	v_pk_fma_f32 v[4:5], v[36:37], v[4:5], v[112:113]
	s_nop 0
	v_pk_fma_f32 v[4:5], v[68:69], v[130:131], v[4:5]
	s_nop 0
	v_pk_add_f32 v[4:5], v[84:85], v[4:5]
	s_nop 0
	v_pk_mul_f32 v[4:5], v[94:95], v[4:5]
	v_cvt_pk_bf16_f32 v94, v96, v97
	v_cvt_pk_bf16_f32 v97, v4, v5
	v_add3_u32 v4, v147, s5, 2
	v_cvt_pk_bf16_f32 v95, v100, v101
	v_cvt_pk_bf16_f32 v96, v98, v99
	v_mad_i64_i32 v[4:5], s[40:41], v4, s77, v[110:111]
	global_store_dwordx4 v[4:5], v[94:97], off sc1
.LBB0_1487:
	s_or_b64 exec, exec, s[2:3]
	v_mov_b32_e32 v4, v2
	v_mov_b32_e32 v5, v2
	v_add_u32_e32 v106, 3, v3
	v_mov_b32_e32 v3, v2
	v_mov_b64_e32 v[96:97], v[4:5]
	v_cmp_gt_u32_e32 vcc, s74, v106
	v_mov_b64_e32 v[94:95], v[2:3]
	s_and_saveexec_b64 s[2:3], vcc
	ds_read_b128 v[94:97], v149 offset:1584
	s_or_b64 exec, exec, s[2:3]
	v_mov_b64_e32 v[100:101], v[4:5]
	v_mov_b64_e32 v[98:99], v[2:3]
	s_and_saveexec_b64 s[2:3], vcc
	ds_read_b128 v[98:101], v148 offset:1584
	s_or_b64 exec, exec, s[2:3]
	v_cmp_le_i32_e32 vcc, s39, v106
	v_cmp_ge_u32_e64 s[2:3], s35, v106
	s_and_b64 s[2:3], vcc, s[2:3]
	s_and_saveexec_b64 s[40:41], s[2:3]
	s_xor_b64 s[2:3], exec, s[40:41]
	s_cbranch_execz .LBB0_1468
	v_pk_mul_f32 v[4:5], v[42:43], v[144:145]
	s_waitcnt lgkmcnt(0)
	v_and_b32_e32 v107, 0xffff0000, v94
	v_pk_fma_f32 v[4:5], v[26:27], v[128:129], v[4:5]
	v_lshlrev_b32_e32 v106, 16, v94
	v_pk_fma_f32 v[4:5], v[58:59], v[106:107], v[4:5]
	v_pk_mul_f32 v[106:107], v[46:47], v[142:143]
	v_pk_add_f32 v[4:5], v[74:75], v[4:5]
	v_pk_fma_f32 v[106:107], v[30:31], v[126:127], v[106:107]
	v_mul_f32_e32 v3, 0xbfb8aa3b, v4
	v_exp_f32_e32 v3, v3
	v_and_b32_e32 v117, 0xffff0000, v98
	v_lshlrev_b32_e32 v116, 16, v98
	v_pk_fma_f32 v[106:107], v[62:63], v[116:117], v[106:107]
	v_add_f32_e32 v3, 1.0, v3
	v_rcp_f32_e32 v112, v3
	v_mul_f32_e32 v3, 0xbfb8aa3b, v5
	v_exp_f32_e32 v3, v3
	v_pk_mul_f32 v[116:117], v[44:45], v[140:141]
	v_and_b32_e32 v119, 0xffff0000, v95
	v_pk_fma_f32 v[116:117], v[28:29], v[124:125], v[116:117]
	v_lshlrev_b32_e32 v118, 16, v95
	v_pk_fma_f32 v[116:117], v[60:61], v[118:119], v[116:117]
	v_add_f32_e32 v3, 1.0, v3
	v_pk_add_f32 v[116:117], v[76:77], v[116:117]
	v_rcp_f32_e32 v113, v3
	v_mul_f32_e32 v3, 0xbfb8aa3b, v116
	v_exp_f32_e32 v3, v3
	v_pk_add_f32 v[106:107], v[78:79], v[106:107]
	v_pk_mul_f32 v[4:5], v[4:5], v[112:113]
	v_pk_mul_f32 v[112:113], v[48:49], v[138:139]
	v_add_f32_e32 v3, 1.0, v3
	v_pk_mul_f32 v[4:5], v[4:5], v[106:107]
	v_rcp_f32_e32 v106, v3
	v_mul_f32_e32 v3, 0xbfb8aa3b, v117
	v_pk_fma_f32 v[112:113], v[32:33], v[120:121], v[112:113]
	v_exp_f32_e32 v3, v3
	v_and_b32_e32 v119, 0xffff0000, v99
	v_lshlrev_b32_e32 v118, 16, v99
	v_pk_fma_f32 v[112:113], v[64:65], v[118:119], v[112:113]
	v_pk_mul_f32 v[118:119], v[38:39], v[136:137]
	v_add_f32_e32 v3, 1.0, v3
	v_pk_fma_f32 v[114:115], v[22:23], v[114:115], v[118:119]
	v_and_b32_e32 v119, 0xffff0000, v96
	v_lshlrev_b32_e32 v118, 16, v96
	v_pk_fma_f32 v[114:115], v[54:55], v[118:119], v[114:115]
	v_rcp_f32_e32 v107, v3
	v_pk_add_f32 v[114:115], v[70:71], v[114:115]
	v_pk_add_f32 v[112:113], v[80:81], v[112:113]
	v_mul_f32_e32 v3, 0xbfb8aa3b, v114
	v_exp_f32_e32 v3, v3
	v_pk_mul_f32 v[106:107], v[116:117], v[106:107]
	v_pk_mul_f32 v[116:117], v[50:51], v[134:135]
	v_pk_mul_f32 v[106:107], v[106:107], v[112:113]
	v_add_f32_e32 v3, 1.0, v3
	v_rcp_f32_e32 v112, v3
	v_mul_f32_e32 v3, 0xbfb8aa3b, v115
	v_pk_fma_f32 v[108:109], v[34:35], v[108:109], v[116:117]
	v_exp_f32_e32 v3, v3
	v_and_b32_e32 v117, 0xffff0000, v100
	v_lshlrev_b32_e32 v116, 16, v100
	v_pk_fma_f32 v[108:109], v[66:67], v[116:117], v[108:109]
	v_pk_mul_f32 v[116:117], v[40:41], v[132:133]
	v_add_f32_e32 v3, 1.0, v3
	v_pk_fma_f32 v[104:105], v[24:25], v[104:105], v[116:117]
	v_and_b32_e32 v117, 0xffff0000, v97
	v_lshlrev_b32_e32 v116, 16, v97
	v_pk_fma_f32 v[104:105], v[56:57], v[116:117], v[104:105]
	v_rcp_f32_e32 v113, v3
	v_pk_add_f32 v[104:105], v[72:73], v[104:105]
	v_pk_add_f32 v[108:109], v[82:83], v[108:109]
	v_mul_f32_e32 v3, 0xbfb8aa3b, v104
	v_exp_f32_e32 v3, v3
	v_pk_mul_f32 v[112:113], v[114:115], v[112:113]
	v_pk_mul_f32 v[114:115], v[52:53], v[130:131]
	v_pk_mul_f32 v[108:109], v[112:113], v[108:109]
	v_add_f32_e32 v3, 1.0, v3
	v_rcp_f32_e32 v112, v3
	v_mul_f32_e32 v3, 0xbfb8aa3b, v105
	v_exp_f32_e32 v3, v3
	v_pk_fma_f32 v[102:103], v[36:37], v[102:103], v[114:115]
	v_and_b32_e32 v115, 0xffff0000, v101
	v_lshlrev_b32_e32 v114, 16, v101
	v_add_f32_e32 v3, 1.0, v3
	v_rcp_f32_e32 v113, v3
	v_pk_fma_f32 v[102:103], v[68:69], v[114:115], v[102:103]
	v_add3_u32 v3, v147, s5, 3
	v_pk_add_f32 v[102:103], v[84:85], v[102:103]
	v_pk_mul_f32 v[104:105], v[104:105], v[112:113]
	s_nop 0
	v_pk_mul_f32 v[112:113], v[104:105], v[102:103]
	v_cvt_pk_bf16_f32 v102, v4, v5
	v_cvt_pk_bf16_f32 v103, v106, v107
	v_cvt_pk_bf16_f32 v104, v108, v109
	v_cvt_pk_bf16_f32 v105, v112, v113
	v_mad_i64_i32 v[4:5], s[40:41], v3, s77, v[110:111]
	global_store_dwordx4 v[4:5], v[102:105], off sc1
	s_branch .LBB0_1468

.LBB0_1513:
	v_add_u32_e32 v46, 0x400, v38
	ds_read2_b32 v[44:45], v46 offset1:65
	ds_read2_b32 v[46:47], v46 offset0:130 offset1:195
	v_add_u32_e32 v50, 0x800, v38
	s_or_b32 s8, s14, 0x80
	ds_read2_b32 v[48:49], v50 offset0:4 offset1:69
	ds_read2_b32 v[50:51], v50 offset0:134 offset1:199
	s_and_b32 s2, s13, 0x3c0
	s_addk_i32 s8, 0xea00
	s_and_b32 s9, s14, 0xffffff00
	s_cmpk_lt_i32 s17, 0x2c0
	s_cselect_b32 s8, s9, s8
	s_and_b32 s9, s15, 64
	s_add_i32 s8, s8, s9
	s_waitcnt lgkmcnt(3)
	v_cvt_pk_bf16_f32 v44, v44, v45
	s_waitcnt lgkmcnt(2)
	v_cvt_pk_bf16_f32 v45, v46, v47
	s_waitcnt lgkmcnt(1)
	v_cvt_pk_bf16_f32 v46, v48, v49
	v_add_u32_e32 v48, s8, v1
	v_ashrrev_i32_e32 v49, 31, v48
	v_lshlrev_b64 v[48:49], 11, v[48:49]
	v_lshl_add_u64 v[48:49], s[6:7], 0, v[48:49]
	s_lshl_b32 s2, s2, 1
	v_lshl_add_u64 v[48:49], v[48:49], 0, s[2:3]
	s_waitcnt lgkmcnt(0)
	v_cvt_pk_bf16_f32 v47, v50, v51
	v_lshl_add_u64 v[48:49], v[48:49], 0, v[34:35]
	s_cmpk_gt_i32 s17, 0x4f7
	global_store_dwordx4 v[48:49], v[44:47], off sc1
	s_cbranch_scc0 .LBB0_1516
	s_cmpk_gt_i32 s17, 0x46f
	s_cbranch_scc0 .LBB0_1517

.LBB0_1516:
	s_nop 0
	v_add_u32_e32 v44, 0x4400, v38
	v_add_u32_e32 v46, 0x4600, v38
	v_add_u32_e32 v48, 0x4800, v38
	s_add_i32 s8, s12, 0xfffffef0
	ds_read2_b32 v[44:45], v44 offset0:64 offset1:129
	ds_read2_b32 v[46:47], v46 offset0:66 offset1:131
	ds_read2_b32 v[48:49], v48 offset0:68 offset1:133
	s_lshl_b32 s18, s8, 2
	s_lshl_b32 s8, s8, 3
	s_add_i32 s9, s13, 0x2200
	s_and_b32 s8, s8, 0xffffff00
	s_and_b32 s9, s9, 0x3c0
	s_add_i32 s19, s8, 0xffffea80
	s_cmpk_lt_i32 s17, 0x238
	v_add_u32_e32 v50, 0x4a00, v38
	s_waitcnt lgkmcnt(2)
	v_cvt_pk_bf16_f32 v44, v44, v45
	s_waitcnt lgkmcnt(1)
	v_cvt_pk_bf16_f32 v45, v46, v47
	s_waitcnt lgkmcnt(0)
	v_cvt_pk_bf16_f32 v46, v48, v49
	s_cselect_b32 s8, s8, s19
	v_and_or_b32 v48, s18, 64, v1
	ds_read2_b32 v[50:51], v50 offset0:70 offset1:135
	v_or_b32_e32 v48, s8, v48
	v_ashrrev_i32_e32 v49, 31, v48
	v_lshlrev_b64 v[48:49], 11, v[48:49]
	v_lshl_add_u64 v[48:49], s[6:7], 0, v[48:49]
	s_lshl_b32 s8, s9, 1
	s_mov_b32 s9, s3
	v_lshl_add_u64 v[48:49], v[48:49], 0, s[8:9]
	s_waitcnt lgkmcnt(0)
	v_cvt_pk_bf16_f32 v47, v50, v51
	v_lshl_add_u64 v[48:49], v[48:49], 0, v[34:35]
	global_store_dwordx4 v[48:49], v[44:47], off sc1
	s_cmpk_gt_i32 s17, 0x46f
	s_cbranch_scc1 .LBB0_1515
.LBB0_1517:
	v_add_u32_e32 v44, 0x8400, v38
	v_add_u32_e32 v48, 0x8800, v38
	s_add_i32 s8, s12, 0xffffff78
	ds_read2_b32 v[44:45], v44 offset0:128 offset1:193
	ds_read2_b32 v[46:47], v48 offset0:2 offset1:67
	ds_read2_b32 v[48:49], v48 offset0:132 offset1:197
	s_lshl_b32 s9, s8, 2
	s_lshl_b32 s8, s8, 3
	s_and_b32 s8, s8, 0xffffff00
	s_add_i32 s18, s8, 0xffffea80
	s_cmpk_lt_i32 s17, 0x1b0
	v_add_u32_e32 v50, 0x8c00, v38
	s_waitcnt lgkmcnt(2)
	v_cvt_pk_bf16_f32 v44, v44, v45
	s_waitcnt lgkmcnt(1)
	v_cvt_pk_bf16_f32 v45, v46, v47
	s_waitcnt lgkmcnt(0)
	v_cvt_pk_bf16_f32 v46, v48, v49
	s_cselect_b32 s8, s8, s18
	v_and_or_b32 v48, s9, 64, v1
	ds_read2_b32 v[50:51], v50 offset0:6 offset1:71
	v_or_b32_e32 v48, s8, v48
	v_ashrrev_i32_e32 v49, 31, v48
	v_lshlrev_b64 v[48:49], 11, v[48:49]
	v_lshl_add_u64 v[48:49], s[6:7], 0, v[48:49]
	v_lshl_add_u64 v[48:49], v[48:49], 0, s[2:3]
	s_waitcnt lgkmcnt(0)
	v_cvt_pk_bf16_f32 v47, v50, v51
	v_lshl_add_u64 v[48:49], v[48:49], 0, v[34:35]
	global_store_dwordx4 v[48:49], v[44:47], off sc1
	s_cmpk_gt_i32 s17, 0x3e7
	s_cbranch_scc1 .LBB0_1495
.LBB0_1518:
	v_add_u32_e32 v44, 0xc600, v38
	v_add_u32_e32 v46, 0xc800, v38
	v_add_u32_e32 v48, 0xca00, v38
	ds_read2_b32 v[44:45], v44 offset0:64 offset1:129
	ds_read2_b32 v[46:47], v46 offset0:66 offset1:131
	ds_read2_b32 v[48:49], v48 offset0:68 offset1:133
	s_lshl_b32 s9, s12, 3
	s_add_i32 s2, s13, 0x6600
	s_and_b32 s9, s9, 0xffffff00
	s_and_b32 s2, s2, 0x3c0
	s_lshl_b32 s8, s12, 2
	s_add_i32 s18, s9, 0xffffea80
	s_cmpk_lt_i32 s17, 0x128
	v_add_u32_e32 v50, 0xcc00, v38
	s_waitcnt lgkmcnt(2)
	v_cvt_pk_bf16_f32 v44, v44, v45
	s_waitcnt lgkmcnt(1)
	v_cvt_pk_bf16_f32 v45, v46, v47
	s_waitcnt lgkmcnt(0)
	v_cvt_pk_bf16_f32 v46, v48, v49
	s_cselect_b32 s9, s9, s18
	v_and_or_b32 v48, s8, 64, v1
	ds_read2_b32 v[50:51], v50 offset0:70 offset1:135
	v_or_b32_e32 v48, s9, v48
	v_ashrrev_i32_e32 v49, 31, v48
	v_lshlrev_b64 v[48:49], 11, v[48:49]
	v_lshl_add_u64 v[48:49], s[6:7], 0, v[48:49]
	s_lshl_b32 s2, s2, 1
	v_lshl_add_u64 v[48:49], v[48:49], 0, s[2:3]
	s_waitcnt lgkmcnt(0)
	v_cvt_pk_bf16_f32 v47, v50, v51
	v_lshl_add_u64 v[48:49], v[48:49], 0, v[34:35]
	global_store_dwordx4 v[48:49], v[44:47], off sc1
	s_branch .LBB0_1495

.LBB0_1552:
	v_add_u32_e32 v37, 0x400, v38
	ds_read2_b32 v[58:59], v37 offset1:65
	ds_read2_b32 v[60:61], v37 offset0:130 offset1:195
	v_add_u32_e32 v37, 0x800, v38
	s_mul_hi_i32 s6, s12, 0x2e8ba2e9
	ds_read2_b32 v[62:63], v37 offset0:4 offset1:69
	ds_read2_b32 v[64:65], v37 offset0:134 offset1:199
	s_lshr_b32 s10, s6, 31
	s_ashr_i32 s6, s6, 3
	s_add_i32 s6, s6, s10
	s_mul_i32 s10, s6, 0xfffff500
	s_add_i32 s10, s13, s10
	s_waitcnt lgkmcnt(3)
	v_cvt_pk_bf16_f32 v58, v58, v59
	s_waitcnt lgkmcnt(2)
	v_cvt_pk_bf16_f32 v59, v60, v61
	s_waitcnt lgkmcnt(1)
	v_cvt_pk_bf16_f32 v60, v62, v63
	v_lshl_or_b32 v37, s6, 6, v1
	v_mov_b64_e32 v[62:63], s[4:5]
	v_mad_i64_i32 v[62:63], s[20:21], v37, s18, v[62:63]
	s_ashr_i32 s11, s10, 31
	v_lshl_add_u64 v[62:63], s[10:11], 1, v[62:63]
	s_waitcnt lgkmcnt(0)
	v_cvt_pk_bf16_f32 v61, v64, v65
	v_lshl_add_u64 v[62:63], v[62:63], 0, v[34:35]
	s_cmpk_gt_i32 s12, 0x237
	global_store_dwordx4 v[62:63], v[58:61], off sc1
	s_cbranch_scc0 .LBB0_1555
	s_cmpk_gt_i32 s12, 0x1af
	s_cbranch_scc0 .LBB0_1556

.LBB0_1555:
	v_add_u32_e32 v37, 0x4400, v38
	ds_read2_b32 v[58:59], v37 offset0:64 offset1:129
	v_add_u32_e32 v37, 0x4600, v38
	s_add_i32 s6, s12, 0x88
	ds_read2_b32 v[60:61], v37 offset0:66 offset1:131
	v_add_u32_e32 v37, 0x4800, v38
	s_mul_hi_i32 s10, s6, 0x2e8ba2e9
	ds_read2_b32 v[62:63], v37 offset0:68 offset1:133
	s_lshr_b32 s11, s10, 31
	s_ashr_i32 s10, s10, 3
	s_add_i32 s11, s10, s11
	v_add_u32_e32 v37, 0x4a00, v38
	s_mul_i32 s10, s11, 44
	ds_read2_b32 v[64:65], v37 offset0:70 offset1:135
	s_sub_i32 s6, s6, s10
	s_lshl_b32 s10, s6, 6
	s_waitcnt lgkmcnt(3)
	v_cvt_pk_bf16_f32 v58, v58, v59
	s_waitcnt lgkmcnt(2)
	v_cvt_pk_bf16_f32 v59, v60, v61
	s_waitcnt lgkmcnt(1)
	v_cvt_pk_bf16_f32 v60, v62, v63
	v_lshl_or_b32 v37, s11, 6, v1
	v_mov_b64_e32 v[62:63], s[4:5]
	v_mad_i64_i32 v[62:63], s[20:21], v37, s18, v[62:63]
	s_ashr_i32 s11, s10, 31
	v_lshl_add_u64 v[62:63], s[10:11], 1, v[62:63]
	s_waitcnt lgkmcnt(0)
	v_cvt_pk_bf16_f32 v61, v64, v65
	v_lshl_add_u64 v[62:63], v[62:63], 0, v[34:35]
	global_store_dwordx4 v[62:63], v[58:61], off sc1
	s_cmpk_gt_i32 s12, 0x1af
	s_cbranch_scc1 .LBB0_1554
.LBB0_1556:
	v_add_u32_e32 v37, 0x8400, v38
	ds_read2_b32 v[58:59], v37 offset0:128 offset1:193
	v_add_u32_e32 v37, 0x8800, v38
	ds_read2_b32 v[60:61], v37 offset0:2 offset1:67
	ds_read2_b32 v[62:63], v37 offset0:132 offset1:197
	s_add_i32 s6, s12, 0x110
	s_mul_hi_u32 s10, s6, 0xba2e8ba3
	v_add_u32_e32 v37, 0x8c00, v38
	s_lshr_b32 s10, s10, 5
	ds_read2_b32 v[64:65], v37 offset0:6 offset1:71
	s_mul_i32 s11, s10, 44
	s_sub_i32 s6, s6, s11
	s_waitcnt lgkmcnt(3)
	v_cvt_pk_bf16_f32 v58, v58, v59
	s_waitcnt lgkmcnt(2)
	v_cvt_pk_bf16_f32 v59, v60, v61
	s_waitcnt lgkmcnt(1)
	v_cvt_pk_bf16_f32 v60, v62, v63
	v_lshl_or_b32 v37, s10, 6, v1
	v_mov_b64_e32 v[62:63], s[4:5]
	v_mad_u64_u32 v[62:63], s[10:11], v37, s18, v[62:63]
	s_lshl_b32 s6, s6, 7
	v_lshl_add_u64 v[62:63], v[62:63], 0, s[6:7]
	s_waitcnt lgkmcnt(0)
	v_cvt_pk_bf16_f32 v61, v64, v65
	v_lshl_add_u64 v[62:63], v[62:63], 0, v[34:35]
	global_store_dwordx4 v[62:63], v[58:61], off sc1
	s_cmpk_gt_i32 s12, 0x127
	s_cbranch_scc1 .LBB0_1524
.LBB0_1557:
	v_add_u32_e32 v37, 0xc600, v38
	ds_read2_b32 v[58:59], v37 offset0:64 offset1:129
	v_add_u32_e32 v37, 0xc800, v38
	ds_read2_b32 v[60:61], v37 offset0:66 offset1:131
	v_add_u32_e32 v37, 0xca00, v38
	ds_read2_b32 v[62:63], v37 offset0:68 offset1:133
	s_add_i32 s6, s12, 0x198
	s_mul_hi_u32 s10, s6, 0xba2e8ba3
	v_add_u32_e32 v37, 0xcc00, v38
	s_lshr_b32 s10, s10, 5
	ds_read2_b32 v[64:65], v37 offset0:70 offset1:135
	s_mul_i32 s11, s10, 44
	s_sub_i32 s6, s6, s11
	s_waitcnt lgkmcnt(3)
	v_cvt_pk_bf16_f32 v58, v58, v59
	s_waitcnt lgkmcnt(2)
	v_cvt_pk_bf16_f32 v59, v60, v61
	s_waitcnt lgkmcnt(1)
	v_cvt_pk_bf16_f32 v60, v62, v63
	v_lshl_or_b32 v37, s10, 6, v1
	v_mov_b64_e32 v[62:63], s[4:5]
	v_mad_u64_u32 v[62:63], s[10:11], v37, s18, v[62:63]
	s_lshl_b32 s6, s6, 7
	v_lshl_add_u64 v[62:63], v[62:63], 0, s[6:7]
	s_waitcnt lgkmcnt(0)
	v_cvt_pk_bf16_f32 v61, v64, v65
	v_lshl_add_u64 v[62:63], v[62:63], 0, v[34:35]
	global_store_dwordx4 v[62:63], v[58:61], off sc1
	s_branch .LBB0_1524

.LBB0_1703:
	v_add_u32_e32 v35, 0x400, v39
	ds_read2_b32 v[60:61], v35 offset1:65
	ds_read2_b32 v[62:63], v35 offset0:130 offset1:195
	v_add_u32_e32 v35, 0x800, v39
	s_ashr_i32 s10, s20, 31
	ds_read2_b32 v[64:65], v35 offset0:4 offset1:69
	ds_read2_b32 v[66:67], v35 offset0:134 offset1:199
	s_lshr_b32 s10, s10, 28
	s_add_i32 s10, s20, s10
	s_ashr_i32 s11, s10, 4
	s_waitcnt lgkmcnt(3)
	v_cvt_pk_bf16_f32 v60, v60, v61
	s_waitcnt lgkmcnt(2)
	v_cvt_pk_bf16_f32 v61, v62, v63
	s_waitcnt lgkmcnt(1)
	v_cvt_pk_bf16_f32 v62, v64, v65
	v_lshl_or_b32 v64, s11, 6, v38
	s_lshl_b32 s10, s11, 10
	v_ashrrev_i32_e32 v65, 31, v64
	s_sub_i32 s10, s22, s10
	v_lshlrev_b64 v[64:65], 11, v[64:65]
	v_lshl_add_u64 v[64:65], s[2:3], 0, v[64:65]
	s_ashr_i32 s11, s10, 31
	v_lshl_add_u64 v[64:65], s[10:11], 1, v[64:65]
	s_add_i32 s10, s56, s20
	s_waitcnt lgkmcnt(0)
	v_cvt_pk_bf16_f32 v63, v66, v67
	v_lshl_add_u64 v[64:65], v[64:65], 0, v[36:37]
	s_cmpk_gt_i32 s10, 0x37f
	global_store_dwordx4 v[64:65], v[60:63], off sc1
	s_cbranch_scc0 .LBB0_1706
	s_add_i32 s10, s24, s20
	s_cmpk_gt_i32 s10, 0x37f
	s_cbranch_scc0 .LBB0_1707

.LBB0_1706:
	v_add_u32_e32 v35, 0x4400, v39
	ds_read2_b32 v[60:61], v35 offset0:64 offset1:129
	v_add_u32_e32 v35, 0x4600, v39
	ds_read2_b32 v[62:63], v35 offset0:66 offset1:131
	v_add_u32_e32 v35, 0x4800, v39
	s_ashr_i32 s11, s10, 31
	ds_read2_b32 v[64:65], v35 offset0:68 offset1:133
	s_lshr_b32 s11, s11, 28
	s_add_i32 s11, s10, s11
	s_and_b32 s12, s11, 0x3fffff0
	s_lshl_b32 s11, s11, 2
	v_add_u32_e32 v35, 0x4a00, v39
	s_andn2_b32 s11, s11, 63
	ds_read2_b32 v[66:67], v35 offset0:70 offset1:135
	s_waitcnt lgkmcnt(3)
	v_cvt_pk_bf16_f32 v60, v60, v61
	s_waitcnt lgkmcnt(2)
	v_cvt_pk_bf16_f32 v61, v62, v63
	s_waitcnt lgkmcnt(1)
	v_cvt_pk_bf16_f32 v62, v64, v65
	v_or_b32_e32 v64, s11, v38
	s_sub_i32 s10, s10, s12
	v_ashrrev_i32_e32 v65, 31, v64
	s_lshl_b32 s10, s10, 6
	v_lshlrev_b64 v[64:65], 11, v[64:65]
	v_lshl_add_u64 v[64:65], s[2:3], 0, v[64:65]
	s_ashr_i32 s11, s10, 31
	v_lshl_add_u64 v[64:65], s[10:11], 1, v[64:65]
	s_waitcnt lgkmcnt(0)
	v_cvt_pk_bf16_f32 v63, v66, v67
	v_lshl_add_u64 v[64:65], v[64:65], 0, v[36:37]
	global_store_dwordx4 v[64:65], v[60:63], off sc1
	s_add_i32 s10, s24, s20
	s_cmpk_gt_i32 s10, 0x37f
	s_cbranch_scc1 .LBB0_1705
.LBB0_1707:
	v_add_u32_e32 v35, 0x8400, v39
	ds_read2_b32 v[60:61], v35 offset0:128 offset1:193
	v_add_u32_e32 v35, 0x8800, v39
	s_ashr_i32 s11, s10, 31
	ds_read2_b32 v[62:63], v35 offset0:2 offset1:67
	ds_read2_b32 v[64:65], v35 offset0:132 offset1:197
	s_lshr_b32 s11, s11, 28
	s_add_i32 s11, s10, s11
	s_and_b32 s12, s11, 0x3fffff0
	s_lshl_b32 s11, s11, 2
	v_add_u32_e32 v35, 0x8c00, v39
	s_andn2_b32 s11, s11, 63
	ds_read2_b32 v[66:67], v35 offset0:6 offset1:71
	s_waitcnt lgkmcnt(3)
	v_cvt_pk_bf16_f32 v60, v60, v61
	s_waitcnt lgkmcnt(2)
	v_cvt_pk_bf16_f32 v61, v62, v63
	s_waitcnt lgkmcnt(1)
	v_cvt_pk_bf16_f32 v62, v64, v65
	v_or_b32_e32 v64, s11, v38
	s_sub_i32 s10, s10, s12
	v_ashrrev_i32_e32 v65, 31, v64
	s_lshl_b32 s10, s10, 6
	v_lshlrev_b64 v[64:65], 11, v[64:65]
	v_lshl_add_u64 v[64:65], s[2:3], 0, v[64:65]
	s_ashr_i32 s11, s10, 31
	v_lshl_add_u64 v[64:65], s[10:11], 1, v[64:65]
	s_waitcnt lgkmcnt(0)
	v_cvt_pk_bf16_f32 v63, v66, v67
	v_lshl_add_u64 v[64:65], v[64:65], 0, v[36:37]
	global_store_dwordx4 v[64:65], v[60:63], off sc1
	s_add_i32 s10, s16, s20
	s_cmpk_gt_i32 s10, 0x37f
	s_cbranch_scc1 .LBB0_1670
.LBB0_1708:
	v_add_u32_e32 v35, 0xc600, v39
	ds_read2_b32 v[60:61], v35 offset0:64 offset1:129
	v_add_u32_e32 v35, 0xc800, v39
	ds_read2_b32 v[62:63], v35 offset0:66 offset1:131
	v_add_u32_e32 v35, 0xca00, v39
	s_ashr_i32 s11, s10, 31
	ds_read2_b32 v[64:65], v35 offset0:68 offset1:133
	s_lshr_b32 s11, s11, 28
	s_add_i32 s11, s10, s11
	s_and_b32 s12, s11, 0x3fffff0
	s_lshl_b32 s11, s11, 2
	v_add_u32_e32 v35, 0xcc00, v39
	s_andn2_b32 s11, s11, 63
	ds_read2_b32 v[66:67], v35 offset0:70 offset1:135
	s_waitcnt lgkmcnt(3)
	v_cvt_pk_bf16_f32 v60, v60, v61
	s_waitcnt lgkmcnt(2)
	v_cvt_pk_bf16_f32 v61, v62, v63
	s_waitcnt lgkmcnt(1)
	v_cvt_pk_bf16_f32 v62, v64, v65
	v_or_b32_e32 v64, s11, v38
	s_sub_i32 s10, s10, s12
	v_ashrrev_i32_e32 v65, 31, v64
	s_lshl_b32 s10, s10, 6
	v_lshlrev_b64 v[64:65], 11, v[64:65]
	v_lshl_add_u64 v[64:65], s[2:3], 0, v[64:65]
	s_ashr_i32 s11, s10, 31
	v_lshl_add_u64 v[64:65], s[10:11], 1, v[64:65]
	s_waitcnt lgkmcnt(0)
	v_cvt_pk_bf16_f32 v63, v66, v67
	v_lshl_add_u64 v[64:65], v[64:65], 0, v[36:37]
	global_store_dwordx4 v[64:65], v[60:63], off sc1
	s_branch .LBB0_1670

.LBB0_1776:
	v_add_u32_e32 v35, 0x400, v39
	ds_read2_b32 v[60:61], v35 offset1:65
	ds_read2_b32 v[62:63], v35 offset0:130 offset1:195
	v_add_u32_e32 v35, 0x800, v39
	s_ashr_i32 s10, s20, 31
	ds_read2_b32 v[64:65], v35 offset0:4 offset1:69
	ds_read2_b32 v[66:67], v35 offset0:134 offset1:199
	s_lshr_b32 s10, s10, 28
	s_add_i32 s10, s20, s10
	s_ashr_i32 s11, s10, 4
	s_waitcnt lgkmcnt(3)
	v_cvt_pk_bf16_f32 v60, v60, v61
	s_waitcnt lgkmcnt(2)
	v_cvt_pk_bf16_f32 v61, v62, v63
	s_waitcnt lgkmcnt(1)
	v_cvt_pk_bf16_f32 v62, v64, v65
	v_lshl_or_b32 v64, s11, 6, v38
	s_lshl_b32 s10, s11, 10
	v_ashrrev_i32_e32 v65, 31, v64
	s_sub_i32 s10, s22, s10
	v_lshlrev_b64 v[64:65], 11, v[64:65]
	v_lshl_add_u64 v[64:65], s[2:3], 0, v[64:65]
	s_ashr_i32 s11, s10, 31
	v_lshl_add_u64 v[64:65], s[10:11], 1, v[64:65]
	s_add_i32 s10, s56, s20
	s_waitcnt lgkmcnt(0)
	v_cvt_pk_bf16_f32 v63, v66, v67
	v_lshl_add_u64 v[64:65], v[64:65], 0, v[36:37]
	s_cmpk_gt_i32 s10, 0xff
	global_store_dwordx4 v[64:65], v[60:63], off sc1
	s_cbranch_scc0 .LBB0_1779
	s_add_i32 s10, s24, s20
	s_cmpk_gt_i32 s10, 0xff
	s_cbranch_scc0 .LBB0_1780

.LBB0_1779:
	v_add_u32_e32 v35, 0x4400, v39
	ds_read2_b32 v[60:61], v35 offset0:64 offset1:129
	v_add_u32_e32 v35, 0x4600, v39
	ds_read2_b32 v[62:63], v35 offset0:66 offset1:131
	v_add_u32_e32 v35, 0x4800, v39
	s_ashr_i32 s11, s10, 31
	ds_read2_b32 v[64:65], v35 offset0:68 offset1:133
	s_lshr_b32 s11, s11, 28
	s_add_i32 s11, s10, s11
	s_and_b32 s12, s11, 0x3fffff0
	s_lshl_b32 s11, s11, 2
	v_add_u32_e32 v35, 0x4a00, v39
	s_andn2_b32 s11, s11, 63
	ds_read2_b32 v[66:67], v35 offset0:70 offset1:135
	s_waitcnt lgkmcnt(3)
	v_cvt_pk_bf16_f32 v60, v60, v61
	s_waitcnt lgkmcnt(2)
	v_cvt_pk_bf16_f32 v61, v62, v63
	s_waitcnt lgkmcnt(1)
	v_cvt_pk_bf16_f32 v62, v64, v65
	v_or_b32_e32 v64, s11, v38
	s_sub_i32 s10, s10, s12
	v_ashrrev_i32_e32 v65, 31, v64
	s_lshl_b32 s10, s10, 6
	v_lshlrev_b64 v[64:65], 11, v[64:65]
	v_lshl_add_u64 v[64:65], s[2:3], 0, v[64:65]
	s_ashr_i32 s11, s10, 31
	v_lshl_add_u64 v[64:65], s[10:11], 1, v[64:65]
	s_waitcnt lgkmcnt(0)
	v_cvt_pk_bf16_f32 v63, v66, v67
	v_lshl_add_u64 v[64:65], v[64:65], 0, v[36:37]
	global_store_dwordx4 v[64:65], v[60:63], off sc1
	s_add_i32 s10, s24, s20
	s_cmpk_gt_i32 s10, 0xff
	s_cbranch_scc1 .LBB0_1778
.LBB0_1780:
	v_add_u32_e32 v35, 0x8400, v39
	ds_read2_b32 v[60:61], v35 offset0:128 offset1:193
	v_add_u32_e32 v35, 0x8800, v39
	s_ashr_i32 s11, s10, 31
	ds_read2_b32 v[62:63], v35 offset0:2 offset1:67
	ds_read2_b32 v[64:65], v35 offset0:132 offset1:197
	s_lshr_b32 s11, s11, 28
	s_add_i32 s11, s10, s11
	s_and_b32 s12, s11, 0x3fffff0
	s_lshl_b32 s11, s11, 2
	v_add_u32_e32 v35, 0x8c00, v39
	s_andn2_b32 s11, s11, 63
	ds_read2_b32 v[66:67], v35 offset0:6 offset1:71
	s_waitcnt lgkmcnt(3)
	v_cvt_pk_bf16_f32 v60, v60, v61
	s_waitcnt lgkmcnt(2)
	v_cvt_pk_bf16_f32 v61, v62, v63
	s_waitcnt lgkmcnt(1)
	v_cvt_pk_bf16_f32 v62, v64, v65
	v_or_b32_e32 v64, s11, v38
	s_sub_i32 s10, s10, s12
	v_ashrrev_i32_e32 v65, 31, v64
	s_lshl_b32 s10, s10, 6
	v_lshlrev_b64 v[64:65], 11, v[64:65]
	v_lshl_add_u64 v[64:65], s[2:3], 0, v[64:65]
	s_ashr_i32 s11, s10, 31
	v_lshl_add_u64 v[64:65], s[10:11], 1, v[64:65]
	s_waitcnt lgkmcnt(0)
	v_cvt_pk_bf16_f32 v63, v66, v67
	v_lshl_add_u64 v[64:65], v[64:65], 0, v[36:37]
	global_store_dwordx4 v[64:65], v[60:63], off sc1
	s_add_i32 s10, s16, s20
	s_cmpk_gt_i32 s10, 0xff
	s_cbranch_scc1 .LBB0_1743

.LBB0_1849:
	s_ashr_i32 s10, s20, 31
	s_lshr_b32 s10, s10, 28
	s_add_i32 s10, s20, s10
	s_ashr_i32 s11, s10, 4
	v_add_u32_e32 v35, 0x400, v39
	s_lshl_b32 s10, s11, 10
	ds_read2_b32 v[60:61], v35 offset1:65
	ds_read2_b32 v[62:63], v35 offset0:130 offset1:195
	v_add_u32_e32 v35, 0x800, v39
	s_lshl_b32 s12, s11, 6
	s_lshl_b32 s11, s11, 7
	ds_read2_b32 v[64:65], v35 offset0:4 offset1:69
	ds_read2_b32 v[66:67], v35 offset0:134 offset1:199
	s_or_b32 s13, s11, 0x80
	s_sub_i32 s10, s22, s10
	s_addk_i32 s13, 0xea00
	s_and_b32 s11, s11, 0xffffff00
	s_cmpk_lt_i32 s20, 0x2c0
	s_cselect_b32 s11, s11, s13
	v_and_or_b32 v35, s12, 64, v38
	s_waitcnt lgkmcnt(3)
	v_cvt_pk_bf16_f32 v60, v60, v61
	s_waitcnt lgkmcnt(2)
	v_cvt_pk_bf16_f32 v61, v62, v63
	s_waitcnt lgkmcnt(1)
	v_cvt_pk_bf16_f32 v62, v64, v65
	v_or_b32_e32 v64, s11, v35
	v_ashrrev_i32_e32 v65, 31, v64
	v_lshlrev_b64 v[64:65], 11, v[64:65]
	v_lshl_add_u64 v[64:65], s[2:3], 0, v[64:65]
	s_ashr_i32 s11, s10, 31
	v_lshl_add_u64 v[64:65], s[10:11], 1, v[64:65]
	s_add_i32 s10, s56, s20
	s_waitcnt lgkmcnt(0)
	v_cvt_pk_bf16_f32 v63, v66, v67
	v_lshl_add_u64 v[64:65], v[64:65], 0, v[36:37]
	s_cmpk_gt_i32 s10, 0x57f
	global_store_dwordx4 v[64:65], v[60:63], off sc1
	s_cbranch_scc0 .LBB0_1852
	s_add_i32 s10, s24, s20
	s_cmpk_gt_i32 s10, 0x57f
	s_cbranch_scc0 .LBB0_1853

.LBB0_1852:
	s_ashr_i32 s11, s10, 31
	s_lshr_b32 s11, s11, 28
	s_add_i32 s11, s10, s11
	v_add_u32_e32 v35, 0x4400, v39
	s_ashr_i32 s13, s11, 4
	s_and_b32 s11, s11, 0x3fffff0
	ds_read2_b32 v[60:61], v35 offset0:64 offset1:129
	v_add_u32_e32 v35, 0x4600, v39
	s_sub_i32 s11, s10, s11
	ds_read2_b32 v[62:63], v35 offset0:66 offset1:131
	v_add_u32_e32 v35, 0x4800, v39
	s_lshl_b32 s12, s11, 6
	ds_read2_b32 v[64:65], v35 offset0:68 offset1:133
	s_lshl_b32 s11, s13, 6
	s_lshl_b32 s13, s13, 7
	s_and_b32 s14, s13, 0xffffff00
	s_bitset1_b32 s13, 7
	s_addk_i32 s13, 0xea00
	v_add_u32_e32 v35, 0x4a00, v39
	s_cmpk_lt_i32 s10, 0x2c0
	ds_read2_b32 v[66:67], v35 offset0:70 offset1:135
	s_cselect_b32 s10, s14, s13
	v_and_or_b32 v35, s11, 64, v38
	s_waitcnt lgkmcnt(3)
	v_cvt_pk_bf16_f32 v60, v60, v61
	s_waitcnt lgkmcnt(2)
	v_cvt_pk_bf16_f32 v61, v62, v63
	s_waitcnt lgkmcnt(1)
	v_cvt_pk_bf16_f32 v62, v64, v65
	v_or_b32_e32 v64, s10, v35
	v_ashrrev_i32_e32 v65, 31, v64
	v_lshlrev_b64 v[64:65], 11, v[64:65]
	v_lshl_add_u64 v[64:65], s[2:3], 0, v[64:65]
	s_ashr_i32 s13, s12, 31
	v_lshl_add_u64 v[64:65], s[12:13], 1, v[64:65]
	s_waitcnt lgkmcnt(0)
	v_cvt_pk_bf16_f32 v63, v66, v67
	v_lshl_add_u64 v[64:65], v[64:65], 0, v[36:37]
	global_store_dwordx4 v[64:65], v[60:63], off sc1
	s_add_i32 s10, s24, s20
	s_cmpk_gt_i32 s10, 0x57f
	s_cbranch_scc1 .LBB0_1851
.LBB0_1853:
	s_ashr_i32 s11, s10, 31
	s_lshr_b32 s11, s11, 28
	s_add_i32 s11, s10, s11
	s_ashr_i32 s13, s11, 4
	s_and_b32 s11, s11, 0x3fffff0
	v_add_u32_e32 v35, 0x8400, v39
	s_sub_i32 s11, s10, s11
	ds_read2_b32 v[60:61], v35 offset0:128 offset1:193
	v_add_u32_e32 v35, 0x8800, v39
	s_lshl_b32 s12, s11, 6
	ds_read2_b32 v[62:63], v35 offset0:2 offset1:67
	ds_read2_b32 v[64:65], v35 offset0:132 offset1:197
	s_lshl_b32 s11, s13, 6
	s_lshl_b32 s13, s13, 7
	s_and_b32 s14, s13, 0xffffff00
	s_bitset1_b32 s13, 7
	s_addk_i32 s13, 0xea00
	v_add_u32_e32 v35, 0x8c00, v39
	s_cmpk_lt_i32 s10, 0x2c0
	ds_read2_b32 v[66:67], v35 offset0:6 offset1:71
	s_cselect_b32 s10, s14, s13
	v_and_or_b32 v35, s11, 64, v38
	s_waitcnt lgkmcnt(3)
	v_cvt_pk_bf16_f32 v60, v60, v61
	s_waitcnt lgkmcnt(2)
	v_cvt_pk_bf16_f32 v61, v62, v63
	s_waitcnt lgkmcnt(1)
	v_cvt_pk_bf16_f32 v62, v64, v65
	v_or_b32_e32 v64, s10, v35
	v_ashrrev_i32_e32 v65, 31, v64
	v_lshlrev_b64 v[64:65], 11, v[64:65]
	v_lshl_add_u64 v[64:65], s[2:3], 0, v[64:65]
	s_ashr_i32 s13, s12, 31
	v_lshl_add_u64 v[64:65], s[12:13], 1, v[64:65]
	s_waitcnt lgkmcnt(0)
	v_cvt_pk_bf16_f32 v63, v66, v67
	v_lshl_add_u64 v[64:65], v[64:65], 0, v[36:37]
	global_store_dwordx4 v[64:65], v[60:63], off sc1
	s_add_i32 s10, s16, s20
	s_cmpk_gt_i32 s10, 0x57f
	s_cbranch_scc1 .LBB0_1816
.LBB0_1854:
	s_ashr_i32 s11, s10, 31
	s_lshr_b32 s11, s11, 28
	s_add_i32 s11, s10, s11
	v_add_u32_e32 v35, 0xc600, v39
	s_ashr_i32 s13, s11, 4
	s_and_b32 s11, s11, 0x3fffff0
	ds_read2_b32 v[60:61], v35 offset0:64 offset1:129
	v_add_u32_e32 v35, 0xc800, v39
	s_sub_i32 s11, s10, s11
	ds_read2_b32 v[62:63], v35 offset0:66 offset1:131
	v_add_u32_e32 v35, 0xca00, v39
	s_lshl_b32 s12, s11, 6
	ds_read2_b32 v[64:65], v35 offset0:68 offset1:133
	s_lshl_b32 s11, s13, 6
	s_lshl_b32 s13, s13, 7
	s_and_b32 s14, s13, 0xffffff00
	s_bitset1_b32 s13, 7
	s_addk_i32 s13, 0xea00
	v_add_u32_e32 v35, 0xcc00, v39
	s_cmpk_lt_i32 s10, 0x2c0
	ds_read2_b32 v[66:67], v35 offset0:70 offset1:135
	s_cselect_b32 s10, s14, s13
	v_and_or_b32 v35, s11, 64, v38
	s_waitcnt lgkmcnt(3)
	v_cvt_pk_bf16_f32 v60, v60, v61
	s_waitcnt lgkmcnt(2)
	v_cvt_pk_bf16_f32 v61, v62, v63
	s_waitcnt lgkmcnt(1)
	v_cvt_pk_bf16_f32 v62, v64, v65
	v_or_b32_e32 v64, s10, v35
	v_ashrrev_i32_e32 v65, 31, v64
	v_lshlrev_b64 v[64:65], 11, v[64:65]
	v_lshl_add_u64 v[64:65], s[2:3], 0, v[64:65]
	s_ashr_i32 s13, s12, 31
	v_lshl_add_u64 v[64:65], s[12:13], 1, v[64:65]
	s_waitcnt lgkmcnt(0)
	v_cvt_pk_bf16_f32 v63, v66, v67
	v_lshl_add_u64 v[64:65], v[64:65], 0, v[36:37]
	global_store_dwordx4 v[64:65], v[60:63], off sc1
	s_branch .LBB0_1816

.LBB0_1922:
	v_add_u32_e32 v35, 0x400, v39
	ds_read2_b32 v[60:61], v35 offset1:65
	ds_read2_b32 v[62:63], v35 offset0:130 offset1:195
	v_add_u32_e32 v35, 0x800, v39
	s_mul_hi_i32 s10, s20, 0x2e8ba2e9
	ds_read2_b32 v[64:65], v35 offset0:4 offset1:69
	ds_read2_b32 v[66:67], v35 offset0:134 offset1:199
	s_lshr_b32 s11, s10, 31
	s_ashr_i32 s10, s10, 3
	s_add_i32 s11, s10, s11
	s_mul_i32 s10, s11, 0xfffff500
	s_add_i32 s10, s22, s10
	s_waitcnt lgkmcnt(3)
	v_cvt_pk_bf16_f32 v60, v60, v61
	s_waitcnt lgkmcnt(2)
	v_cvt_pk_bf16_f32 v61, v62, v63
	s_waitcnt lgkmcnt(1)
	v_cvt_pk_bf16_f32 v62, v64, v65
	v_lshl_or_b32 v35, s11, 6, v38
	v_mov_b64_e32 v[64:65], s[2:3]
	v_mad_i64_i32 v[64:65], s[12:13], v35, s29, v[64:65]
	s_ashr_i32 s11, s10, 31
	v_lshl_add_u64 v[64:65], s[10:11], 1, v[64:65]
	s_add_i32 s10, s56, s20
	s_waitcnt lgkmcnt(0)
	v_cvt_pk_bf16_f32 v63, v66, v67
	v_lshl_add_u64 v[64:65], v[64:65], 0, v[36:37]
	s_cmpk_gt_i32 s10, 0x2bf
	global_store_dwordx4 v[64:65], v[60:63], off sc1
	s_cbranch_scc0 .LBB0_1925
	s_add_i32 s10, s24, s20
	s_cmpk_gt_i32 s10, 0x2bf
	s_cbranch_scc0 .LBB0_1926

.LBB0_1925:
	v_add_u32_e32 v35, 0x4400, v39
	ds_read2_b32 v[60:61], v35 offset0:64 offset1:129
	v_add_u32_e32 v35, 0x4600, v39
	ds_read2_b32 v[62:63], v35 offset0:66 offset1:131
	v_add_u32_e32 v35, 0x4800, v39
	s_mul_hi_i32 s11, s10, 0x2e8ba2e9
	ds_read2_b32 v[64:65], v35 offset0:68 offset1:133
	s_lshr_b32 s12, s11, 31
	s_ashr_i32 s11, s11, 3
	s_add_i32 s11, s11, s12
	v_add_u32_e32 v35, 0x4a00, v39
	s_mul_i32 s12, s11, 44
	ds_read2_b32 v[66:67], v35 offset0:70 offset1:135
	s_sub_i32 s10, s10, s12
	s_lshl_b32 s10, s10, 6
	s_waitcnt lgkmcnt(3)
	v_cvt_pk_bf16_f32 v60, v60, v61
	s_waitcnt lgkmcnt(2)
	v_cvt_pk_bf16_f32 v61, v62, v63
	s_waitcnt lgkmcnt(1)
	v_cvt_pk_bf16_f32 v62, v64, v65
	v_lshl_or_b32 v35, s11, 6, v38
	v_mov_b64_e32 v[64:65], s[2:3]
	v_mad_i64_i32 v[64:65], s[12:13], v35, s29, v[64:65]
	s_ashr_i32 s11, s10, 31
	v_lshl_add_u64 v[64:65], s[10:11], 1, v[64:65]
	s_waitcnt lgkmcnt(0)
	v_cvt_pk_bf16_f32 v63, v66, v67
	v_lshl_add_u64 v[64:65], v[64:65], 0, v[36:37]
	global_store_dwordx4 v[64:65], v[60:63], off sc1
	s_add_i32 s10, s24, s20
	s_cmpk_gt_i32 s10, 0x2bf
	s_cbranch_scc1 .LBB0_1924
.LBB0_1926:
	v_add_u32_e32 v35, 0x8400, v39
	ds_read2_b32 v[60:61], v35 offset0:128 offset1:193
	v_add_u32_e32 v35, 0x8800, v39
	s_mul_hi_i32 s11, s10, 0x2e8ba2e9
	ds_read2_b32 v[62:63], v35 offset0:2 offset1:67
	ds_read2_b32 v[64:65], v35 offset0:132 offset1:197
	s_lshr_b32 s12, s11, 31
	s_ashr_i32 s11, s11, 3
	s_add_i32 s11, s11, s12
	v_add_u32_e32 v35, 0x8c00, v39
	s_mul_i32 s12, s11, 44
	ds_read2_b32 v[66:67], v35 offset0:6 offset1:71
	s_sub_i32 s10, s10, s12
	s_lshl_b32 s10, s10, 6
	s_waitcnt lgkmcnt(3)
	v_cvt_pk_bf16_f32 v60, v60, v61
	s_waitcnt lgkmcnt(2)
	v_cvt_pk_bf16_f32 v61, v62, v63
	s_waitcnt lgkmcnt(1)
	v_cvt_pk_bf16_f32 v62, v64, v65
	v_lshl_or_b32 v35, s11, 6, v38
	v_mov_b64_e32 v[64:65], s[2:3]
	v_mad_i64_i32 v[64:65], s[12:13], v35, s29, v[64:65]
	s_ashr_i32 s11, s10, 31
	v_lshl_add_u64 v[64:65], s[10:11], 1, v[64:65]
	s_waitcnt lgkmcnt(0)
	v_cvt_pk_bf16_f32 v63, v66, v67
	v_lshl_add_u64 v[64:65], v[64:65], 0, v[36:37]
	global_store_dwordx4 v[64:65], v[60:63], off sc1
	s_add_i32 s10, s16, s20
	s_cmpk_gt_i32 s10, 0x2bf
	s_cbranch_scc1 .LBB0_1889
.LBB0_1927:
	v_add_u32_e32 v35, 0xc600, v39
	ds_read2_b32 v[60:61], v35 offset0:64 offset1:129
	v_add_u32_e32 v35, 0xc800, v39
	ds_read2_b32 v[62:63], v35 offset0:66 offset1:131
	v_add_u32_e32 v35, 0xca00, v39
	s_mul_hi_i32 s11, s10, 0x2e8ba2e9
	ds_read2_b32 v[64:65], v35 offset0:68 offset1:133
	s_lshr_b32 s12, s11, 31
	s_ashr_i32 s11, s11, 3
	s_add_i32 s11, s11, s12
	v_add_u32_e32 v35, 0xcc00, v39
	s_mul_i32 s12, s11, 44
	ds_read2_b32 v[66:67], v35 offset0:70 offset1:135
	s_sub_i32 s10, s10, s12
	s_lshl_b32 s10, s10, 6
	s_waitcnt lgkmcnt(3)
	v_cvt_pk_bf16_f32 v60, v60, v61
	s_waitcnt lgkmcnt(2)
	v_cvt_pk_bf16_f32 v61, v62, v63
	s_waitcnt lgkmcnt(1)
	v_cvt_pk_bf16_f32 v62, v64, v65
	v_lshl_or_b32 v35, s11, 6, v38
	v_mov_b64_e32 v[64:65], s[2:3]
	v_mad_i64_i32 v[64:65], s[12:13], v35, s29, v[64:65]
	s_ashr_i32 s11, s10, 31
	v_lshl_add_u64 v[64:65], s[10:11], 1, v[64:65]
	s_waitcnt lgkmcnt(0)
	v_cvt_pk_bf16_f32 v63, v66, v67
	v_lshl_add_u64 v[64:65], v[64:65], 0, v[36:37]
	global_store_dwordx4 v[64:65], v[60:63], off sc1
	s_branch .LBB0_1889

.LBB0_1995:
	v_add_u32_e32 v72, 0x400, v47
	ds_read2_b32 v[70:71], v72 offset1:65
	ds_read2_b32 v[72:73], v72 offset0:130 offset1:195
	v_add_u32_e32 v76, 0x800, v47
	ds_read2_b32 v[74:75], v76 offset0:4 offset1:69
	ds_read2_b32 v[76:77], v76 offset0:134 offset1:199
	s_add_i32 s2, s56, s24
	s_waitcnt lgkmcnt(3)
	v_cvt_pk_bf16_f32 v70, v70, v71
	s_waitcnt lgkmcnt(2)
	v_cvt_pk_bf16_f32 v71, v72, v73
	s_waitcnt lgkmcnt(1)
	v_cvt_pk_bf16_f32 v72, v74, v75
	v_add_u32_e32 v74, s13, v35
	v_ashrrev_i32_e32 v75, 31, v74
	v_lshlrev_b64 v[74:75], 7, v[74:75]
	s_waitcnt lgkmcnt(0)
	v_cvt_pk_bf16_f32 v73, v76, v77
	v_lshl_add_u64 v[74:75], v[38:39], 0, v[74:75]
	s_cmp_gt_i32 s2, 7
	global_store_dwordx4 v[74:75], v[70:73], off sc1
	s_cbranch_scc0 .LBB0_1998
	s_add_i32 s2, s26, s24
	s_cmp_gt_i32 s2, 7
	s_cbranch_scc0 .LBB0_1999

.LBB0_1998:
	s_nop 0
	v_add_u32_e32 v70, 0x4400, v47
	v_add_u32_e32 v72, 0x4600, v47
	v_add_u32_e32 v74, 0x4800, v47
	ds_read2_b32 v[70:71], v70 offset0:64 offset1:129
	ds_read2_b32 v[72:73], v72 offset0:66 offset1:131
	ds_read2_b32 v[74:75], v74 offset0:68 offset1:133
	v_add_u32_e32 v76, 0x4a00, v47
	ds_read2_b32 v[76:77], v76 offset0:70 offset1:135
	s_waitcnt lgkmcnt(3)
	v_cvt_pk_bf16_f32 v70, v70, v71
	s_waitcnt lgkmcnt(2)
	v_cvt_pk_bf16_f32 v71, v72, v73
	s_waitcnt lgkmcnt(1)
	v_cvt_pk_bf16_f32 v72, v74, v75
	v_add_u32_e32 v74, s13, v49
	v_ashrrev_i32_e32 v75, 31, v74
	v_lshlrev_b64 v[74:75], 7, v[74:75]
	s_waitcnt lgkmcnt(0)
	v_cvt_pk_bf16_f32 v73, v76, v77
	v_lshl_add_u64 v[74:75], v[38:39], 0, v[74:75]
	global_store_dwordx4 v[74:75], v[70:73], off sc1
	s_add_i32 s2, s26, s24
	s_cmp_gt_i32 s2, 7
	s_cbranch_scc1 .LBB0_1997
.LBB0_1999:
	v_add_u32_e32 v70, 0x8400, v47
	v_add_u32_e32 v74, 0x8800, v47
	ds_read2_b32 v[70:71], v70 offset0:128 offset1:193
	ds_read2_b32 v[72:73], v74 offset0:2 offset1:67
	ds_read2_b32 v[74:75], v74 offset0:132 offset1:197
	v_add_u32_e32 v76, 0x8c00, v47
	ds_read2_b32 v[76:77], v76 offset0:6 offset1:71
	s_waitcnt lgkmcnt(3)
	v_cvt_pk_bf16_f32 v70, v70, v71
	s_waitcnt lgkmcnt(2)
	v_cvt_pk_bf16_f32 v71, v72, v73
	s_waitcnt lgkmcnt(1)
	v_cvt_pk_bf16_f32 v72, v74, v75
	v_add_u32_e32 v74, s13, v37
	v_ashrrev_i32_e32 v75, 31, v74
	v_lshlrev_b64 v[74:75], 7, v[74:75]
	s_waitcnt lgkmcnt(0)
	v_cvt_pk_bf16_f32 v73, v76, v77
	v_lshl_add_u64 v[74:75], v[38:39], 0, v[74:75]
	global_store_dwordx4 v[74:75], v[70:73], off sc1
	s_add_i32 s2, s16, s24
	s_cmp_gt_i32 s2, 7
	s_cbranch_scc1 .LBB0_1962
.LBB0_2000:
	v_add_u32_e32 v70, 0xc600, v47
	v_add_u32_e32 v72, 0xc800, v47
	v_add_u32_e32 v74, 0xca00, v47
	ds_read2_b32 v[70:71], v70 offset0:64 offset1:129
	ds_read2_b32 v[72:73], v72 offset0:66 offset1:131
	ds_read2_b32 v[74:75], v74 offset0:68 offset1:133
	v_add_u32_e32 v76, 0xcc00, v47
	ds_read2_b32 v[76:77], v76 offset0:70 offset1:135
	s_waitcnt lgkmcnt(3)
	v_cvt_pk_bf16_f32 v70, v70, v71
	s_waitcnt lgkmcnt(2)
	v_cvt_pk_bf16_f32 v71, v72, v73
	s_waitcnt lgkmcnt(1)
	v_cvt_pk_bf16_f32 v72, v74, v75
	v_add_u32_e32 v74, s13, v48
	v_ashrrev_i32_e32 v75, 31, v74
	v_lshlrev_b64 v[74:75], 7, v[74:75]
	s_waitcnt lgkmcnt(0)
	v_cvt_pk_bf16_f32 v73, v76, v77
	v_lshl_add_u64 v[74:75], v[38:39], 0, v[74:75]
	global_store_dwordx4 v[74:75], v[70:73], off sc1
	s_branch .LBB0_1962

.LBB0_2216:
	v_add_u32_e32 v69, 0x400, v42
	ds_read2_b32 v[70:71], v69 offset1:65
	ds_read2_b32 v[72:73], v69 offset0:130 offset1:195
	v_add_u32_e32 v69, 0x800, v42
	ds_read2_b32 v[74:75], v69 offset0:4 offset1:69
	ds_read2_b32 v[76:77], v69 offset0:134 offset1:199
	s_add_i32 s2, s56, s24
	s_waitcnt lgkmcnt(3)
	v_cvt_pk_bf16_f32 v70, v70, v71
	s_waitcnt lgkmcnt(2)
	v_cvt_pk_bf16_f32 v71, v72, v73
	s_waitcnt lgkmcnt(1)
	v_cvt_pk_bf16_f32 v72, v74, v75
	v_add_u32_e32 v74, s13, v35
	v_ashrrev_i32_e32 v75, 31, v74
	v_lshlrev_b64 v[74:75], 7, v[74:75]
	s_waitcnt lgkmcnt(0)
	v_cvt_pk_bf16_f32 v73, v76, v77
	v_lshl_add_u64 v[74:75], v[38:39], 0, v[74:75]
	s_cmp_gt_i32 s2, 7
	global_store_dwordx4 v[74:75], v[70:73], off sc1
	s_cbranch_scc0 .LBB0_2219
	s_add_i32 s2, s26, s24
	s_cmp_gt_i32 s2, 7
	s_cbranch_scc0 .LBB0_2220

.LBB0_2219:
	v_add_u32_e32 v69, 0x4400, v42
	ds_read2_b32 v[70:71], v69 offset0:64 offset1:129
	v_add_u32_e32 v69, 0x4600, v42
	ds_read2_b32 v[72:73], v69 offset0:66 offset1:131
	v_add_u32_e32 v69, 0x4800, v42
	ds_read2_b32 v[74:75], v69 offset0:68 offset1:133
	v_add_u32_e32 v69, 0x4a00, v42
	ds_read2_b32 v[76:77], v69 offset0:70 offset1:135
	s_waitcnt lgkmcnt(3)
	v_cvt_pk_bf16_f32 v70, v70, v71
	s_waitcnt lgkmcnt(2)
	v_cvt_pk_bf16_f32 v71, v72, v73
	s_waitcnt lgkmcnt(1)
	v_cvt_pk_bf16_f32 v72, v74, v75
	v_add_u32_e32 v74, s13, v48
	v_ashrrev_i32_e32 v75, 31, v74
	v_lshlrev_b64 v[74:75], 7, v[74:75]
	s_waitcnt lgkmcnt(0)
	v_cvt_pk_bf16_f32 v73, v76, v77
	v_lshl_add_u64 v[74:75], v[38:39], 0, v[74:75]
	global_store_dwordx4 v[74:75], v[70:73], off sc1
	s_add_i32 s2, s26, s24
	s_cmp_gt_i32 s2, 7
	s_cbranch_scc1 .LBB0_2218
.LBB0_2220:
	v_add_u32_e32 v69, 0x8400, v42
	ds_read2_b32 v[70:71], v69 offset0:128 offset1:193
	v_add_u32_e32 v69, 0x8800, v42
	ds_read2_b32 v[72:73], v69 offset0:2 offset1:67
	ds_read2_b32 v[74:75], v69 offset0:132 offset1:197
	v_add_u32_e32 v69, 0x8c00, v42
	ds_read2_b32 v[76:77], v69 offset0:6 offset1:71
	s_waitcnt lgkmcnt(3)
	v_cvt_pk_bf16_f32 v70, v70, v71
	s_waitcnt lgkmcnt(2)
	v_cvt_pk_bf16_f32 v71, v72, v73
	s_waitcnt lgkmcnt(1)
	v_cvt_pk_bf16_f32 v72, v74, v75
	v_add_u32_e32 v74, s13, v43
	v_ashrrev_i32_e32 v75, 31, v74
	v_lshlrev_b64 v[74:75], 7, v[74:75]
	s_waitcnt lgkmcnt(0)
	v_cvt_pk_bf16_f32 v73, v76, v77
	v_lshl_add_u64 v[74:75], v[38:39], 0, v[74:75]
	global_store_dwordx4 v[74:75], v[70:73], off sc1
	s_add_i32 s2, s16, s24
	s_cmp_gt_i32 s2, 7
	s_cbranch_scc1 .LBB0_2183
.LBB0_2221:
	v_add_u32_e32 v69, 0xc600, v42
	ds_read2_b32 v[70:71], v69 offset0:64 offset1:129
	v_add_u32_e32 v69, 0xc800, v42
	ds_read2_b32 v[72:73], v69 offset0:66 offset1:131
	v_add_u32_e32 v69, 0xca00, v42
	ds_read2_b32 v[74:75], v69 offset0:68 offset1:133
	v_add_u32_e32 v69, 0xcc00, v42
	ds_read2_b32 v[76:77], v69 offset0:70 offset1:135
	s_waitcnt lgkmcnt(3)
	v_cvt_pk_bf16_f32 v70, v70, v71
	s_waitcnt lgkmcnt(2)
	v_cvt_pk_bf16_f32 v71, v72, v73
	s_waitcnt lgkmcnt(1)
	v_cvt_pk_bf16_f32 v72, v74, v75
	v_add_u32_e32 v74, s13, v47
	v_ashrrev_i32_e32 v75, 31, v74
	v_lshlrev_b64 v[74:75], 7, v[74:75]
	s_waitcnt lgkmcnt(0)
	v_cvt_pk_bf16_f32 v73, v76, v77
	v_lshl_add_u64 v[74:75], v[38:39], 0, v[74:75]
	global_store_dwordx4 v[74:75], v[70:73], off sc1
	s_branch .LBB0_2183

.LBB0_2289:
	v_add_u32_e32 v35, 0x400, v39
	ds_read2_b32 v[60:61], v35 offset1:65
	ds_read2_b32 v[62:63], v35 offset0:130 offset1:195
	v_add_u32_e32 v35, 0x800, v39
	ds_read2_b32 v[64:65], v35 offset0:4 offset1:69
	ds_read2_b32 v[66:67], v35 offset0:134 offset1:199
	s_lshr_b32 s8, s14, 31
	s_add_i32 s8, s14, s8
	s_ashr_i32 s9, s8, 1
	s_waitcnt lgkmcnt(3)
	v_cvt_pk_bf16_f32 v60, v60, v61
	s_waitcnt lgkmcnt(2)
	v_cvt_pk_bf16_f32 v61, v62, v63
	s_waitcnt lgkmcnt(1)
	v_cvt_pk_bf16_f32 v62, v64, v65
	v_lshl_or_b32 v64, s9, 6, v38
	s_lshl_b32 s8, s9, 7
	v_ashrrev_i32_e32 v65, 31, v64
	s_sub_i32 s8, s17, s8
	v_lshlrev_b64 v[64:65], 8, v[64:65]
	v_lshl_add_u64 v[64:65], s[2:3], 0, v[64:65]
	s_ashr_i32 s9, s8, 31
	v_lshl_add_u64 v[64:65], s[8:9], 1, v[64:65]
	s_add_i32 s8, s56, s14
	s_waitcnt lgkmcnt(0)
	v_cvt_pk_bf16_f32 v63, v66, v67
	v_lshl_add_u64 v[64:65], v[64:65], 0, v[36:37]
	s_cmp_gt_i32 s8, 15
	global_store_dwordx4 v[64:65], v[60:63], off sc1
	s_cbranch_scc0 .LBB0_2292
	s_add_i32 s8, s19, s14
	s_cmp_gt_i32 s8, 15
	s_cbranch_scc0 .LBB0_2293

.LBB0_2292:
	v_add_u32_e32 v35, 0x4400, v39
	ds_read2_b32 v[60:61], v35 offset0:64 offset1:129
	v_add_u32_e32 v35, 0x4600, v39
	ds_read2_b32 v[62:63], v35 offset0:66 offset1:131
	v_add_u32_e32 v35, 0x4800, v39
	ds_read2_b32 v[64:65], v35 offset0:68 offset1:133
	s_lshr_b32 s9, s8, 31
	s_add_i32 s9, s8, s9
	s_and_b32 s10, s9, 0x3fffffe
	s_lshl_b32 s9, s9, 5
	v_add_u32_e32 v35, 0x4a00, v39
	s_andn2_b32 s9, s9, 63
	ds_read2_b32 v[66:67], v35 offset0:70 offset1:135
	s_waitcnt lgkmcnt(3)
	v_cvt_pk_bf16_f32 v60, v60, v61
	s_waitcnt lgkmcnt(2)
	v_cvt_pk_bf16_f32 v61, v62, v63
	s_waitcnt lgkmcnt(1)
	v_cvt_pk_bf16_f32 v62, v64, v65
	v_or_b32_e32 v64, s9, v38
	s_sub_i32 s8, s8, s10
	v_ashrrev_i32_e32 v65, 31, v64
	s_lshl_b32 s8, s8, 6
	v_lshlrev_b64 v[64:65], 8, v[64:65]
	v_lshl_add_u64 v[64:65], s[2:3], 0, v[64:65]
	s_ashr_i32 s9, s8, 31
	v_lshl_add_u64 v[64:65], s[8:9], 1, v[64:65]
	s_waitcnt lgkmcnt(0)
	v_cvt_pk_bf16_f32 v63, v66, v67
	v_lshl_add_u64 v[64:65], v[64:65], 0, v[36:37]
	global_store_dwordx4 v[64:65], v[60:63], off sc1
	s_add_i32 s8, s19, s14
	s_cmp_gt_i32 s8, 15
	s_cbranch_scc1 .LBB0_2291
.LBB0_2293:
	v_add_u32_e32 v35, 0x8400, v39
	ds_read2_b32 v[60:61], v35 offset0:128 offset1:193
	v_add_u32_e32 v35, 0x8800, v39
	ds_read2_b32 v[62:63], v35 offset0:2 offset1:67
	ds_read2_b32 v[64:65], v35 offset0:132 offset1:197
	s_lshr_b32 s9, s8, 31
	s_add_i32 s9, s8, s9
	s_and_b32 s10, s9, 0x3fffffe
	s_lshl_b32 s9, s9, 5
	v_add_u32_e32 v35, 0x8c00, v39
	s_andn2_b32 s9, s9, 63
	ds_read2_b32 v[66:67], v35 offset0:6 offset1:71
	s_waitcnt lgkmcnt(3)
	v_cvt_pk_bf16_f32 v60, v60, v61
	s_waitcnt lgkmcnt(2)
	v_cvt_pk_bf16_f32 v61, v62, v63
	s_waitcnt lgkmcnt(1)
	v_cvt_pk_bf16_f32 v62, v64, v65
	v_or_b32_e32 v64, s9, v38
	s_sub_i32 s8, s8, s10
	v_ashrrev_i32_e32 v65, 31, v64
	s_lshl_b32 s8, s8, 6
	v_lshlrev_b64 v[64:65], 8, v[64:65]
	v_lshl_add_u64 v[64:65], s[2:3], 0, v[64:65]
	s_ashr_i32 s9, s8, 31
	v_lshl_add_u64 v[64:65], s[8:9], 1, v[64:65]
	s_waitcnt lgkmcnt(0)
	v_cvt_pk_bf16_f32 v63, v66, v67
	v_lshl_add_u64 v[64:65], v[64:65], 0, v[36:37]
	global_store_dwordx4 v[64:65], v[60:63], off sc1
	s_add_i32 s8, s16, s14
	s_cmp_gt_i32 s8, 15
	s_cbranch_scc1 .LBB0_2256
.LBB0_2294:
	v_add_u32_e32 v35, 0xc600, v39
	ds_read2_b32 v[60:61], v35 offset0:64 offset1:129
	v_add_u32_e32 v35, 0xc800, v39
	ds_read2_b32 v[62:63], v35 offset0:66 offset1:131
	v_add_u32_e32 v35, 0xca00, v39
	ds_read2_b32 v[64:65], v35 offset0:68 offset1:133
	s_lshr_b32 s9, s8, 31
	s_add_i32 s9, s8, s9
	s_and_b32 s10, s9, 0x3fffffe
	s_lshl_b32 s9, s9, 5
	v_add_u32_e32 v35, 0xcc00, v39
	s_andn2_b32 s9, s9, 63
	ds_read2_b32 v[66:67], v35 offset0:70 offset1:135
	s_waitcnt lgkmcnt(3)
	v_cvt_pk_bf16_f32 v60, v60, v61
	s_waitcnt lgkmcnt(2)
	v_cvt_pk_bf16_f32 v61, v62, v63
	s_waitcnt lgkmcnt(1)
	v_cvt_pk_bf16_f32 v62, v64, v65
	v_or_b32_e32 v64, s9, v38
	s_sub_i32 s8, s8, s10
	v_ashrrev_i32_e32 v65, 31, v64
	s_lshl_b32 s8, s8, 6
	v_lshlrev_b64 v[64:65], 8, v[64:65]
	v_lshl_add_u64 v[64:65], s[2:3], 0, v[64:65]
	s_ashr_i32 s9, s8, 31
	v_lshl_add_u64 v[64:65], s[8:9], 1, v[64:65]
	s_waitcnt lgkmcnt(0)
	v_cvt_pk_bf16_f32 v63, v66, v67
	v_lshl_add_u64 v[64:65], v[64:65], 0, v[36:37]
	global_store_dwordx4 v[64:65], v[60:63], off sc1
	s_branch .LBB0_2256

.LBB0_2318:
	v_add_u32_e32 v39, 0x400, v50
	ds_read2_b32 v[46:47], v39 offset1:65
	ds_read2_b32 v[48:49], v39 offset0:130 offset1:195
	v_add_u32_e32 v39, 0x800, v50
	ds_read2_b32 v[52:53], v39 offset0:4 offset1:69
	ds_read2_b32 v[54:55], v39 offset0:134 offset1:199
	s_and_b32 s12, s19, 0x7fffffc0
	s_waitcnt lgkmcnt(3)
	v_cvt_pk_bf16_f32 v46, v46, v47
	s_waitcnt lgkmcnt(2)
	v_cvt_pk_bf16_f32 v47, v48, v49
	s_waitcnt lgkmcnt(1)
	v_cvt_pk_bf16_f32 v48, v52, v53
	v_or_b32_e32 v52, s12, v1
	v_mov_b32_e32 v53, v35
	v_lshlrev_b64 v[52:53], 11, v[52:53]
	v_lshl_add_u64 v[52:53], s[6:7], 0, v[52:53]
	v_lshl_add_u64 v[52:53], s[2:3], 1, v[52:53]
	s_waitcnt lgkmcnt(0)
	v_cvt_pk_bf16_f32 v49, v54, v55
	v_lshl_add_u64 v[52:53], v[52:53], 0, v[34:35]
	s_cmpk_gt_i32 s20, 0x33f
	global_store_dwordx4 v[52:53], v[46:49], off sc1
	s_cbranch_scc0 .LBB0_2321
	s_cmpk_gt_i32 s20, 0x2ff
	s_cbranch_scc0 .LBB0_2322

.LBB0_2321:
	v_add_u32_e32 v39, 0x4400, v50
	ds_read2_b32 v[46:47], v39 offset0:64 offset1:129
	v_add_u32_e32 v39, 0x4600, v50
	ds_read2_b32 v[48:49], v39 offset0:66 offset1:131
	v_add_u32_e32 v39, 0x4800, v50
	ds_read2_b32 v[52:53], v39 offset0:68 offset1:133
	v_add_u32_e32 v39, 0x4a00, v50
	s_and_b32 s12, s19, 0xffffffc0
	ds_read2_b32 v[54:55], v39 offset0:70 offset1:135
	s_waitcnt lgkmcnt(3)
	v_cvt_pk_bf16_f32 v46, v46, v47
	s_waitcnt lgkmcnt(2)
	v_cvt_pk_bf16_f32 v47, v48, v49
	s_waitcnt lgkmcnt(1)
	v_cvt_pk_bf16_f32 v48, v52, v53
	v_add_u32_e32 v52, s12, v44
	v_ashrrev_i32_e32 v53, 31, v52
	v_lshlrev_b64 v[52:53], 11, v[52:53]
	v_lshl_add_u64 v[52:53], s[6:7], 0, v[52:53]
	v_lshl_add_u64 v[52:53], s[2:3], 1, v[52:53]
	s_waitcnt lgkmcnt(0)
	v_cvt_pk_bf16_f32 v49, v54, v55
	v_lshl_add_u64 v[52:53], v[52:53], 0, v[34:35]
	global_store_dwordx4 v[52:53], v[46:49], off sc1
	s_cmpk_gt_i32 s20, 0x2ff
	s_cbranch_scc1 .LBB0_2320
.LBB0_2322:
	v_add_u32_e32 v39, 0x8400, v50
	ds_read2_b32 v[46:47], v39 offset0:128 offset1:193
	v_add_u32_e32 v39, 0x8800, v50
	ds_read2_b32 v[48:49], v39 offset0:2 offset1:67
	ds_read2_b32 v[52:53], v39 offset0:132 offset1:197
	v_add_u32_e32 v39, 0x8c00, v50
	s_and_b32 s12, s19, 0xffffffc0
	ds_read2_b32 v[54:55], v39 offset0:6 offset1:71
	s_waitcnt lgkmcnt(3)
	v_cvt_pk_bf16_f32 v46, v46, v47
	s_waitcnt lgkmcnt(2)
	v_cvt_pk_bf16_f32 v47, v48, v49
	s_waitcnt lgkmcnt(1)
	v_cvt_pk_bf16_f32 v48, v52, v53
	v_add_u32_e32 v52, s12, v43
	v_ashrrev_i32_e32 v53, 31, v52
	v_lshlrev_b64 v[52:53], 11, v[52:53]
	v_lshl_add_u64 v[52:53], s[6:7], 0, v[52:53]
	v_lshl_add_u64 v[52:53], s[2:3], 1, v[52:53]
	s_waitcnt lgkmcnt(0)
	v_cvt_pk_bf16_f32 v49, v54, v55
	v_lshl_add_u64 v[52:53], v[52:53], 0, v[34:35]
	global_store_dwordx4 v[52:53], v[46:49], off sc1
	s_cmpk_gt_i32 s20, 0x2bf
	s_cbranch_scc1 .LBB0_2298
.LBB0_2323:
	v_add_u32_e32 v39, 0xc600, v50
	ds_read2_b32 v[46:47], v39 offset0:64 offset1:129
	v_add_u32_e32 v39, 0xc800, v50
	ds_read2_b32 v[48:49], v39 offset0:66 offset1:131
	v_add_u32_e32 v39, 0xca00, v50
	ds_read2_b32 v[52:53], v39 offset0:68 offset1:133
	v_add_u32_e32 v39, 0xcc00, v50
	s_and_b32 s12, s19, 0xffffffc0
	ds_read2_b32 v[54:55], v39 offset0:70 offset1:135
	s_waitcnt lgkmcnt(3)
	v_cvt_pk_bf16_f32 v46, v46, v47
	s_waitcnt lgkmcnt(2)
	v_cvt_pk_bf16_f32 v47, v48, v49
	s_waitcnt lgkmcnt(1)
	v_cvt_pk_bf16_f32 v48, v52, v53
	v_add_u32_e32 v52, s12, v42
	v_ashrrev_i32_e32 v53, 31, v52
	v_lshlrev_b64 v[52:53], 11, v[52:53]
	v_lshl_add_u64 v[52:53], s[6:7], 0, v[52:53]
	v_lshl_add_u64 v[52:53], s[2:3], 1, v[52:53]
	s_waitcnt lgkmcnt(0)
	v_cvt_pk_bf16_f32 v49, v54, v55
	v_lshl_add_u64 v[52:53], v[52:53], 0, v[34:35]
	global_store_dwordx4 v[52:53], v[46:49], off sc1
	s_branch .LBB0_2298

.LBB0_2336:
	v_add_u32_e32 v14, 0x400, v51
	s_waitcnt vmcnt(1)
	ds_write2_b32 v14, v6, v7 offset1:1
	v_add_u32_e32 v6, 0x408, v51
	ds_write2_b32 v6, v8, v9 offset1:1
	v_add_u32_e32 v6, 0x2480, v51
	s_waitcnt vmcnt(0)
	ds_write2_b32 v6, v2, v3 offset1:1
	v_add_u32_e32 v2, 0x2488, v51
	ds_write2_b32 v2, v4, v5 offset1:1
	v_add_u32_e32 v2, 0x4500, v51
	ds_write2_b32 v2, v10, v11 offset1:1
	v_add_u32_e32 v2, 0x4508, v51
	ds_write2_b32 v2, v12, v13 offset1:1
	v_add_u32_e32 v2, 0x6580, v51
	ds_write2_b32 v2, v39, v15 offset1:1
	v_add_u32_e32 v2, 0x6588, v51
	ds_write2_b32 v2, v16, v17 offset1:1
	v_add_u32_e32 v2, 0x8600, v51
	ds_write2_b32 v2, v22, v23 offset1:1
	v_add_u32_e32 v2, 0x8608, v51
	ds_write2_b32 v2, v24, v25 offset1:1
	v_add_u32_e32 v2, 0xa680, v51
	ds_write2_b32 v2, v18, v19 offset1:1
	v_add_u32_e32 v2, 0xa688, v51
	ds_write2_b32 v2, v20, v21 offset1:1
	v_add_u32_e32 v2, 0xc700, v51
	ds_write2_b32 v2, v30, v31 offset1:1
	v_add_u32_e32 v2, 0xc708, v51
	ds_write2_b32 v2, v32, v33 offset1:1
	v_add_u32_e32 v2, 0xe780, v51
	ds_write2_b32 v2, v26, v27 offset1:1
	v_add_u32_e32 v2, 0xe788, v51
	v_add_u32_e32 v4, 0x400, v50
	ds_write2_b32 v2, v28, v29 offset1:1
	s_waitcnt lgkmcnt(0)
	s_barrier
	ds_read2_b32 v[2:3], v4 offset1:65
	ds_read2_b32 v[4:5], v4 offset0:130 offset1:195
	v_add_u32_e32 v8, 0x800, v50
	ds_read2_b32 v[6:7], v8 offset0:4 offset1:69
	ds_read2_b32 v[8:9], v8 offset0:134 offset1:199
	s_add_u32 s14, s8, 0x6c8000
	s_addc_u32 s15, s9, 0
	s_lshl_b32 s12, s18, 6
	v_mov_b32_e32 v35, 0
	s_and_b32 s13, s12, 0x3c0
	s_waitcnt lgkmcnt(3)
	v_cvt_pk_bf16_f32 v2, v2, v3
	s_waitcnt lgkmcnt(2)
	v_cvt_pk_bf16_f32 v3, v4, v5
	s_waitcnt lgkmcnt(1)
	v_cvt_pk_bf16_f32 v4, v6, v7
	v_add_lshl_u32 v6, s11, v1, 11
	v_mov_b32_e32 v7, v35
	s_mov_b32 s17, 0
	v_lshl_add_u64 v[6:7], s[14:15], 0, v[6:7]
	s_lshl_b32 s16, s13, 1
	v_lshl_add_u64 v[6:7], v[6:7], 0, s[16:17]
	s_waitcnt lgkmcnt(0)
	v_cvt_pk_bf16_f32 v5, v8, v9
	v_lshl_add_u64 v[6:7], v[6:7], 0, v[34:35]
	s_and_b64 vcc, exec, s[2:3]
	global_store_dwordx4 v[6:7], v[2:5], off sc1
	s_cbranch_vccz .LBB0_2389
	s_and_b64 vcc, exec, s[4:5]
	s_cbranch_vccz .LBB0_2390

.LBB0_2339:
	v_add_u32_e32 v2, 0xc600, v50
	v_add_u32_e32 v4, 0xc800, v50
	v_add_u32_e32 v6, 0xca00, v50
	ds_read2_b32 v[2:3], v2 offset0:64 offset1:129
	ds_read2_b32 v[4:5], v4 offset0:66 offset1:131
	ds_read2_b32 v[6:7], v6 offset0:68 offset1:133
	v_add_u32_e32 v8, 0xcc00, v50
	ds_read2_b32 v[8:9], v8 offset0:70 offset1:135
	s_waitcnt lgkmcnt(3)
	v_cvt_pk_bf16_f32 v2, v2, v3
	s_waitcnt lgkmcnt(2)
	v_cvt_pk_bf16_f32 v3, v4, v5
	s_waitcnt lgkmcnt(1)
	v_cvt_pk_bf16_f32 v4, v6, v7
	v_add_lshl_u32 v6, v42, s11, 11
	v_mov_b32_e32 v7, 0
	s_waitcnt lgkmcnt(0)
	v_cvt_pk_bf16_f32 v5, v8, v9
	v_lshl_add_u64 v[8:9], s[14:15], 0, v[6:7]
	v_lshl_add_u64 v[8:9], v[8:9], 0, s[16:17]
	v_mov_b32_e32 v35, v7
	v_lshl_add_u64 v[6:7], v[8:9], 0, v[34:35]
	global_store_dwordx4 v[6:7], v[2:5], off sc1

.LBB0_2383:
	v_add_u32_e32 v35, 0x400, v50
	ds_read2_b32 v[66:67], v35 offset1:65
	ds_read2_b32 v[68:69], v35 offset0:130 offset1:195
	v_add_u32_e32 v35, 0x800, v50
	ds_read2_b32 v[70:71], v35 offset0:4 offset1:69
	ds_read2_b32 v[72:73], v35 offset0:134 offset1:199
	v_add_u32_e32 v35, s2, v1
	s_waitcnt lgkmcnt(3)
	v_cvt_pk_bf16_f32 v66, v66, v67
	s_waitcnt lgkmcnt(2)
	v_cvt_pk_bf16_f32 v67, v68, v69
	s_waitcnt lgkmcnt(1)
	v_cvt_pk_bf16_f32 v68, v70, v71
	v_add_u32_e32 v70, 0xffff9000, v35
	v_ashrrev_i32_e32 v71, 31, v70
	v_lshlrev_b64 v[70:71], 7, v[70:71]
	s_waitcnt lgkmcnt(0)
	v_cvt_pk_bf16_f32 v69, v72, v73
	v_lshl_add_u64 v[70:71], v[44:45], 0, v[70:71]
	s_cmpk_gt_i32 s18, 0xffc7
	global_store_dwordx4 v[70:71], v[66:69], off sc1
	s_cbranch_scc0 .LBB0_2386
	s_cmpk_gt_i32 s18, 0xff87
	s_cbranch_scc0 .LBB0_2387

.LBB0_2386:
	v_add_u32_e32 v65, 0x4400, v50
	ds_read2_b32 v[66:67], v65 offset0:64 offset1:129
	v_add_u32_e32 v65, 0x4600, v50
	ds_read2_b32 v[68:69], v65 offset0:66 offset1:131
	v_add_u32_e32 v65, 0x4800, v50
	ds_read2_b32 v[70:71], v65 offset0:68 offset1:133
	v_add_u32_e32 v65, 0x4a00, v50
	ds_read2_b32 v[72:73], v65 offset0:70 offset1:135
	s_waitcnt lgkmcnt(3)
	v_cvt_pk_bf16_f32 v66, v66, v67
	s_waitcnt lgkmcnt(2)
	v_cvt_pk_bf16_f32 v67, v68, v69
	s_waitcnt lgkmcnt(1)
	v_cvt_pk_bf16_f32 v68, v70, v71
	v_add_u32_e32 v70, 0xffffa000, v35
	v_ashrrev_i32_e32 v71, 31, v70
	v_lshlrev_b64 v[70:71], 7, v[70:71]
	s_waitcnt lgkmcnt(0)
	v_cvt_pk_bf16_f32 v69, v72, v73
	v_lshl_add_u64 v[70:71], v[44:45], 0, v[70:71]
	global_store_dwordx4 v[70:71], v[66:69], off sc1
	s_cmpk_gt_i32 s18, 0xff87
	s_cbranch_scc1 .LBB0_2385
.LBB0_2387:
	v_add_u32_e32 v65, 0x8400, v50
	ds_read2_b32 v[66:67], v65 offset0:128 offset1:193
	v_add_u32_e32 v65, 0x8800, v50
	ds_read2_b32 v[68:69], v65 offset0:2 offset1:67
	ds_read2_b32 v[70:71], v65 offset0:132 offset1:197
	v_add_u32_e32 v65, 0x8c00, v50
	ds_read2_b32 v[72:73], v65 offset0:6 offset1:71
	s_waitcnt lgkmcnt(3)
	v_cvt_pk_bf16_f32 v66, v66, v67
	s_waitcnt lgkmcnt(2)
	v_cvt_pk_bf16_f32 v67, v68, v69
	s_waitcnt lgkmcnt(1)
	v_cvt_pk_bf16_f32 v68, v70, v71
	v_add_u32_e32 v70, 0xffffb000, v35
	v_ashrrev_i32_e32 v71, 31, v70
	v_lshlrev_b64 v[70:71], 7, v[70:71]
	s_waitcnt lgkmcnt(0)
	v_cvt_pk_bf16_f32 v69, v72, v73
	v_lshl_add_u64 v[70:71], v[44:45], 0, v[70:71]
	global_store_dwordx4 v[70:71], v[66:69], off sc1
	s_cmpk_gt_i32 s18, 0xff47
	s_cbranch_scc1 .LBB0_2350
.LBB0_2388:
	v_add_u32_e32 v65, 0xc600, v50
	ds_read2_b32 v[66:67], v65 offset0:64 offset1:129
	v_add_u32_e32 v65, 0xc800, v50
	ds_read2_b32 v[68:69], v65 offset0:66 offset1:131
	v_add_u32_e32 v65, 0xca00, v50
	ds_read2_b32 v[70:71], v65 offset0:68 offset1:133
	v_add_u32_e32 v65, 0xcc00, v50
	ds_read2_b32 v[72:73], v65 offset0:70 offset1:135
	s_waitcnt lgkmcnt(3)
	v_cvt_pk_bf16_f32 v66, v66, v67
	s_waitcnt lgkmcnt(2)
	v_cvt_pk_bf16_f32 v67, v68, v69
	s_waitcnt lgkmcnt(1)
	v_cvt_pk_bf16_f32 v68, v70, v71
	v_add_u32_e32 v70, 0xffffc000, v35
	v_ashrrev_i32_e32 v71, 31, v70
	v_lshlrev_b64 v[70:71], 7, v[70:71]
	s_waitcnt lgkmcnt(0)
	v_cvt_pk_bf16_f32 v69, v72, v73
	v_lshl_add_u64 v[70:71], v[44:45], 0, v[70:71]
	global_store_dwordx4 v[70:71], v[66:69], off sc1
	s_branch .LBB0_2350
.LBB0_2389:
	s_nop 0
	v_add_u32_e32 v2, 0x4400, v50
	v_add_u32_e32 v4, 0x4600, v50
	v_add_u32_e32 v6, 0x4800, v50
	ds_read2_b32 v[2:3], v2 offset0:64 offset1:129
	ds_read2_b32 v[4:5], v4 offset0:66 offset1:131
	ds_read2_b32 v[6:7], v6 offset0:68 offset1:133
	v_add_u32_e32 v8, 0x4a00, v50
	ds_read2_b32 v[8:9], v8 offset0:70 offset1:135
	s_waitcnt lgkmcnt(3)
	v_cvt_pk_bf16_f32 v2, v2, v3
	s_waitcnt lgkmcnt(2)
	v_cvt_pk_bf16_f32 v3, v4, v5
	s_waitcnt lgkmcnt(1)
	v_cvt_pk_bf16_f32 v4, v6, v7
	v_add_lshl_u32 v6, v44, s11, 11
	v_mov_b32_e32 v7, v35
	v_lshl_add_u64 v[6:7], s[14:15], 0, v[6:7]
	v_lshl_add_u64 v[6:7], v[6:7], 0, s[16:17]
	s_waitcnt lgkmcnt(0)
	v_cvt_pk_bf16_f32 v5, v8, v9
	v_lshl_add_u64 v[6:7], v[6:7], 0, v[34:35]
	global_store_dwordx4 v[6:7], v[2:5], off sc1
	s_and_b64 vcc, exec, s[4:5]
	s_cbranch_vccnz .LBB0_2338
.LBB0_2390:
	v_add_u32_e32 v2, 0x8400, v50
	v_add_u32_e32 v6, 0x8800, v50
	ds_read2_b32 v[2:3], v2 offset0:128 offset1:193
	ds_read2_b32 v[4:5], v6 offset0:2 offset1:67
	ds_read2_b32 v[6:7], v6 offset0:132 offset1:197
	v_add_u32_e32 v8, 0x8c00, v50
	ds_read2_b32 v[8:9], v8 offset0:6 offset1:71
	s_waitcnt lgkmcnt(3)
	v_cvt_pk_bf16_f32 v2, v2, v3
	s_waitcnt lgkmcnt(2)
	v_cvt_pk_bf16_f32 v3, v4, v5
	s_waitcnt lgkmcnt(1)
	v_cvt_pk_bf16_f32 v4, v6, v7
	v_add_lshl_u32 v6, v43, s11, 11
	v_mov_b32_e32 v7, 0
	s_waitcnt lgkmcnt(0)
	v_cvt_pk_bf16_f32 v5, v8, v9
	v_lshl_add_u64 v[8:9], s[14:15], 0, v[6:7]
	v_lshl_add_u64 v[8:9], v[8:9], 0, s[16:17]
	v_mov_b32_e32 v35, v7
	v_lshl_add_u64 v[6:7], v[8:9], 0, v[34:35]
	global_store_dwordx4 v[6:7], v[2:5], off sc1
	s_and_b64 vcc, exec, s[6:7]
	s_cbranch_vccz .LBB0_2339
	s_branch .LBB0_2340

.LBB0_2392:
	s_add_i32 s2, s30, 56
	s_and_b32 s2, s2, 63
	s_waitcnt lgkmcnt(0)
	v_readfirstlane_b32 s3, v10
	v_readfirstlane_b32 s4, v11
	s_cmp_gt_u32 s2, 7
	s_waitcnt vmcnt(0)
	v_lshlrev_b32_e32 v4, 7, v1
	s_cbranch_scc1 .LBB0_2394
	s_add_u32 s6, s3, 0x20000
	s_addc_u32 s7, s4, 0
	v_mov_b32_e32 v41, 0
	s_mov_b32 s5, 0
	v_lshl_add_u64 v[2:3], s[6:7], 0, v[40:41]
	s_lshl_b32 s4, s2, 8
	v_lshl_add_u64 v[2:3], v[2:3], 0, s[4:5]
	v_mov_b32_e32 v39, v41
	v_lshl_add_u64 v[2:3], v[2:3], 0, v[38:39]
	v_mov_b32_e32 v43, v41
	global_load_dwordx4 v[6:9], v[2:3], off
	v_lshl_add_u64 v[2:3], s[6:7], 0, v[42:43]
	v_lshl_add_u64 v[2:3], v[2:3], 0, s[4:5]
	v_lshl_add_u64 v[2:3], v[2:3], 0, v[38:39]
	global_load_dwordx4 v[10:13], v[2:3], off
	v_add_u32_e32 v5, 0x400, v51
	v_add_u32_e32 v3, 0x4500, v51
	v_add_u32_e32 v28, 0x400, v50
	v_add_u32_e32 v14, 0x408, v51
	v_add_u32_e32 v15, 0x2480, v51
	v_add_u32_e32 v16, 0x2488, v51
	v_add_u32_e32 v17, 0x4508, v51
	v_add_u32_e32 v18, 0x6580, v51
	v_add_u32_e32 v19, 0x6588, v51
	v_add_u32_e32 v20, 0x8600, v51
	v_add_u32_e32 v21, 0x8608, v51
	v_add_u32_e32 v22, 0xa680, v51
	v_add_u32_e32 v23, 0xa688, v51
	v_add_u32_e32 v24, 0xc700, v51
	v_add_u32_e32 v25, 0xc708, v51
	v_add_u32_e32 v26, 0xe780, v51
	v_add_u32_e32 v27, 0xe788, v51
	v_add_u32_e32 v29, 0x800, v50
	ds_write2_b32 v3, v41, v41 offset1:1
	ds_write2_b32 v17, v41, v41 offset1:1
	ds_write2_b32 v18, v41, v41 offset1:1
	ds_write2_b32 v19, v41, v41 offset1:1
	ds_write2_b32 v20, v41, v41 offset1:1
	ds_write2_b32 v21, v41, v41 offset1:1
	ds_write2_b32 v22, v41, v41 offset1:1
	ds_write2_b32 v23, v41, v41 offset1:1
	ds_write2_b32 v24, v41, v41 offset1:1
	ds_write2_b32 v25, v41, v41 offset1:1
	ds_write2_b32 v26, v41, v41 offset1:1
	ds_write2_b32 v27, v41, v41 offset1:1
	v_lshl_or_b32 v2, s2, 13, v4
	v_mov_b32_e32 v3, v41
	v_mov_b32_e32 v35, v41
	v_lshl_add_u64 v[2:3], s[8:9], 0, v[2:3]
	v_lshl_add_u64 v[2:3], v[2:3], 0, v[34:35]
	v_add_co_u32_e32 v2, vcc, 0x30d8000, v2
	s_waitcnt vmcnt(1)
	ds_write2_b32 v5, v6, v7 offset1:1
	ds_write2_b32 v14, v8, v9 offset1:1
	s_waitcnt vmcnt(0)
	ds_write2_b32 v15, v10, v11 offset1:1
	ds_write2_b32 v16, v12, v13 offset1:1
	s_waitcnt lgkmcnt(0)
	s_barrier
	ds_read2_b32 v[6:7], v28 offset1:65
	ds_read2_b32 v[8:9], v28 offset0:130 offset1:195
	ds_read2_b32 v[10:11], v29 offset0:4 offset1:69
	ds_read2_b32 v[12:13], v29 offset0:134 offset1:199
	v_addc_co_u32_e32 v3, vcc, 0, v3, vcc
	s_waitcnt lgkmcnt(3)
	v_cvt_pk_bf16_f32 v6, v6, v7
	s_waitcnt lgkmcnt(2)
	v_cvt_pk_bf16_f32 v7, v8, v9
	s_waitcnt lgkmcnt(1)
	v_cvt_pk_bf16_f32 v8, v10, v11
	s_waitcnt lgkmcnt(0)
	v_cvt_pk_bf16_f32 v9, v12, v13
	global_store_dwordx4 v[2:3], v[6:9], off sc1
	s_barrier
.LBB0_2394:
	v_mov_b32_e32 v41, 0
	ds_read_b64 v[2:3], v41 offset:360
	s_add_i32 s2, s30, 48
	s_and_b32 s6, s2, 63
	s_mov_b32 s3, 0
	s_cmp_gt_u32 s6, 7
	s_waitcnt lgkmcnt(0)
	v_readfirstlane_b32 s4, v2
	v_readfirstlane_b32 s5, v3
	s_cbranch_scc1 .LBB0_2396
	s_nop 0
	v_lshl_add_u64 v[2:3], s[4:5], 0, v[40:41]
	s_lshl_b32 s2, s6, 8
	v_lshl_add_u64 v[2:3], v[2:3], 0, s[2:3]
	v_mov_b32_e32 v39, v41
	v_lshl_add_u64 v[2:3], v[2:3], 0, v[38:39]
	v_mov_b32_e32 v43, v41
	global_load_dwordx4 v[6:9], v[2:3], off
	v_lshl_add_u64 v[2:3], s[4:5], 0, v[42:43]
	v_lshl_add_u64 v[2:3], v[2:3], 0, s[2:3]
	v_lshl_add_u64 v[2:3], v[2:3], 0, v[38:39]
	global_load_dwordx4 v[10:13], v[2:3], off
	v_add_u32_e32 v5, 0x400, v51
	v_add_u32_e32 v17, 0x4500, v51
	v_add_u32_e32 v29, 0x400, v50
	v_add_u32_e32 v14, 0x408, v51
	v_add_u32_e32 v15, 0x2480, v51
	v_add_u32_e32 v16, 0x2488, v51
	v_add_u32_e32 v18, 0x4508, v51
	v_add_u32_e32 v19, 0x6580, v51
	v_add_u32_e32 v20, 0x6588, v51
	v_add_u32_e32 v21, 0x8600, v51
	v_add_u32_e32 v22, 0x8608, v51
	v_add_u32_e32 v23, 0xa680, v51
	v_add_u32_e32 v24, 0xa688, v51
	v_add_u32_e32 v25, 0xc700, v51
	v_add_u32_e32 v26, 0xc708, v51
	v_add_u32_e32 v27, 0xe780, v51
	v_add_u32_e32 v28, 0xe788, v51
	v_add_u32_e32 v30, 0x800, v50
	ds_write2_b32 v17, v41, v41 offset1:1
	ds_write2_b32 v18, v41, v41 offset1:1
	ds_write2_b32 v19, v41, v41 offset1:1
	ds_write2_b32 v20, v41, v41 offset1:1
	ds_write2_b32 v21, v41, v41 offset1:1
	ds_write2_b32 v22, v41, v41 offset1:1
	ds_write2_b32 v23, v41, v41 offset1:1
	ds_write2_b32 v24, v41, v41 offset1:1
	ds_write2_b32 v25, v41, v41 offset1:1
	ds_write2_b32 v26, v41, v41 offset1:1
	ds_write2_b32 v27, v41, v41 offset1:1
	ds_write2_b32 v28, v41, v41 offset1:1
	v_lshl_or_b32 v2, s6, 13, v4
	v_mov_b32_e32 v3, v41
	v_mov_b32_e32 v35, v41
	v_lshl_add_u64 v[2:3], s[8:9], 0, v[2:3]
	v_lshl_add_u64 v[2:3], v[2:3], 0, v[34:35]
	v_add_co_u32_e32 v2, vcc, 0x30e8000, v2
	s_waitcnt vmcnt(1)
	ds_write2_b32 v5, v6, v7 offset1:1
	ds_write2_b32 v14, v8, v9 offset1:1
	s_waitcnt vmcnt(0)
	ds_write2_b32 v15, v10, v11 offset1:1
	ds_write2_b32 v16, v12, v13 offset1:1
	s_waitcnt lgkmcnt(0)
	s_barrier
	ds_read2_b32 v[6:7], v29 offset1:65
	ds_read2_b32 v[8:9], v29 offset0:130 offset1:195
	ds_read2_b32 v[10:11], v30 offset0:4 offset1:69
	ds_read2_b32 v[12:13], v30 offset0:134 offset1:199
	v_addc_co_u32_e32 v3, vcc, 0, v3, vcc
	s_waitcnt lgkmcnt(3)
	v_cvt_pk_bf16_f32 v6, v6, v7
	s_waitcnt lgkmcnt(2)
	v_cvt_pk_bf16_f32 v7, v8, v9
	s_waitcnt lgkmcnt(1)
	v_cvt_pk_bf16_f32 v8, v10, v11
	s_waitcnt lgkmcnt(0)
	v_cvt_pk_bf16_f32 v9, v12, v13
	global_store_dwordx4 v[2:3], v[6:9], off sc1
	s_barrier
	ds_read_b64 v[2:3], v41 offset:360
.LBB0_2396:
	s_add_i32 s2, s30, 40
	s_and_b32 s2, s2, 63
	s_waitcnt lgkmcnt(0)
	v_readfirstlane_b32 s3, v2
	s_cmp_gt_u32 s2, 7
	v_readfirstlane_b32 s4, v3
	s_cbranch_scc1 .LBB0_2398
	s_add_u32 s6, s3, 0x20000
	s_addc_u32 s7, s4, 0
	v_mov_b32_e32 v41, 0
	s_mov_b32 s5, 0
	v_lshl_add_u64 v[2:3], s[6:7], 0, v[40:41]
	s_lshl_b32 s4, s2, 8
	v_lshl_add_u64 v[2:3], v[2:3], 0, s[4:5]
	v_mov_b32_e32 v39, v41
	v_lshl_add_u64 v[2:3], v[2:3], 0, v[38:39]
	v_mov_b32_e32 v43, v41
	global_load_dwordx4 v[6:9], v[2:3], off
	v_lshl_add_u64 v[2:3], s[6:7], 0, v[42:43]
	v_lshl_add_u64 v[2:3], v[2:3], 0, s[4:5]
	v_lshl_add_u64 v[2:3], v[2:3], 0, v[38:39]
	global_load_dwordx4 v[10:13], v[2:3], off
	v_add_u32_e32 v5, 0x400, v51
	v_add_u32_e32 v2, 0x4500, v51
	v_add_u32_e32 v27, 0x400, v50
	v_add_u32_e32 v15, 0x408, v51
	v_add_u32_e32 v16, 0x2480, v51
	v_add_u32_e32 v17, 0x2488, v51
	v_add_u32_e32 v3, 0x4508, v51
	v_add_u32_e32 v14, 0x6580, v51
	v_add_u32_e32 v18, 0x6588, v51
	v_add_u32_e32 v19, 0x8600, v51
	v_add_u32_e32 v20, 0x8608, v51
	v_add_u32_e32 v21, 0xa680, v51
	v_add_u32_e32 v22, 0xa688, v51
	v_add_u32_e32 v23, 0xc700, v51
	v_add_u32_e32 v24, 0xc708, v51
	v_add_u32_e32 v25, 0xe780, v51
	v_add_u32_e32 v26, 0xe788, v51
	v_add_u32_e32 v28, 0x800, v50
	ds_write2_b32 v2, v41, v41 offset1:1
	ds_write2_b32 v3, v41, v41 offset1:1
	ds_write2_b32 v14, v41, v41 offset1:1
	ds_write2_b32 v18, v41, v41 offset1:1
	ds_write2_b32 v19, v41, v41 offset1:1
	ds_write2_b32 v20, v41, v41 offset1:1
	ds_write2_b32 v21, v41, v41 offset1:1
	ds_write2_b32 v22, v41, v41 offset1:1
	ds_write2_b32 v23, v41, v41 offset1:1
	ds_write2_b32 v24, v41, v41 offset1:1
	ds_write2_b32 v25, v41, v41 offset1:1
	ds_write2_b32 v26, v41, v41 offset1:1
	v_lshl_or_b32 v40, s2, 13, v4
	v_mov_b32_e32 v35, v41
	v_lshl_add_u64 v[2:3], s[8:9], 0, v[40:41]
	v_lshl_add_u64 v[2:3], v[2:3], 0, v[34:35]
	v_add_co_u32_e32 v14, vcc, 0x30f8000, v2
	s_waitcnt vmcnt(1)
	ds_write2_b32 v5, v6, v7 offset1:1
	ds_write2_b32 v15, v8, v9 offset1:1
	s_waitcnt vmcnt(0)
	ds_write2_b32 v16, v10, v11 offset1:1
	ds_write2_b32 v17, v12, v13 offset1:1
	s_waitcnt lgkmcnt(0)
	s_barrier
	ds_read2_b32 v[4:5], v27 offset1:65
	ds_read2_b32 v[6:7], v27 offset0:130 offset1:195
	ds_read2_b32 v[8:9], v28 offset0:4 offset1:69
	ds_read2_b32 v[10:11], v28 offset0:134 offset1:199
	v_addc_co_u32_e32 v15, vcc, 0, v3, vcc
	s_waitcnt lgkmcnt(3)
	v_cvt_pk_bf16_f32 v2, v4, v5
	s_waitcnt lgkmcnt(2)
	v_cvt_pk_bf16_f32 v3, v6, v7
	s_waitcnt lgkmcnt(1)
	v_cvt_pk_bf16_f32 v4, v8, v9
	s_waitcnt lgkmcnt(0)
	v_cvt_pk_bf16_f32 v5, v10, v11
	global_store_dwordx4 v[14:15], v[2:5], off sc1
	s_barrier
.LBB0_2398:
	s_nop 0
	v_mov_b32_e32 v3, 0
	ds_read_b64 v[4:5], v3 offset:368
	s_and_b32 s2, s30, 48
	s_mov_b32 s3, 0
	s_cmp_lg_u32 s2, 32
	s_waitcnt lgkmcnt(0)
	v_readfirstlane_b32 s4, v4
	v_readfirstlane_b32 s5, v5
	s_cbranch_scc1 .LBB0_2400
	s_and_b32 s7, s10, 64
	s_lshl_b32 s2, s30, 5
	v_or_b32_e32 v2, s7, v199
	s_and_b32 s6, s2, 0x1c0
	v_lshlrev_b32_e32 v2, 11, v2
	v_lshl_add_u64 v[4:5], s[4:5], 0, v[2:3]
	s_lshl_b32 s2, s6, 2
	v_or_b32_e32 v2, s7, v37
	v_lshl_add_u64 v[4:5], v[4:5], 0, s[2:3]
	v_mov_b32_e32 v39, v3
	v_lshlrev_b32_e32 v2, 11, v2
	v_lshl_add_u64 v[4:5], v[4:5], 0, v[38:39]
	v_lshl_add_u64 v[8:9], s[4:5], 0, v[2:3]
	global_load_dwordx4 v[4:7], v[4:5], off
	v_lshl_add_u64 v[8:9], v[8:9], 0, s[2:3]
	v_lshl_add_u64 v[8:9], v[8:9], 0, v[38:39]
	global_load_dwordx4 v[8:11], v[8:9], off
	v_add_u32_e32 v13, 0x400, v51
	v_add_u32_e32 v2, 0x4500, v51
	v_add_u32_e32 v27, 0x400, v50
	v_or_b32_e32 v1, s6, v1
	v_add_u32_e32 v14, 0x408, v51
	v_add_u32_e32 v15, 0x2480, v51
	v_add_u32_e32 v16, 0x2488, v51
	v_add_u32_e32 v12, 0x4508, v51
	v_add_u32_e32 v17, 0x6580, v51
	v_add_u32_e32 v18, 0x6588, v51
	v_add_u32_e32 v19, 0x8600, v51
	v_add_u32_e32 v20, 0x8608, v51
	v_add_u32_e32 v21, 0xa680, v51
	v_add_u32_e32 v22, 0xa688, v51
	v_add_u32_e32 v23, 0xc700, v51
	v_add_u32_e32 v24, 0xc708, v51
	v_add_u32_e32 v25, 0xe780, v51
	v_add_u32_e32 v26, 0xe788, v51
	v_add_u32_e32 v28, 0x800, v50
	ds_write2_b32 v2, v3, v3 offset1:1
	ds_write2_b32 v12, v3, v3 offset1:1
	ds_write2_b32 v17, v3, v3 offset1:1
	ds_write2_b32 v18, v3, v3 offset1:1
	ds_write2_b32 v19, v3, v3 offset1:1
	ds_write2_b32 v20, v3, v3 offset1:1
	ds_write2_b32 v21, v3, v3 offset1:1
	ds_write2_b32 v22, v3, v3 offset1:1
	ds_write2_b32 v23, v3, v3 offset1:1
	ds_write2_b32 v24, v3, v3 offset1:1
	ds_write2_b32 v25, v3, v3 offset1:1
	ds_write2_b32 v26, v3, v3 offset1:1
	v_lshlrev_b32_e32 v2, 8, v1
	v_mov_b32_e32 v35, v3
	v_lshl_add_u64 v[2:3], s[8:9], 0, v[2:3]
	s_lshl_b32 s2, s7, 1
	v_lshl_add_u64 v[2:3], v[2:3], 0, s[2:3]
	v_lshl_add_u64 v[2:3], v[2:3], 0, v[34:35]
	v_add_co_u32_e32 v12, vcc, 0x3108000, v2
	s_waitcnt vmcnt(1)
	ds_write2_b32 v13, v4, v5 offset1:1
	ds_write2_b32 v14, v6, v7 offset1:1
	s_waitcnt vmcnt(0)
	ds_write2_b32 v15, v8, v9 offset1:1
	ds_write2_b32 v16, v10, v11 offset1:1
	s_waitcnt lgkmcnt(0)
	s_barrier
	ds_read2_b32 v[4:5], v27 offset1:65
	ds_read2_b32 v[6:7], v27 offset0:130 offset1:195
	ds_read2_b32 v[8:9], v28 offset0:4 offset1:69
	ds_read2_b32 v[10:11], v28 offset0:134 offset1:199
	v_addc_co_u32_e32 v13, vcc, 0, v3, vcc
	s_waitcnt lgkmcnt(3)
	v_cvt_pk_bf16_f32 v2, v4, v5
	s_waitcnt lgkmcnt(2)
	v_cvt_pk_bf16_f32 v3, v6, v7
	s_waitcnt lgkmcnt(1)
	v_cvt_pk_bf16_f32 v4, v8, v9
	s_waitcnt lgkmcnt(0)
	v_cvt_pk_bf16_f32 v5, v10, v11
	global_store_dwordx4 v[12:13], v[2:5], off sc1
	s_barrier

.LBB0_2457:
	s_lshr_b32 s2, s2, 10
	s_mulk_i32 s2, 0x1800
	s_addk_i32 s2, 0x1800
	s_and_b64 s[12:13], s[12:13], exec
	s_cselect_b32 s2, 0, s2
	s_lshl_b64 s[12:13], s[18:19], 11
	v_lshl_add_u64 v[46:47], v[14:15], 0, s[12:13]
	global_load_dwordx2 v[34:35], v[46:47], off
	v_lshl_add_u64 v[48:49], v[16:17], 0, s[12:13]
	s_lshl_b64 s[14:15], s[2:3], 2
	global_load_dwordx2 v[36:37], v[48:49], off
	global_load_dwordx4 v[2:5], v1, s[16:17]
	v_lshl_add_u64 v[50:51], v[18:19], 0, s[14:15]
	global_load_dwordx4 v[30:33], v[50:51], off
	s_lshl_b64 s[18:19], s[18:19], 12
	v_lshl_add_u64 v[52:53], v[20:21], 0, s[18:19]
	v_lshl_add_u64 v[58:59], v[22:23], 0, s[14:15]
	s_add_u32 s4, s4, s6
	s_addc_u32 s5, s5, s7
	s_add_u32 s8, s8, s10
	s_addc_u32 s9, s9, s11
	s_cmpk_lt_i32 s4, 0x1800
	s_waitcnt vmcnt(3)
	v_lshlrev_b32_e32 v38, 16, v34
	v_and_b32_e32 v39, 0xffff0000, v34
	s_waitcnt vmcnt(2)
	v_lshlrev_b32_e32 v40, 16, v36
	v_and_b32_e32 v41, 0xffff0000, v36
	v_lshlrev_b32_e32 v34, 16, v35
	v_and_b32_e32 v35, 0xffff0000, v35
	v_lshlrev_b32_e32 v36, 16, v37
	v_and_b32_e32 v37, 0xffff0000, v37
	v_pk_add_f32 v[38:39], v[38:39], v[40:41]
	v_pk_add_f32 v[34:35], v[34:35], v[36:37]
	s_waitcnt vmcnt(0)
	v_pk_fma_f32 v[2:3], v[30:31], v[38:39], v[2:3]
	v_pk_fma_f32 v[4:5], v[32:33], v[34:35], v[4:5]
	global_store_dwordx4 v[52:53], v[2:5], off sc1
	global_load_dwordx2 v[38:39], v[46:47], off offset:512
	global_load_dwordx2 v[40:41], v[48:49], off offset:512
	global_load_dwordx4 v[30:33], v1, s[16:17] offset:1024
	global_load_dwordx4 v[34:37], v[50:51], off offset:1024
	v_mov_b32_e32 v60, v3
	v_mov_b32_e32 v62, v4
	v_mov_b32_e32 v64, v5
	s_waitcnt vmcnt(3)
	v_lshlrev_b32_e32 v42, 16, v38
	v_and_b32_e32 v43, 0xffff0000, v38
	s_waitcnt vmcnt(2)
	v_lshlrev_b32_e32 v44, 16, v40
	v_and_b32_e32 v45, 0xffff0000, v40
	v_lshlrev_b32_e32 v38, 16, v39
	v_and_b32_e32 v39, 0xffff0000, v39
	v_lshlrev_b32_e32 v40, 16, v41
	v_and_b32_e32 v41, 0xffff0000, v41
	v_pk_add_f32 v[42:43], v[42:43], v[44:45]
	v_pk_add_f32 v[38:39], v[38:39], v[40:41]
	s_waitcnt vmcnt(0)
	v_pk_fma_f32 v[30:31], v[34:35], v[42:43], v[30:31]
	v_pk_fma_f32 v[32:33], v[36:37], v[38:39], v[32:33]
	global_store_dwordx4 v[52:53], v[30:33], off offset:1024 sc1
	global_load_dwordx2 v[42:43], v[46:47], off offset:1024
	global_load_dwordx2 v[44:45], v[48:49], off offset:1024
	global_load_dwordx4 v[34:37], v1, s[16:17] offset:2048
	global_load_dwordx4 v[38:41], v[50:51], off offset:2048
	v_mov_b32_e32 v61, v31
	v_pk_mul_f32 v[60:61], v[60:61], v[60:61]
	v_mov_b32_e32 v63, v32
	v_mov_b32_e32 v65, v33
	s_waitcnt vmcnt(3)
	v_lshlrev_b32_e32 v54, 16, v42
	v_and_b32_e32 v55, 0xffff0000, v42
	s_waitcnt vmcnt(2)
	v_lshlrev_b32_e32 v56, 16, v44
	v_and_b32_e32 v57, 0xffff0000, v44
	v_lshlrev_b32_e32 v42, 16, v43
	v_and_b32_e32 v43, 0xffff0000, v43
	v_lshlrev_b32_e32 v44, 16, v45
	v_and_b32_e32 v45, 0xffff0000, v45
	v_pk_add_f32 v[54:55], v[54:55], v[56:57]
	v_pk_add_f32 v[42:43], v[42:43], v[44:45]
	s_waitcnt vmcnt(0)
	v_pk_fma_f32 v[34:35], v[38:39], v[54:55], v[34:35]
	v_pk_fma_f32 v[36:37], v[40:41], v[42:43], v[36:37]
	global_store_dwordx4 v[52:53], v[34:37], off offset:2048 sc1
	global_load_dwordx2 v[54:55], v[46:47], off offset:1536
	global_load_dwordx2 v[56:57], v[48:49], off offset:1536
	global_load_dwordx4 v[38:41], v1, s[16:17] offset:3072
	global_load_dwordx4 v[42:45], v[50:51], off offset:3072
	s_waitcnt vmcnt(3)
	v_lshlrev_b32_e32 v46, 16, v54
	v_and_b32_e32 v47, 0xffff0000, v54
	s_waitcnt vmcnt(2)
	v_lshlrev_b32_e32 v48, 16, v56
	v_and_b32_e32 v49, 0xffff0000, v56
	v_lshlrev_b32_e32 v50, 16, v55
	v_and_b32_e32 v51, 0xffff0000, v55
	v_lshlrev_b32_e32 v54, 16, v57
	v_and_b32_e32 v55, 0xffff0000, v57
	v_pk_add_f32 v[46:47], v[46:47], v[48:49]
	v_pk_add_f32 v[48:49], v[50:51], v[54:55]
	s_waitcnt vmcnt(0)
	v_pk_fma_f32 v[38:39], v[42:43], v[46:47], v[38:39]
	v_pk_fma_f32 v[40:41], v[44:45], v[48:49], v[40:41]
	global_store_dwordx4 v[52:53], v[38:41], off offset:3072 sc1
	global_load_dwordx4 v[42:45], v[6:7], off
	global_load_dwordx4 v[46:49], v[58:59], off
	v_lshl_add_u64 v[54:55], v[24:25], 0, s[14:15]
	global_load_dwordx4 v[50:53], v[54:55], off
	v_mov_b32_e32 v56, v2
	v_mov_b32_e32 v57, v30
	v_pk_fma_f32 v[56:57], v[56:57], v[56:57], v[60:61]
	v_mov_b32_e32 v60, v36
	v_pk_fma_f32 v[56:57], v[62:63], v[62:63], v[56:57]
	v_mov_b32_e32 v62, v34
	v_pk_fma_f32 v[56:57], v[64:65], v[64:65], v[56:57]
	v_mov_b32_e32 v64, v35
	v_mov_b32_e32 v65, v39
	v_mov_b32_e32 v63, v38
	v_pk_mul_f32 v[64:65], v[64:65], v[64:65]
	v_mov_b32_e32 v61, v40
	v_pk_fma_f32 v[62:63], v[62:63], v[62:63], v[64:65]
	v_add_f32_e32 v29, v56, v57
	v_mov_b32_e32 v56, v37
	v_mov_b32_e32 v57, v41
	v_pk_fma_f32 v[60:61], v[60:61], v[60:61], v[62:63]
	s_nop 0
	v_pk_fma_f32 v[56:57], v[56:57], v[56:57], v[60:61]
	s_nop 0
	v_add_f32_e32 v29, v29, v56
	v_add_f32_e32 v29, v29, v57
	s_nop 1
	v_add_f32_dpp v29, v29, v29 quad_perm:[1,0,3,2] row_mask:0xf bank_mask:0xf bound_ctrl:1
	s_nop 1
	v_add_f32_dpp v29, v29, v29 quad_perm:[2,3,0,1] row_mask:0xf bank_mask:0xf bound_ctrl:1
	s_nop 1
	v_add_f32_dpp v29, v29, v29 row_half_mirror row_mask:0xf bank_mask:0xf bound_ctrl:1
	s_nop 1
	v_add_f32_dpp v29, v29, v29 row_mirror row_mask:0xf bank_mask:0xf bound_ctrl:1
	s_nop 0
	v_readlane_b32 s2, v29, 16
	v_readlane_b32 s16, v29, 48
	v_readlane_b32 s14, v29, 0
	v_readlane_b32 s15, v29, 32
	v_mov_b32_e32 v56, s2
	v_mov_b32_e32 v57, s16
	v_pk_add_f32 v[56:57], s[14:15], v[56:57]
	s_nop 0
	v_add_f32_e32 v29, v56, v57
	v_fmamk_f32 v29, v29, 0x3a800000, v28
	v_mul_f32_e32 v56, 0x4b800000, v29
	v_cmp_gt_f32_e32 vcc, s22, v29
	s_nop 1
	v_cndmask_b32_e32 v29, v29, v56, vcc
	v_rsq_f32_e32 v29, v29
	v_lshl_add_u64 v[56:57], v[26:27], 0, s[12:13]
	v_mul_f32_e32 v60, 0x45800000, v29
	v_cndmask_b32_e32 v60, v29, v60, vcc
	v_pk_mul_f32 v[2:3], v[2:3], v[60:61] op_sel_hi:[1,0]
	v_pk_mul_f32 v[4:5], v[4:5], v[60:61] op_sel_hi:[1,0]
	v_pk_mul_f32 v[30:31], v[30:31], v[60:61] op_sel_hi:[1,0]
	v_pk_mul_f32 v[32:33], v[32:33], v[60:61] op_sel_hi:[1,0]
	v_pk_mul_f32 v[34:35], v[34:35], v[60:61] op_sel_hi:[1,0]
	v_pk_mul_f32 v[36:37], v[36:37], v[60:61] op_sel_hi:[1,0]
	v_pk_mul_f32 v[38:39], v[38:39], v[60:61] op_sel_hi:[1,0]
	v_pk_mul_f32 v[40:41], v[40:41], v[60:61] op_sel_hi:[1,0]
	s_waitcnt vmcnt(2)
	v_pk_mul_f32 v[2:3], v[42:43], v[2:3]
	s_waitcnt vmcnt(1)
	v_pk_add_f32 v[42:43], v[46:47], 1.0 op_sel_hi:[1,0]
	v_pk_mul_f32 v[4:5], v[44:45], v[4:5]
	v_pk_add_f32 v[44:45], v[48:49], 1.0 op_sel_hi:[1,0]
	s_waitcnt vmcnt(0)
	v_pk_fma_f32 v[2:3], v[42:43], v[2:3], v[50:51]
	v_pk_fma_f32 v[4:5], v[44:45], v[4:5], v[52:53]
	v_cvt_pk_bf16_f32 v2, v2, v3
	v_cvt_pk_bf16_f32 v3, v4, v5
	global_store_dwordx2 v[56:57], v[2:3], off
	global_load_dwordx4 v[2:5], v[8:9], off
	s_nop 0
	global_load_dwordx4 v[42:45], v[58:59], off offset:1024
	global_load_dwordx4 v[46:49], v[54:55], off offset:1024
	s_waitcnt vmcnt(2)
	v_pk_mul_f32 v[2:3], v[2:3], v[30:31]
	s_waitcnt vmcnt(1)
	v_pk_add_f32 v[30:31], v[42:43], 1.0 op_sel_hi:[1,0]
	v_pk_mul_f32 v[4:5], v[4:5], v[32:33]
	v_pk_add_f32 v[32:33], v[44:45], 1.0 op_sel_hi:[1,0]
	s_waitcnt vmcnt(0)
	v_pk_fma_f32 v[2:3], v[30:31], v[2:3], v[46:47]
	v_pk_fma_f32 v[4:5], v[32:33], v[4:5], v[48:49]
	v_cvt_pk_bf16_f32 v2, v2, v3
	v_cvt_pk_bf16_f32 v3, v4, v5
	global_store_dwordx2 v[56:57], v[2:3], off offset:512
	global_load_dwordx4 v[2:5], v[10:11], off
	s_nop 0
	global_load_dwordx4 v[30:33], v[58:59], off offset:2048
	global_load_dwordx4 v[42:45], v[54:55], off offset:2048
	s_waitcnt vmcnt(2)
	v_pk_mul_f32 v[2:3], v[2:3], v[34:35]
	s_waitcnt vmcnt(1)
	v_pk_add_f32 v[30:31], v[30:31], 1.0 op_sel_hi:[1,0]
	v_pk_mul_f32 v[4:5], v[4:5], v[36:37]
	v_pk_add_f32 v[32:33], v[32:33], 1.0 op_sel_hi:[1,0]
	s_waitcnt vmcnt(0)
	v_pk_fma_f32 v[2:3], v[2:3], v[30:31], v[42:43]
	v_pk_fma_f32 v[4:5], v[4:5], v[32:33], v[44:45]
	v_cvt_pk_bf16_f32 v2, v2, v3
	v_cvt_pk_bf16_f32 v3, v4, v5
	global_store_dwordx2 v[56:57], v[2:3], off offset:1024
	global_load_dwordx4 v[2:5], v[12:13], off
	s_nop 0
	global_load_dwordx4 v[30:33], v[58:59], off offset:3072
	global_load_dwordx4 v[34:37], v[54:55], off offset:3072
	s_waitcnt vmcnt(2)
	v_pk_mul_f32 v[2:3], v[38:39], v[2:3]
	s_waitcnt vmcnt(1)
	v_pk_add_f32 v[30:31], v[30:31], 1.0 op_sel_hi:[1,0]
	v_pk_mul_f32 v[4:5], v[40:41], v[4:5]
	v_pk_add_f32 v[32:33], v[32:33], 1.0 op_sel_hi:[1,0]
	s_waitcnt vmcnt(0)
	v_pk_fma_f32 v[2:3], v[2:3], v[30:31], v[34:35]
	v_pk_fma_f32 v[4:5], v[4:5], v[32:33], v[36:37]
	v_cvt_pk_bf16_f32 v2, v2, v3
	v_cvt_pk_bf16_f32 v3, v4, v5
	global_store_dwordx2 v[56:57], v[2:3], off offset:1536
	s_cbranch_scc0 .LBB0_2462

.LBB0_3317:
	v_add_u32_e32 v3, s37, v153
	v_cmp_gt_u32_e32 vcc, s66, v3
	v_mov_b32_e32 v86, 0
	v_mov_b32_e32 v90, 0
	v_mov_b32_e32 v91, 0
	v_mov_b32_e32 v92, 0
	v_mov_b32_e32 v93, 0
	s_and_saveexec_b64 s[6:7], vcc
	ds_read_b128 v[90:93], v131
	s_or_b64 exec, exec, s[6:7]
	v_mov_b32_e32 v87, 0
	v_mov_b32_e32 v88, 0
	v_mov_b32_e32 v89, 0
	s_and_saveexec_b64 s[6:7], vcc
	ds_read_b128 v[86:89], v131 offset:256
	s_or_b64 exec, exec, s[6:7]
	v_cmp_le_u32_e32 vcc, s36, v3
	v_cmp_ge_u32_e64 s[6:7], s29, v3
	s_and_b64 s[34:35], vcc, s[6:7]
	s_waitcnt lgkmcnt(0)
	v_and_b32_e32 v127, 0xffff0000, v78
	v_lshlrev_b32_e32 v126, 16, v78
	s_waitcnt lgkmcnt(0)
	v_and_b32_e32 v107, 0xffff0000, v90
	v_lshlrev_b32_e32 v106, 16, v90
	v_and_b32_e32 v125, 0xffff0000, v82
	v_lshlrev_b32_e32 v124, 16, v82
	v_and_b32_e32 v103, 0xffff0000, v86
	v_lshlrev_b32_e32 v102, 16, v86
	v_and_b32_e32 v123, 0xffff0000, v79
	v_lshlrev_b32_e32 v122, 16, v79
	v_and_b32_e32 v101, 0xffff0000, v91
	v_lshlrev_b32_e32 v100, 16, v91
	v_and_b32_e32 v121, 0xffff0000, v83
	v_lshlrev_b32_e32 v120, 16, v83
	v_and_b32_e32 v97, 0xffff0000, v87
	v_lshlrev_b32_e32 v96, 16, v87
	v_and_b32_e32 v119, 0xffff0000, v80
	v_lshlrev_b32_e32 v118, 16, v80
	v_and_b32_e32 v91, 0xffff0000, v92
	v_lshlrev_b32_e32 v90, 16, v92
	v_and_b32_e32 v117, 0xffff0000, v84
	v_lshlrev_b32_e32 v116, 16, v84
	v_and_b32_e32 v83, 0xffff0000, v88
	v_lshlrev_b32_e32 v82, 16, v88
	v_and_b32_e32 v115, 0xffff0000, v81
	v_lshlrev_b32_e32 v114, 16, v81
	v_and_b32_e32 v79, 0xffff0000, v93
	v_lshlrev_b32_e32 v78, 16, v93
	v_and_b32_e32 v81, 0xffff0000, v85
	v_lshlrev_b32_e32 v80, 16, v85
	v_and_b32_e32 v5, 0xffff0000, v89
	v_lshlrev_b32_e32 v4, 16, v89
	s_and_saveexec_b64 s[6:7], s[34:35]
	s_cbranch_execz .LBB0_3323
	v_and_b32_e32 v85, 0xffff0000, v74
	v_lshlrev_b32_e32 v84, 16, v74
	v_pk_mul_f32 v[84:85], v[10:11], v[84:85]
	v_and_b32_e32 v87, 0xffff0000, v70
	v_pk_fma_f32 v[84:85], v[26:27], v[126:127], v[84:85]
	v_lshlrev_b32_e32 v86, 16, v70
	v_pk_fma_f32 v[84:85], v[42:43], v[106:107], v[84:85]
	v_and_b32_e32 v93, 0xffff0000, v75
	v_pk_add_f32 v[84:85], v[58:59], v[84:85]
	v_lshlrev_b32_e32 v92, 16, v75
	v_mul_f32_e32 v74, 0xbfb8aa3b, v84
	v_exp_f32_e32 v74, v74
	v_pk_mul_f32 v[86:87], v[14:15], v[86:87]
	v_add_f32_e32 v70, 1.0, v74
	v_rcp_f32_e32 v88, v70
	v_mul_f32_e32 v70, 0xbfb8aa3b, v85
	v_exp_f32_e32 v70, v70
	v_pk_mul_f32 v[74:75], v[12:13], v[92:93]
	v_pk_fma_f32 v[86:87], v[30:31], v[124:125], v[86:87]
	v_pk_fma_f32 v[74:75], v[28:29], v[122:123], v[74:75]
	v_add_f32_e32 v70, 1.0, v70
	v_rcp_f32_e32 v89, v70
	v_pk_fma_f32 v[86:87], v[46:47], v[102:103], v[86:87]
	v_pk_fma_f32 v[74:75], v[44:45], v[100:101], v[74:75]
	v_pk_add_f32 v[86:87], v[62:63], v[86:87]
	v_pk_add_f32 v[74:75], v[60:61], v[74:75]
	v_pk_mul_f32 v[84:85], v[84:85], v[88:89]
	v_mul_f32_e32 v70, 0xbfb8aa3b, v74
	v_pk_mul_f32 v[84:85], v[84:85], v[86:87]
	v_and_b32_e32 v87, 0xffff0000, v71
	v_lshlrev_b32_e32 v86, 16, v71
	v_mul_f32_e32 v71, 0xbfb8aa3b, v75
	v_exp_f32_e32 v70, v70
	v_exp_f32_e32 v71, v71
	v_and_b32_e32 v89, 0xffff0000, v76
	v_lshlrev_b32_e32 v88, 16, v76
	v_add_f32_e32 v70, 1.0, v70
	v_add_f32_e32 v71, 1.0, v71
	v_rcp_f32_e32 v70, v70
	v_rcp_f32_e32 v71, v71
	v_pk_mul_f32 v[86:87], v[16:17], v[86:87]
	v_pk_mul_f32 v[88:89], v[6:7], v[88:89]
	v_pk_fma_f32 v[86:87], v[32:33], v[120:121], v[86:87]
	v_pk_fma_f32 v[88:89], v[22:23], v[118:119], v[88:89]
	v_pk_fma_f32 v[86:87], v[48:49], v[96:97], v[86:87]
	v_pk_fma_f32 v[88:89], v[38:39], v[90:91], v[88:89]
	v_pk_add_f32 v[86:87], v[64:65], v[86:87]
	v_pk_add_f32 v[88:89], v[54:55], v[88:89]
	v_pk_mul_f32 v[70:71], v[74:75], v[70:71]
	v_mul_f32_e32 v76, 0xbfb8aa3b, v88
	v_pk_mul_f32 v[74:75], v[70:71], v[86:87]
	v_mul_f32_e32 v71, 0xbfb8aa3b, v89
	v_exp_f32_e32 v76, v76
	v_exp_f32_e32 v71, v71
	v_and_b32_e32 v87, 0xffff0000, v72
	v_lshlrev_b32_e32 v86, 16, v72
	v_add_f32_e32 v70, 1.0, v76
	v_add_f32_e32 v71, 1.0, v71
	v_rcp_f32_e32 v70, v70
	v_rcp_f32_e32 v71, v71
	v_and_b32_e32 v93, 0xffff0000, v77
	v_lshlrev_b32_e32 v92, 16, v77
	v_pk_mul_f32 v[86:87], v[18:19], v[86:87]
	v_pk_mul_f32 v[76:77], v[8:9], v[92:93]
	v_pk_fma_f32 v[86:87], v[34:35], v[116:117], v[86:87]
	v_pk_fma_f32 v[76:77], v[24:25], v[114:115], v[76:77]
	v_pk_fma_f32 v[86:87], v[50:51], v[82:83], v[86:87]
	v_pk_fma_f32 v[76:77], v[40:41], v[78:79], v[76:77]
	v_pk_add_f32 v[86:87], v[66:67], v[86:87]
	v_pk_add_f32 v[76:77], v[56:57], v[76:77]
	v_pk_mul_f32 v[70:71], v[88:89], v[70:71]
	v_mul_f32_e32 v72, 0xbfb8aa3b, v76
	v_pk_mul_f32 v[86:87], v[70:71], v[86:87]
	v_mul_f32_e32 v71, 0xbfb8aa3b, v77
	v_exp_f32_e32 v72, v72
	v_exp_f32_e32 v71, v71
	v_and_b32_e32 v89, 0xffff0000, v73
	v_lshlrev_b32_e32 v88, 16, v73
	v_add_f32_e32 v70, 1.0, v72
	v_add_f32_e32 v71, 1.0, v71
	v_rcp_f32_e32 v70, v70
	v_rcp_f32_e32 v71, v71
	v_pk_mul_f32 v[72:73], v[20:21], v[88:89]
	v_pk_mul_f32 v[70:71], v[76:77], v[70:71]
	v_pk_fma_f32 v[72:73], v[36:37], v[80:81], v[72:73]
	s_nop 0
	v_pk_fma_f32 v[72:73], v[52:53], v[4:5], v[72:73]
	s_nop 0
	v_pk_add_f32 v[72:73], v[68:69], v[72:73]
	s_nop 0
	v_pk_mul_f32 v[76:77], v[70:71], v[72:73]
	v_cvt_pk_bf16_f32 v71, v74, v75
	v_add_u32_e32 v74, s37, v130
	v_cvt_pk_bf16_f32 v70, v84, v85
	v_cvt_pk_bf16_f32 v72, v86, v87
	v_cvt_pk_bf16_f32 v73, v76, v77
	v_mad_i64_i32 v[74:75], s[34:35], v74, s67, v[94:95]
	global_store_dwordx4 v[74:75], v[70:73], off sc1
.LBB0_3323:
	s_or_b64 exec, exec, s[6:7]
	v_add_u32_e32 v84, 1, v3
	v_cmp_gt_u32_e32 vcc, s66, v84
	v_mov_b32_e32 v70, 0
	v_mov_b32_e32 v74, 0
	v_mov_b32_e32 v75, 0
	v_mov_b32_e32 v76, 0
	v_mov_b32_e32 v77, 0
	s_and_saveexec_b64 s[6:7], vcc
	ds_read_b128 v[74:77], v131 offset:528
	s_or_b64 exec, exec, s[6:7]
	v_mov_b32_e32 v71, 0
	v_mov_b32_e32 v72, 0
	v_mov_b32_e32 v73, 0
	s_and_saveexec_b64 s[6:7], vcc
	ds_read_b128 v[70:73], v131 offset:784
	s_or_b64 exec, exec, s[6:7]
	v_cmp_le_u32_e32 vcc, s36, v84
	v_cmp_ge_u32_e64 s[6:7], s29, v84
	s_and_b64 s[34:35], vcc, s[6:7]
	s_waitcnt lgkmcnt(0)
	v_and_b32_e32 v113, 0xffff0000, v74
	v_lshlrev_b32_e32 v112, 16, v74
	v_and_b32_e32 v111, 0xffff0000, v70
	v_lshlrev_b32_e32 v110, 16, v70
	v_and_b32_e32 v109, 0xffff0000, v75
	v_lshlrev_b32_e32 v108, 16, v75
	v_and_b32_e32 v105, 0xffff0000, v71
	v_lshlrev_b32_e32 v104, 16, v71
	v_and_b32_e32 v99, 0xffff0000, v76
	v_lshlrev_b32_e32 v98, 16, v76
	v_and_b32_e32 v93, 0xffff0000, v72
	v_lshlrev_b32_e32 v92, 16, v72
	v_and_b32_e32 v89, 0xffff0000, v77
	v_lshlrev_b32_e32 v88, 16, v77
	v_and_b32_e32 v87, 0xffff0000, v73
	v_lshlrev_b32_e32 v86, 16, v73
	s_and_saveexec_b64 s[6:7], s[34:35]
	s_cbranch_execz .LBB0_3329
	v_pk_mul_f32 v[70:71], v[26:27], v[106:107]
	s_nop 0
	v_pk_fma_f32 v[70:71], v[10:11], v[126:127], v[70:71]
	s_nop 0
	v_pk_fma_f32 v[70:71], v[42:43], v[112:113], v[70:71]
	s_nop 0
	v_pk_add_f32 v[70:71], v[58:59], v[70:71]
	s_nop 0
	v_mul_f32_e32 v72, 0xbfb8aa3b, v70
	v_exp_f32_e32 v74, v72
	v_mul_f32_e32 v72, 0xbfb8aa3b, v71
	v_exp_f32_e32 v75, v72
	v_pk_mul_f32 v[72:73], v[30:31], v[102:103]
	v_add_f32_e32 v74, 1.0, v74
	v_rcp_f32_e32 v74, v74
	v_add_f32_e32 v75, 1.0, v75
	v_rcp_f32_e32 v75, v75
	v_pk_fma_f32 v[72:73], v[14:15], v[124:125], v[72:73]
	v_pk_mul_f32 v[70:71], v[70:71], v[74:75]
	v_pk_mul_f32 v[74:75], v[28:29], v[100:101]
	v_pk_fma_f32 v[72:73], v[46:47], v[110:111], v[72:73]
	v_pk_fma_f32 v[74:75], v[12:13], v[122:123], v[74:75]
	v_pk_add_f32 v[72:73], v[62:63], v[72:73]
	v_pk_fma_f32 v[74:75], v[44:45], v[108:109], v[74:75]
	v_pk_mul_f32 v[70:71], v[70:71], v[72:73]
	v_pk_add_f32 v[74:75], v[60:61], v[74:75]
	v_cvt_pk_bf16_f32 v70, v70, v71
	v_mul_f32_e32 v76, 0xbfb8aa3b, v74
	v_mul_f32_e32 v72, 0xbfb8aa3b, v75
	v_exp_f32_e32 v76, v76
	v_exp_f32_e32 v73, v72
	v_add_f32_e32 v72, 1.0, v76
	v_add_f32_e32 v73, 1.0, v73
	v_rcp_f32_e32 v72, v72
	v_rcp_f32_e32 v73, v73
	v_pk_mul_f32 v[76:77], v[32:33], v[96:97]
	v_pk_mul_f32 v[72:73], v[74:75], v[72:73]
	v_pk_mul_f32 v[74:75], v[22:23], v[90:91]
	v_pk_fma_f32 v[76:77], v[16:17], v[120:121], v[76:77]
	v_pk_fma_f32 v[74:75], v[6:7], v[118:119], v[74:75]
	v_pk_fma_f32 v[76:77], v[48:49], v[104:105], v[76:77]
	v_pk_fma_f32 v[74:75], v[38:39], v[98:99], v[74:75]
	v_pk_add_f32 v[76:77], v[64:65], v[76:77]
	v_pk_add_f32 v[74:75], v[54:55], v[74:75]
	v_pk_mul_f32 v[72:73], v[72:73], v[76:77]
	v_mul_f32_e32 v84, 0xbfb8aa3b, v74
	v_mul_f32_e32 v76, 0xbfb8aa3b, v75
	v_exp_f32_e32 v84, v84
	v_exp_f32_e32 v77, v76
	v_cvt_pk_bf16_f32 v71, v72, v73
	v_add_f32_e32 v76, 1.0, v84
	v_add_f32_e32 v77, 1.0, v77
	v_rcp_f32_e32 v76, v76
	v_rcp_f32_e32 v77, v77
	v_pk_mul_f32 v[84:85], v[34:35], v[82:83]
	v_pk_mul_f32 v[74:75], v[74:75], v[76:77]
	v_pk_mul_f32 v[76:77], v[24:25], v[78:79]
	v_pk_fma_f32 v[84:85], v[18:19], v[116:117], v[84:85]
	v_pk_fma_f32 v[76:77], v[8:9], v[114:115], v[76:77]
	v_pk_fma_f32 v[84:85], v[50:51], v[92:93], v[84:85]
	v_pk_fma_f32 v[76:77], v[40:41], v[88:89], v[76:77]
	v_pk_add_f32 v[84:85], v[66:67], v[84:85]
	v_pk_add_f32 v[76:77], v[56:57], v[76:77]
	v_pk_mul_f32 v[74:75], v[74:75], v[84:85]
	v_mul_f32_e32 v114, 0xbfb8aa3b, v76
	v_mul_f32_e32 v84, 0xbfb8aa3b, v77
	v_exp_f32_e32 v114, v114
	v_exp_f32_e32 v85, v84
	v_cvt_pk_bf16_f32 v72, v74, v75
	v_add3_u32 v74, v130, s37, 1
	v_add_f32_e32 v84, 1.0, v114
	v_add_f32_e32 v85, 1.0, v85
	v_rcp_f32_e32 v84, v84
	v_rcp_f32_e32 v85, v85
	v_pk_mul_f32 v[114:115], v[36:37], v[4:5]
	v_mad_i64_i32 v[74:75], s[34:35], v74, s67, v[94:95]
	v_pk_fma_f32 v[80:81], v[20:21], v[80:81], v[114:115]
	v_pk_mul_f32 v[76:77], v[76:77], v[84:85]
	v_pk_fma_f32 v[80:81], v[52:53], v[86:87], v[80:81]
	s_nop 0
	v_pk_add_f32 v[80:81], v[68:69], v[80:81]
	s_nop 0
	v_pk_mul_f32 v[76:77], v[76:77], v[80:81]
	s_nop 0
	v_cvt_pk_bf16_f32 v73, v76, v77
	global_store_dwordx4 v[74:75], v[70:73], off sc1
.LBB0_3329:
	s_or_b64 exec, exec, s[6:7]
	v_add_u32_e32 v80, 2, v3
	v_cmp_gt_u32_e32 vcc, s66, v80
	v_mov_b32_e32 v70, 0
	v_mov_b32_e32 v74, 0
	v_mov_b32_e32 v75, 0
	v_mov_b32_e32 v76, 0
	v_mov_b32_e32 v77, 0
	s_and_saveexec_b64 s[6:7], vcc
	ds_read_b128 v[74:77], v131 offset:1056
	s_or_b64 exec, exec, s[6:7]
	v_mov_b32_e32 v71, 0
	v_mov_b32_e32 v72, 0
	v_mov_b32_e32 v73, 0
	s_and_saveexec_b64 s[6:7], vcc
	ds_read_b128 v[70:73], v131 offset:1312
	s_or_b64 exec, exec, s[6:7]
	v_cmp_le_u32_e32 vcc, s36, v80
	v_cmp_ge_u32_e64 s[6:7], s29, v80
	s_and_b64 s[34:35], vcc, s[6:7]
	s_waitcnt lgkmcnt(0)
	v_and_b32_e32 v129, 0xffff0000, v74
	v_lshlrev_b32_e32 v128, 16, v74
	v_and_b32_e32 v127, 0xffff0000, v70
	v_lshlrev_b32_e32 v126, 16, v70
	v_and_b32_e32 v125, 0xffff0000, v75
	v_lshlrev_b32_e32 v124, 16, v75
	v_and_b32_e32 v123, 0xffff0000, v71
	v_lshlrev_b32_e32 v122, 16, v71
	v_and_b32_e32 v121, 0xffff0000, v76
	v_lshlrev_b32_e32 v120, 16, v76
	v_and_b32_e32 v119, 0xffff0000, v72
	v_lshlrev_b32_e32 v118, 16, v72
	v_and_b32_e32 v117, 0xffff0000, v77
	v_lshlrev_b32_e32 v116, 16, v77
	v_and_b32_e32 v115, 0xffff0000, v73
	v_lshlrev_b32_e32 v114, 16, v73
	s_and_saveexec_b64 s[6:7], s[34:35]
	s_cbranch_execz .LBB0_3335
	v_pk_mul_f32 v[80:81], v[26:27], v[112:113]
	s_nop 0
	v_pk_fma_f32 v[80:81], v[10:11], v[106:107], v[80:81]
	s_nop 0
	v_pk_fma_f32 v[80:81], v[42:43], v[128:129], v[80:81]
	s_nop 0
	v_pk_add_f32 v[80:81], v[58:59], v[80:81]
	s_nop 0
	v_mul_f32_e32 v84, 0xbfb8aa3b, v80
	v_exp_f32_e32 v106, v84
	v_mul_f32_e32 v84, 0xbfb8aa3b, v81
	v_exp_f32_e32 v107, v84
	v_pk_mul_f32 v[84:85], v[30:31], v[110:111]
	v_add_f32_e32 v106, 1.0, v106
	v_rcp_f32_e32 v106, v106
	v_add_f32_e32 v107, 1.0, v107
	v_rcp_f32_e32 v107, v107
	v_pk_fma_f32 v[84:85], v[14:15], v[102:103], v[84:85]
	v_pk_mul_f32 v[102:103], v[28:29], v[108:109]
	v_pk_fma_f32 v[84:85], v[46:47], v[126:127], v[84:85]
	v_pk_fma_f32 v[100:101], v[12:13], v[100:101], v[102:103]
	v_pk_add_f32 v[84:85], v[62:63], v[84:85]
	v_pk_fma_f32 v[100:101], v[44:45], v[124:125], v[100:101]
	v_pk_mul_f32 v[80:81], v[80:81], v[106:107]
	v_pk_add_f32 v[100:101], v[60:61], v[100:101]
	v_pk_mul_f32 v[80:81], v[80:81], v[84:85]
	v_mul_f32_e32 v102, 0xbfb8aa3b, v100
	v_mul_f32_e32 v84, 0xbfb8aa3b, v101
	v_exp_f32_e32 v102, v102
	v_exp_f32_e32 v85, v84
	v_add_f32_e32 v84, 1.0, v102
	v_add_f32_e32 v85, 1.0, v85
	v_rcp_f32_e32 v84, v84
	v_rcp_f32_e32 v85, v85
	v_pk_mul_f32 v[102:103], v[32:33], v[104:105]
	v_pk_mul_f32 v[84:85], v[100:101], v[84:85]
	v_pk_mul_f32 v[100:101], v[22:23], v[98:99]
	v_pk_fma_f32 v[96:97], v[16:17], v[96:97], v[102:103]
	v_pk_fma_f32 v[90:91], v[6:7], v[90:91], v[100:101]
	v_pk_fma_f32 v[96:97], v[48:49], v[122:123], v[96:97]
	v_pk_fma_f32 v[90:91], v[38:39], v[120:121], v[90:91]
	v_pk_add_f32 v[96:97], v[64:65], v[96:97]
	v_pk_add_f32 v[90:91], v[54:55], v[90:91]
	v_pk_mul_f32 v[84:85], v[84:85], v[96:97]
	v_mul_f32_e32 v100, 0xbfb8aa3b, v90
	v_mul_f32_e32 v96, 0xbfb8aa3b, v91
	v_exp_f32_e32 v100, v100
	v_exp_f32_e32 v97, v96
	v_add_f32_e32 v96, 1.0, v100
	v_add_f32_e32 v97, 1.0, v97
	v_rcp_f32_e32 v96, v96
	v_rcp_f32_e32 v97, v97
	v_pk_mul_f32 v[100:101], v[34:35], v[92:93]
	v_pk_mul_f32 v[90:91], v[90:91], v[96:97]
	v_pk_mul_f32 v[96:97], v[24:25], v[88:89]
	v_pk_fma_f32 v[82:83], v[18:19], v[82:83], v[100:101]
	v_pk_fma_f32 v[78:79], v[8:9], v[78:79], v[96:97]
	v_pk_fma_f32 v[82:83], v[50:51], v[118:119], v[82:83]
	v_pk_fma_f32 v[78:79], v[40:41], v[116:117], v[78:79]
	v_pk_add_f32 v[82:83], v[66:67], v[82:83]
	v_pk_add_f32 v[78:79], v[56:57], v[78:79]
	v_pk_mul_f32 v[82:83], v[90:91], v[82:83]
	v_mul_f32_e32 v96, 0xbfb8aa3b, v78
	v_mul_f32_e32 v90, 0xbfb8aa3b, v79
	v_exp_f32_e32 v96, v96
	v_exp_f32_e32 v91, v90
	v_add_f32_e32 v90, 1.0, v96
	v_add_f32_e32 v91, 1.0, v91
	v_rcp_f32_e32 v90, v90
	v_rcp_f32_e32 v91, v91
	v_pk_mul_f32 v[96:97], v[36:37], v[86:87]
	v_pk_mul_f32 v[78:79], v[78:79], v[90:91]
	v_pk_fma_f32 v[4:5], v[20:21], v[4:5], v[96:97]
	s_nop 0
	v_pk_fma_f32 v[4:5], v[52:53], v[114:115], v[4:5]
	s_nop 0
	v_pk_add_f32 v[4:5], v[68:69], v[4:5]
	s_nop 0
	v_pk_mul_f32 v[4:5], v[78:79], v[4:5]
	v_cvt_pk_bf16_f32 v78, v80, v81
	v_cvt_pk_bf16_f32 v81, v4, v5
	v_add3_u32 v4, v130, s37, 2
	v_cvt_pk_bf16_f32 v79, v84, v85
	v_cvt_pk_bf16_f32 v80, v82, v83
	v_mad_i64_i32 v[4:5], s[34:35], v4, s67, v[94:95]
	global_store_dwordx4 v[4:5], v[78:81], off sc1
.LBB0_3335:
	s_or_b64 exec, exec, s[6:7]
	v_mov_b32_e32 v4, v2
	v_mov_b32_e32 v5, v2
	v_add_u32_e32 v90, 3, v3
	v_mov_b32_e32 v3, v2
	v_mov_b64_e32 v[80:81], v[4:5]
	v_cmp_gt_u32_e32 vcc, s66, v90
	v_mov_b64_e32 v[78:79], v[2:3]
	s_and_saveexec_b64 s[6:7], vcc
	ds_read_b128 v[78:81], v131 offset:1584
	s_or_b64 exec, exec, s[6:7]
	v_mov_b64_e32 v[84:85], v[4:5]
	v_mov_b64_e32 v[82:83], v[2:3]
	s_and_saveexec_b64 s[6:7], vcc
	ds_read_b128 v[82:85], v131 offset:1840
	s_or_b64 exec, exec, s[6:7]
	v_cmp_le_u32_e32 vcc, s36, v90
	v_cmp_ge_u32_e64 s[6:7], s29, v90
	s_and_b64 s[6:7], vcc, s[6:7]
	s_and_saveexec_b64 s[34:35], s[6:7]
	s_xor_b64 s[6:7], exec, s[34:35]
	s_cbranch_execz .LBB0_3316
	v_pk_mul_f32 v[4:5], v[26:27], v[128:129]
	s_waitcnt lgkmcnt(0)
	v_and_b32_e32 v91, 0xffff0000, v78
	v_pk_fma_f32 v[4:5], v[10:11], v[112:113], v[4:5]
	v_lshlrev_b32_e32 v90, 16, v78
	v_pk_fma_f32 v[4:5], v[42:43], v[90:91], v[4:5]
	v_pk_mul_f32 v[90:91], v[30:31], v[126:127]
	v_pk_add_f32 v[4:5], v[58:59], v[4:5]
	v_pk_fma_f32 v[90:91], v[14:15], v[110:111], v[90:91]
	v_mul_f32_e32 v3, 0xbfb8aa3b, v4
	v_exp_f32_e32 v3, v3
	v_and_b32_e32 v101, 0xffff0000, v82
	v_lshlrev_b32_e32 v100, 16, v82
	v_pk_fma_f32 v[90:91], v[46:47], v[100:101], v[90:91]
	v_add_f32_e32 v3, 1.0, v3
	v_rcp_f32_e32 v96, v3
	v_mul_f32_e32 v3, 0xbfb8aa3b, v5
	v_exp_f32_e32 v3, v3
	v_pk_mul_f32 v[100:101], v[28:29], v[124:125]
	v_and_b32_e32 v103, 0xffff0000, v79
	v_pk_fma_f32 v[100:101], v[12:13], v[108:109], v[100:101]
	v_lshlrev_b32_e32 v102, 16, v79
	v_pk_fma_f32 v[100:101], v[44:45], v[102:103], v[100:101]
	v_add_f32_e32 v3, 1.0, v3
	v_pk_add_f32 v[100:101], v[60:61], v[100:101]
	v_rcp_f32_e32 v97, v3
	v_mul_f32_e32 v3, 0xbfb8aa3b, v100
	v_exp_f32_e32 v3, v3
	v_pk_add_f32 v[90:91], v[62:63], v[90:91]
	v_pk_mul_f32 v[4:5], v[4:5], v[96:97]
	v_pk_mul_f32 v[96:97], v[32:33], v[122:123]
	v_add_f32_e32 v3, 1.0, v3
	v_pk_mul_f32 v[4:5], v[4:5], v[90:91]
	v_rcp_f32_e32 v90, v3
	v_mul_f32_e32 v3, 0xbfb8aa3b, v101
	v_pk_fma_f32 v[96:97], v[16:17], v[104:105], v[96:97]
	v_exp_f32_e32 v3, v3
	v_and_b32_e32 v103, 0xffff0000, v83
	v_lshlrev_b32_e32 v102, 16, v83
	v_pk_fma_f32 v[96:97], v[48:49], v[102:103], v[96:97]
	v_pk_mul_f32 v[102:103], v[22:23], v[120:121]
	v_add_f32_e32 v3, 1.0, v3
	v_pk_fma_f32 v[98:99], v[6:7], v[98:99], v[102:103]
	v_and_b32_e32 v103, 0xffff0000, v80
	v_lshlrev_b32_e32 v102, 16, v80
	v_pk_fma_f32 v[98:99], v[38:39], v[102:103], v[98:99]
	v_rcp_f32_e32 v91, v3
	v_pk_add_f32 v[98:99], v[54:55], v[98:99]
	v_pk_add_f32 v[96:97], v[64:65], v[96:97]
	v_mul_f32_e32 v3, 0xbfb8aa3b, v98
	v_exp_f32_e32 v3, v3
	v_pk_mul_f32 v[90:91], v[100:101], v[90:91]
	v_pk_mul_f32 v[100:101], v[34:35], v[118:119]
	v_pk_mul_f32 v[90:91], v[90:91], v[96:97]
	v_add_f32_e32 v3, 1.0, v3
	v_rcp_f32_e32 v96, v3
	v_mul_f32_e32 v3, 0xbfb8aa3b, v99
	v_pk_fma_f32 v[92:93], v[18:19], v[92:93], v[100:101]
	v_exp_f32_e32 v3, v3
	v_and_b32_e32 v101, 0xffff0000, v84
	v_lshlrev_b32_e32 v100, 16, v84
	v_pk_fma_f32 v[92:93], v[50:51], v[100:101], v[92:93]
	v_pk_mul_f32 v[100:101], v[24:25], v[116:117]
	v_add_f32_e32 v3, 1.0, v3
	v_pk_fma_f32 v[88:89], v[8:9], v[88:89], v[100:101]
	v_and_b32_e32 v101, 0xffff0000, v81
	v_lshlrev_b32_e32 v100, 16, v81
	v_pk_fma_f32 v[88:89], v[40:41], v[100:101], v[88:89]
	v_rcp_f32_e32 v97, v3
	v_pk_add_f32 v[88:89], v[56:57], v[88:89]
	v_pk_add_f32 v[92:93], v[66:67], v[92:93]
	v_mul_f32_e32 v3, 0xbfb8aa3b, v88
	v_exp_f32_e32 v3, v3
	v_pk_mul_f32 v[96:97], v[98:99], v[96:97]
	v_pk_mul_f32 v[98:99], v[36:37], v[114:115]
	v_pk_mul_f32 v[92:93], v[96:97], v[92:93]
	v_add_f32_e32 v3, 1.0, v3
	v_rcp_f32_e32 v96, v3
	v_mul_f32_e32 v3, 0xbfb8aa3b, v89
	v_exp_f32_e32 v3, v3
	v_pk_fma_f32 v[86:87], v[20:21], v[86:87], v[98:99]
	v_and_b32_e32 v99, 0xffff0000, v85
	v_lshlrev_b32_e32 v98, 16, v85
	v_add_f32_e32 v3, 1.0, v3
	v_rcp_f32_e32 v97, v3
	v_pk_fma_f32 v[86:87], v[52:53], v[98:99], v[86:87]
	v_add3_u32 v3, v130, s37, 3
	v_pk_add_f32 v[86:87], v[68:69], v[86:87]
	v_pk_mul_f32 v[88:89], v[88:89], v[96:97]
	s_nop 0
	v_pk_mul_f32 v[96:97], v[88:89], v[86:87]
	v_cvt_pk_bf16_f32 v86, v4, v5
	v_cvt_pk_bf16_f32 v87, v90, v91
	v_cvt_pk_bf16_f32 v88, v92, v93
	v_cvt_pk_bf16_f32 v89, v96, v97
	v_mad_i64_i32 v[4:5], s[34:35], v3, s67, v[94:95]
	global_store_dwordx4 v[4:5], v[86:89], off sc1
	s_branch .LBB0_3316

.LBB0_3443:
	s_or_b64 exec, exec, s[2:3]
	ds_read_b128 v[86:89], v90 offset:1024
	ds_read_b128 v[82:85], v90 offset:1152
	s_movk_i32 s2, 0xff
	v_cmp_gt_u32_e32 vcc, s2, v151
	v_mov_b32_e32 v66, 0
	v_mov_b32_e32 v70, 0
	v_mov_b32_e32 v71, 0
	v_mov_b32_e32 v72, 0
	v_mov_b32_e32 v73, 0
	s_and_saveexec_b64 s[2:3], vcc
	ds_read_b128 v[70:73], v90 offset:1552
	s_or_b64 exec, exec, s[2:3]
	v_mov_b32_e32 v67, 0
	v_mov_b32_e32 v68, 0
	v_mov_b32_e32 v69, 0
	s_and_saveexec_b64 s[2:3], vcc
	ds_read_b128 v[66:69], v90 offset:1680
	s_or_b64 exec, exec, s[2:3]
	v_cmp_le_u32_e32 vcc, s9, v151
	v_cmp_ge_u32_e64 s[2:3], s5, v151
	v_lshl_add_u64 v[90:91], v[100:101], 1, s[12:13]
	s_and_b64 s[10:11], vcc, s[2:3]
	s_waitcnt lgkmcnt(0)
	v_lshlrev_b32_e32 v138, 16, v86
	v_lshlrev_b32_e32 v118, 16, v70
	v_lshlrev_b32_e32 v136, 16, v82
	v_lshlrev_b32_e32 v114, 16, v66
	v_lshlrev_b32_e32 v134, 16, v87
	v_lshlrev_b32_e32 v112, 16, v71
	v_lshlrev_b32_e32 v132, 16, v83
	v_lshlrev_b32_e32 v106, 16, v67
	v_lshlrev_b32_e32 v130, 16, v88
	v_lshlrev_b32_e32 v104, 16, v72
	v_lshlrev_b32_e32 v128, 16, v84
	v_lshlrev_b32_e32 v100, 16, v68
	v_lshlrev_b32_e32 v126, 16, v89
	v_lshlrev_b32_e32 v96, 16, v73
	v_lshlrev_b32_e32 v124, 16, v85
	v_lshlrev_b32_e32 v92, 16, v69
	s_and_saveexec_b64 s[2:3], s[10:11]
	s_cbranch_execz .LBB0_3449
	v_and_b32_e32 v139, 0xffff0000, v86
	v_and_b32_e32 v95, 0xffff0000, v78
	v_lshlrev_b32_e32 v94, 16, v78
	s_waitcnt vmcnt(0)
	v_pk_mul_f32 v[102:103], v[58:59], v[138:139]
	v_and_b32_e32 v119, 0xffff0000, v70
	v_pk_fma_f32 v[94:95], v[50:51], v[94:95], v[102:103]
	v_and_b32_e32 v137, 0xffff0000, v82
	v_pk_fma_f32 v[94:95], v[54:55], v[118:119], v[94:95]
	v_and_b32_e32 v103, 0xffff0000, v99
	v_pk_add_f32 v[94:95], v[62:63], v[94:95]
	v_lshlrev_b32_e32 v102, 16, v99
	v_mul_f32_e32 v74, 0xbfb8aa3b, v94
	v_exp_f32_e32 v74, v74
	v_pk_mul_f32 v[108:109], v[46:47], v[136:137]
	v_and_b32_e32 v135, 0xffff0000, v87
	v_pk_fma_f32 v[102:103], v[38:39], v[102:103], v[108:109]
	v_add_f32_e32 v74, 1.0, v74
	v_rcp_f32_e32 v98, v74
	v_mul_f32_e32 v74, 0xbfb8aa3b, v95
	v_exp_f32_e32 v74, v74
	v_and_b32_e32 v109, 0xffff0000, v79
	v_lshlrev_b32_e32 v108, 16, v79
	v_pk_mul_f32 v[78:79], v[60:61], v[134:135]
	v_add_f32_e32 v74, 1.0, v74
	v_rcp_f32_e32 v99, v74
	v_pk_fma_f32 v[78:79], v[52:53], v[108:109], v[78:79]
	v_and_b32_e32 v113, 0xffff0000, v71
	v_pk_fma_f32 v[78:79], v[56:57], v[112:113], v[78:79]
	v_pk_mul_f32 v[94:95], v[94:95], v[98:99]
	v_pk_add_f32 v[78:79], v[64:65], v[78:79]
	v_and_b32_e32 v99, 0xffff0000, v75
	v_mul_f32_e32 v74, 0xbfb8aa3b, v78
	v_lshlrev_b32_e32 v98, 16, v75
	v_mul_f32_e32 v75, 0xbfb8aa3b, v79
	v_exp_f32_e32 v74, v74
	v_exp_f32_e32 v75, v75
	v_and_b32_e32 v115, 0xffff0000, v66
	v_pk_fma_f32 v[102:103], v[42:43], v[114:115], v[102:103]
	v_add_f32_e32 v74, 1.0, v74
	v_pk_add_f32 v[102:103], v[34:35], v[102:103]
	v_and_b32_e32 v133, 0xffff0000, v83
	v_add_f32_e32 v75, 1.0, v75
	v_pk_mul_f32 v[94:95], v[94:95], v[102:103]
	v_rcp_f32_e32 v74, v74
	v_pk_mul_f32 v[102:103], v[48:49], v[132:133]
	v_rcp_f32_e32 v75, v75
	v_and_b32_e32 v131, 0xffff0000, v88
	v_pk_fma_f32 v[98:99], v[40:41], v[98:99], v[102:103]
	v_and_b32_e32 v103, 0xffff0000, v80
	v_lshlrev_b32_e32 v102, 16, v80
	v_pk_mul_f32 v[108:109], v[26:27], v[130:131]
	v_and_b32_e32 v107, 0xffff0000, v67
	v_pk_fma_f32 v[102:103], v[18:19], v[102:103], v[108:109]
	v_and_b32_e32 v105, 0xffff0000, v72
	v_pk_fma_f32 v[98:99], v[44:45], v[106:107], v[98:99]
	v_pk_fma_f32 v[102:103], v[22:23], v[104:105], v[102:103]
	v_pk_add_f32 v[98:99], v[36:37], v[98:99]
	v_pk_add_f32 v[102:103], v[30:31], v[102:103]
	v_pk_mul_f32 v[74:75], v[78:79], v[74:75]
	v_mul_f32_e32 v80, 0xbfb8aa3b, v102
	v_pk_mul_f32 v[78:79], v[74:75], v[98:99]
	v_mul_f32_e32 v75, 0xbfb8aa3b, v103
	v_exp_f32_e32 v80, v80
	v_exp_f32_e32 v75, v75
	v_and_b32_e32 v129, 0xffff0000, v84
	v_and_b32_e32 v99, 0xffff0000, v76
	v_add_f32_e32 v74, 1.0, v80
	v_add_f32_e32 v75, 1.0, v75
	v_rcp_f32_e32 v74, v74
	v_lshlrev_b32_e32 v98, 16, v76
	v_pk_mul_f32 v[108:109], v[6:7], v[128:129]
	v_rcp_f32_e32 v75, v75
	v_and_b32_e32 v127, 0xffff0000, v89
	v_pk_fma_f32 v[98:99], v[2:3], v[98:99], v[108:109]
	v_and_b32_e32 v109, 0xffff0000, v81
	v_lshlrev_b32_e32 v108, 16, v81
	v_pk_mul_f32 v[80:81], v[28:29], v[126:127]
	v_and_b32_e32 v101, 0xffff0000, v68
	v_pk_fma_f32 v[80:81], v[20:21], v[108:109], v[80:81]
	v_and_b32_e32 v97, 0xffff0000, v73
	v_pk_fma_f32 v[98:99], v[10:11], v[100:101], v[98:99]
	v_pk_fma_f32 v[80:81], v[24:25], v[96:97], v[80:81]
	v_pk_add_f32 v[98:99], v[14:15], v[98:99]
	v_pk_add_f32 v[80:81], v[32:33], v[80:81]
	v_pk_mul_f32 v[74:75], v[102:103], v[74:75]
	v_mul_f32_e32 v76, 0xbfb8aa3b, v80
	v_pk_mul_f32 v[98:99], v[74:75], v[98:99]
	v_mul_f32_e32 v75, 0xbfb8aa3b, v81
	v_exp_f32_e32 v76, v76
	v_exp_f32_e32 v75, v75
	v_and_b32_e32 v125, 0xffff0000, v85
	v_and_b32_e32 v103, 0xffff0000, v77
	v_add_f32_e32 v74, 1.0, v76
	v_add_f32_e32 v75, 1.0, v75
	v_rcp_f32_e32 v74, v74
	v_rcp_f32_e32 v75, v75
	v_lshlrev_b32_e32 v102, 16, v77
	v_pk_mul_f32 v[76:77], v[8:9], v[124:125]
	v_and_b32_e32 v93, 0xffff0000, v69
	v_pk_fma_f32 v[76:77], v[4:5], v[102:103], v[76:77]
	v_pk_mul_f32 v[74:75], v[80:81], v[74:75]
	v_pk_fma_f32 v[76:77], v[12:13], v[92:93], v[76:77]
	s_movk_i32 s8, 0x1600
	v_pk_add_f32 v[76:77], v[16:17], v[76:77]
	s_nop 0
	v_pk_mul_f32 v[80:81], v[74:75], v[76:77]
	v_cvt_pk_bf16_f32 v75, v78, v79
	v_add_u32_e32 v78, s4, v151
	v_cvt_pk_bf16_f32 v74, v94, v95
	v_cvt_pk_bf16_f32 v76, v98, v99
	v_cvt_pk_bf16_f32 v77, v80, v81
	v_mad_i64_i32 v[78:79], s[10:11], v78, s8, v[90:91]
	global_store_dwordx4 v[78:79], v[74:77], off sc1
.LBB0_3449:
	s_or_b64 exec, exec, s[2:3]
	v_or_b32_e32 v152, 1, v151
	s_movk_i32 s2, 0xff
	v_cmp_gt_u32_e32 vcc, s2, v152
	v_mov_b32_e32 v74, 0
	v_mov_b32_e32 v78, 0
	v_mov_b32_e32 v79, 0
	v_mov_b32_e32 v80, 0
	v_mov_b32_e32 v81, 0
	s_and_saveexec_b64 s[2:3], vcc
	v_mul_u32_u24_e32 v75, 0x210, v152
	v_add3_u32 v75, 0, v75, v150
	ds_read_b128 v[78:81], v75 offset:1552
	s_or_b64 exec, exec, s[2:3]
	v_mov_b32_e32 v75, 0
	v_mov_b32_e32 v76, 0
	v_mov_b32_e32 v77, 0
	s_and_saveexec_b64 s[2:3], vcc
	v_mul_u32_u24_e32 v74, 0x210, v152
	v_add3_u32 v74, 0, v74, v150
	ds_read_b128 v[74:77], v74 offset:1680
	s_or_b64 exec, exec, s[2:3]
	v_cmp_le_u32_e32 vcc, s9, v152
	v_cmp_gt_u32_e64 s[2:3], s5, v151
	s_and_b64 s[10:11], vcc, s[2:3]
	s_waitcnt lgkmcnt(0)
	v_lshlrev_b32_e32 v122, 16, v78
	v_lshlrev_b32_e32 v120, 16, v74
	v_lshlrev_b32_e32 v116, 16, v79
	v_lshlrev_b32_e32 v110, 16, v75
	v_lshlrev_b32_e32 v108, 16, v80
	v_lshlrev_b32_e32 v102, 16, v76
	v_lshlrev_b32_e32 v98, 16, v81
	v_lshlrev_b32_e32 v94, 16, v77
	s_and_saveexec_b64 s[2:3], s[10:11]
	s_cbranch_execz .LBB0_3455
	v_and_b32_e32 v119, 0xffff0000, v70
	v_and_b32_e32 v139, 0xffff0000, v86
	s_waitcnt vmcnt(0)
	v_pk_mul_f32 v[154:155], v[58:59], v[118:119]
	v_and_b32_e32 v123, 0xffff0000, v78
	v_pk_fma_f32 v[138:139], v[50:51], v[138:139], v[154:155]
	v_and_b32_e32 v137, 0xffff0000, v82
	v_pk_fma_f32 v[138:139], v[54:55], v[122:123], v[138:139]
	v_and_b32_e32 v113, 0xffff0000, v71
	v_pk_add_f32 v[138:139], v[62:63], v[138:139]
	v_and_b32_e32 v135, 0xffff0000, v87
	v_mul_f32_e32 v86, 0xbfb8aa3b, v138
	v_exp_f32_e32 v86, v86
	v_and_b32_e32 v117, 0xffff0000, v79
	v_and_b32_e32 v133, 0xffff0000, v83
	v_and_b32_e32 v115, 0xffff0000, v66
	v_add_f32_e32 v82, 1.0, v86
	v_rcp_f32_e32 v154, v82
	v_mul_f32_e32 v82, 0xbfb8aa3b, v139
	v_exp_f32_e32 v82, v82
	v_pk_mul_f32 v[86:87], v[60:61], v[112:113]
	v_pk_mul_f32 v[156:157], v[46:47], v[114:115]
	v_pk_fma_f32 v[86:87], v[52:53], v[134:135], v[86:87]
	v_add_f32_e32 v82, 1.0, v82
	v_pk_fma_f32 v[86:87], v[56:57], v[116:117], v[86:87]
	v_rcp_f32_e32 v155, v82
	v_pk_add_f32 v[86:87], v[64:65], v[86:87]
	v_pk_fma_f32 v[136:137], v[38:39], v[136:137], v[156:157]
	v_mul_f32_e32 v82, 0xbfb8aa3b, v86
	v_mul_f32_e32 v83, 0xbfb8aa3b, v87
	v_exp_f32_e32 v82, v82
	v_exp_f32_e32 v83, v83
	v_and_b32_e32 v121, 0xffff0000, v74
	v_pk_fma_f32 v[136:137], v[42:43], v[120:121], v[136:137]
	v_add_f32_e32 v82, 1.0, v82
	v_pk_add_f32 v[134:135], v[34:35], v[136:137]
	v_pk_mul_f32 v[136:137], v[138:139], v[154:155]
	v_and_b32_e32 v107, 0xffff0000, v67
	v_add_f32_e32 v83, 1.0, v83
	v_pk_mul_f32 v[134:135], v[136:137], v[134:135]
	v_rcp_f32_e32 v82, v82
	v_pk_mul_f32 v[136:137], v[48:49], v[106:107]
	v_rcp_f32_e32 v83, v83
	v_and_b32_e32 v105, 0xffff0000, v72
	v_pk_fma_f32 v[132:133], v[40:41], v[132:133], v[136:137]
	v_and_b32_e32 v131, 0xffff0000, v88
	v_pk_mul_f32 v[136:137], v[26:27], v[104:105]
	v_and_b32_e32 v111, 0xffff0000, v75
	v_pk_fma_f32 v[130:131], v[18:19], v[130:131], v[136:137]
	v_and_b32_e32 v109, 0xffff0000, v80
	v_pk_fma_f32 v[132:133], v[44:45], v[110:111], v[132:133]
	v_pk_fma_f32 v[130:131], v[22:23], v[108:109], v[130:131]
	v_pk_add_f32 v[132:133], v[36:37], v[132:133]
	v_pk_add_f32 v[130:131], v[30:31], v[130:131]
	v_pk_mul_f32 v[82:83], v[86:87], v[82:83]
	v_mul_f32_e32 v88, 0xbfb8aa3b, v130
	v_pk_mul_f32 v[86:87], v[82:83], v[132:133]
	v_mul_f32_e32 v83, 0xbfb8aa3b, v131
	v_exp_f32_e32 v88, v88
	v_exp_f32_e32 v83, v83
	v_and_b32_e32 v101, 0xffff0000, v68
	v_and_b32_e32 v97, 0xffff0000, v73
	v_add_f32_e32 v82, 1.0, v88
	v_add_f32_e32 v83, 1.0, v83
	v_rcp_f32_e32 v82, v82
	v_rcp_f32_e32 v83, v83
	v_and_b32_e32 v129, 0xffff0000, v84
	v_pk_mul_f32 v[132:133], v[6:7], v[100:101]
	v_and_b32_e32 v127, 0xffff0000, v89
	v_pk_mul_f32 v[88:89], v[28:29], v[96:97]
	v_pk_fma_f32 v[128:129], v[2:3], v[128:129], v[132:133]
	v_and_b32_e32 v103, 0xffff0000, v76
	v_pk_fma_f32 v[88:89], v[20:21], v[126:127], v[88:89]
	v_and_b32_e32 v99, 0xffff0000, v81
	v_pk_fma_f32 v[128:129], v[10:11], v[102:103], v[128:129]
	v_pk_fma_f32 v[88:89], v[24:25], v[98:99], v[88:89]
	v_pk_add_f32 v[126:127], v[14:15], v[128:129]
	v_pk_add_f32 v[88:89], v[32:33], v[88:89]
	v_pk_mul_f32 v[82:83], v[130:131], v[82:83]
	v_mul_f32_e32 v84, 0xbfb8aa3b, v88
	v_pk_mul_f32 v[126:127], v[82:83], v[126:127]
	v_mul_f32_e32 v83, 0xbfb8aa3b, v89
	v_exp_f32_e32 v84, v84
	v_exp_f32_e32 v83, v83
	v_and_b32_e32 v93, 0xffff0000, v69
	v_and_b32_e32 v125, 0xffff0000, v85
	v_add_f32_e32 v82, 1.0, v84
	v_add_f32_e32 v83, 1.0, v83
	v_rcp_f32_e32 v82, v82
	v_rcp_f32_e32 v83, v83
	v_pk_mul_f32 v[84:85], v[8:9], v[92:93]
	v_and_b32_e32 v95, 0xffff0000, v77
	v_pk_fma_f32 v[84:85], v[4:5], v[124:125], v[84:85]
	v_pk_mul_f32 v[82:83], v[88:89], v[82:83]
	v_pk_fma_f32 v[84:85], v[12:13], v[94:95], v[84:85]
	s_movk_i32 s8, 0x1600
	v_pk_add_f32 v[84:85], v[16:17], v[84:85]
	s_nop 0
	v_pk_mul_f32 v[88:89], v[82:83], v[84:85]
	v_cvt_pk_bf16_f32 v83, v86, v87
	v_add_u32_e32 v86, s4, v152
	v_cvt_pk_bf16_f32 v82, v134, v135
	v_cvt_pk_bf16_f32 v84, v126, v127
	v_cvt_pk_bf16_f32 v85, v88, v89
	v_mad_i64_i32 v[86:87], s[10:11], v86, s8, v[90:91]
	global_store_dwordx4 v[86:87], v[82:85], off sc1
.LBB0_3455:
	s_or_b64 exec, exec, s[2:3]
	v_or_b32_e32 v151, 2, v151
	s_movk_i32 s2, 0xff
	v_cmp_gt_u32_e32 vcc, s2, v151
	v_mov_b32_e32 v82, 0
	v_mov_b32_e32 v86, 0
	v_mov_b32_e32 v87, 0
	v_mov_b32_e32 v88, 0
	v_mov_b32_e32 v89, 0
	s_and_saveexec_b64 s[2:3], vcc
	v_mul_u32_u24_e32 v83, 0x210, v151
	v_add3_u32 v83, 0, v83, v150
	ds_read_b128 v[86:89], v83 offset:1552
	s_or_b64 exec, exec, s[2:3]
	v_mov_b32_e32 v83, 0
	v_mov_b32_e32 v84, 0
	v_mov_b32_e32 v85, 0
	s_and_saveexec_b64 s[2:3], vcc
	v_mul_u32_u24_e32 v82, 0x210, v151
	v_add3_u32 v82, 0, v82, v150
	ds_read_b128 v[82:85], v82 offset:1680
	s_or_b64 exec, exec, s[2:3]
	v_cmp_le_u32_e32 vcc, s9, v151
	v_cmp_ge_u32_e64 s[2:3], s5, v151
	s_and_b64 s[10:11], vcc, s[2:3]
	s_waitcnt lgkmcnt(0)
	v_lshlrev_b32_e32 v138, 16, v86
	v_lshlrev_b32_e32 v136, 16, v82
	v_lshlrev_b32_e32 v134, 16, v87
	v_lshlrev_b32_e32 v132, 16, v83
	v_lshlrev_b32_e32 v130, 16, v88
	v_lshlrev_b32_e32 v128, 16, v84
	v_lshlrev_b32_e32 v126, 16, v89
	v_lshlrev_b32_e32 v124, 16, v85
	s_and_saveexec_b64 s[2:3], s[10:11]
	s_cbranch_execz .LBB0_3461
	v_and_b32_e32 v123, 0xffff0000, v78
	v_and_b32_e32 v119, 0xffff0000, v70
	s_waitcnt vmcnt(0)
	v_pk_mul_f32 v[152:153], v[58:59], v[122:123]
	v_and_b32_e32 v139, 0xffff0000, v86
	v_pk_fma_f32 v[118:119], v[50:51], v[118:119], v[152:153]
	v_and_b32_e32 v115, 0xffff0000, v66
	v_pk_fma_f32 v[118:119], v[54:55], v[138:139], v[118:119]
	v_and_b32_e32 v117, 0xffff0000, v79
	v_pk_add_f32 v[118:119], v[62:63], v[118:119]
	v_and_b32_e32 v113, 0xffff0000, v71
	v_mul_f32_e32 v70, 0xbfb8aa3b, v118
	v_exp_f32_e32 v70, v70
	v_and_b32_e32 v135, 0xffff0000, v87
	v_and_b32_e32 v107, 0xffff0000, v67
	v_and_b32_e32 v121, 0xffff0000, v74
	v_add_f32_e32 v66, 1.0, v70
	v_rcp_f32_e32 v152, v66
	v_mul_f32_e32 v66, 0xbfb8aa3b, v119
	v_exp_f32_e32 v66, v66
	v_pk_mul_f32 v[70:71], v[60:61], v[116:117]
	v_pk_mul_f32 v[154:155], v[46:47], v[120:121]
	v_pk_fma_f32 v[70:71], v[52:53], v[112:113], v[70:71]
	v_add_f32_e32 v66, 1.0, v66
	v_pk_fma_f32 v[70:71], v[56:57], v[134:135], v[70:71]
	v_rcp_f32_e32 v153, v66
	v_pk_add_f32 v[70:71], v[64:65], v[70:71]
	v_pk_fma_f32 v[114:115], v[38:39], v[114:115], v[154:155]
	v_mul_f32_e32 v66, 0xbfb8aa3b, v70
	v_mul_f32_e32 v67, 0xbfb8aa3b, v71
	v_exp_f32_e32 v66, v66
	v_exp_f32_e32 v67, v67
	v_and_b32_e32 v137, 0xffff0000, v82
	v_pk_fma_f32 v[114:115], v[42:43], v[136:137], v[114:115]
	v_add_f32_e32 v66, 1.0, v66
	v_pk_add_f32 v[112:113], v[34:35], v[114:115]
	v_pk_mul_f32 v[114:115], v[118:119], v[152:153]
	v_and_b32_e32 v111, 0xffff0000, v75
	v_add_f32_e32 v67, 1.0, v67
	v_pk_mul_f32 v[112:113], v[114:115], v[112:113]
	v_rcp_f32_e32 v66, v66
	v_pk_mul_f32 v[114:115], v[48:49], v[110:111]
	v_rcp_f32_e32 v67, v67
	v_and_b32_e32 v109, 0xffff0000, v80
	v_pk_fma_f32 v[106:107], v[40:41], v[106:107], v[114:115]
	v_and_b32_e32 v105, 0xffff0000, v72
	v_pk_mul_f32 v[114:115], v[26:27], v[108:109]
	v_and_b32_e32 v133, 0xffff0000, v83
	v_pk_fma_f32 v[104:105], v[18:19], v[104:105], v[114:115]
	v_and_b32_e32 v131, 0xffff0000, v88
	v_pk_fma_f32 v[106:107], v[44:45], v[132:133], v[106:107]
	v_pk_fma_f32 v[104:105], v[22:23], v[130:131], v[104:105]
	v_pk_add_f32 v[106:107], v[36:37], v[106:107]
	v_pk_add_f32 v[104:105], v[30:31], v[104:105]
	v_pk_mul_f32 v[66:67], v[70:71], v[66:67]
	v_mul_f32_e32 v72, 0xbfb8aa3b, v104
	v_pk_mul_f32 v[70:71], v[66:67], v[106:107]
	v_mul_f32_e32 v67, 0xbfb8aa3b, v105
	v_exp_f32_e32 v72, v72
	v_exp_f32_e32 v67, v67
	v_and_b32_e32 v103, 0xffff0000, v76
	v_and_b32_e32 v99, 0xffff0000, v81
	v_add_f32_e32 v66, 1.0, v72
	v_add_f32_e32 v67, 1.0, v67
	v_rcp_f32_e32 v66, v66
	v_rcp_f32_e32 v67, v67
	v_and_b32_e32 v101, 0xffff0000, v68
	v_pk_mul_f32 v[106:107], v[6:7], v[102:103]
	v_and_b32_e32 v97, 0xffff0000, v73
	v_pk_mul_f32 v[72:73], v[28:29], v[98:99]
	v_pk_fma_f32 v[100:101], v[2:3], v[100:101], v[106:107]
	v_and_b32_e32 v129, 0xffff0000, v84
	v_pk_fma_f32 v[72:73], v[20:21], v[96:97], v[72:73]
	v_and_b32_e32 v127, 0xffff0000, v89
	v_pk_fma_f32 v[100:101], v[10:11], v[128:129], v[100:101]
	v_pk_fma_f32 v[72:73], v[24:25], v[126:127], v[72:73]
	v_pk_add_f32 v[96:97], v[14:15], v[100:101]
	v_pk_add_f32 v[72:73], v[32:33], v[72:73]
	v_pk_mul_f32 v[66:67], v[104:105], v[66:67]
	v_mul_f32_e32 v68, 0xbfb8aa3b, v72
	v_pk_mul_f32 v[96:97], v[66:67], v[96:97]
	v_mul_f32_e32 v67, 0xbfb8aa3b, v73
	v_exp_f32_e32 v68, v68
	v_exp_f32_e32 v67, v67
	v_and_b32_e32 v95, 0xffff0000, v77
	v_and_b32_e32 v93, 0xffff0000, v69
	v_add_f32_e32 v66, 1.0, v68
	v_add_f32_e32 v67, 1.0, v67
	v_rcp_f32_e32 v66, v66
	v_rcp_f32_e32 v67, v67
	v_pk_mul_f32 v[68:69], v[8:9], v[94:95]
	v_and_b32_e32 v125, 0xffff0000, v85
	v_pk_fma_f32 v[68:69], v[4:5], v[92:93], v[68:69]
	v_pk_mul_f32 v[66:67], v[72:73], v[66:67]
	v_pk_fma_f32 v[68:69], v[12:13], v[124:125], v[68:69]
	s_movk_i32 s8, 0x1600
	v_pk_add_f32 v[68:69], v[16:17], v[68:69]
	s_nop 0
	v_pk_mul_f32 v[72:73], v[66:67], v[68:69]
	v_cvt_pk_bf16_f32 v67, v70, v71
	v_add_u32_e32 v70, s4, v151
	v_cvt_pk_bf16_f32 v66, v112, v113
	v_cvt_pk_bf16_f32 v68, v96, v97
	v_cvt_pk_bf16_f32 v69, v72, v73
	v_mad_i64_i32 v[70:71], s[10:11], v70, s8, v[90:91]
	global_store_dwordx4 v[70:71], v[66:69], off sc1
.LBB0_3461:
	s_or_b64 exec, exec, s[2:3]
	v_or_b32_e32 v92, 3, v1
	s_movk_i32 s2, 0xff
	v_cmp_gt_u32_e32 vcc, s2, v92
	v_mov_b32_e32 v66, 0
	v_mov_b32_e32 v70, 0
	v_mov_b32_e32 v71, 0
	v_mov_b32_e32 v72, 0
	v_mov_b32_e32 v73, 0
	s_and_saveexec_b64 s[2:3], vcc
	v_mul_u32_u24_e32 v67, 0x210, v92
	v_add3_u32 v67, 0, v67, v150
	ds_read_b128 v[70:73], v67 offset:1552
	s_or_b64 exec, exec, s[2:3]
	v_mov_b32_e32 v67, 0
	v_mov_b32_e32 v68, 0
	v_mov_b32_e32 v69, 0
	s_and_saveexec_b64 s[2:3], vcc
	v_mul_u32_u24_e32 v66, 0x210, v92
	v_add3_u32 v66, 0, v66, v150
	ds_read_b128 v[66:69], v66 offset:1680
	s_or_b64 exec, exec, s[2:3]
	v_cmp_le_u32_e32 vcc, s9, v92
	v_cmp_ge_u32_e64 s[2:3], s5, v92
	s_and_b64 s[8:9], vcc, s[2:3]
	s_and_saveexec_b64 s[2:3], s[8:9]
	s_cbranch_execz .LBB0_3467
	v_and_b32_e32 v139, 0xffff0000, v86
	v_and_b32_e32 v123, 0xffff0000, v78
	s_waitcnt vmcnt(0)
	v_pk_mul_f32 v[58:59], v[58:59], v[138:139]
	v_and_b32_e32 v137, 0xffff0000, v82
	v_pk_fma_f32 v[50:51], v[50:51], v[122:123], v[58:59]
	s_waitcnt lgkmcnt(0)
	v_and_b32_e32 v59, 0xffff0000, v70
	v_lshlrev_b32_e32 v58, 16, v70
	v_pk_fma_f32 v[50:51], v[54:55], v[58:59], v[50:51]
	v_and_b32_e32 v121, 0xffff0000, v74
	v_pk_add_f32 v[50:51], v[62:63], v[50:51]
	v_pk_mul_f32 v[46:47], v[46:47], v[136:137]
	v_mul_f32_e32 v54, 0xbfb8aa3b, v50
	v_pk_fma_f32 v[38:39], v[38:39], v[120:121], v[46:47]
	v_mul_f32_e32 v46, 0xbfb8aa3b, v51
	v_exp_f32_e32 v54, v54
	v_exp_f32_e32 v55, v46
	v_and_b32_e32 v47, 0xffff0000, v66
	v_lshlrev_b32_e32 v46, 16, v66
	v_add_f32_e32 v54, 1.0, v54
	v_pk_fma_f32 v[38:39], v[42:43], v[46:47], v[38:39]
	v_add_f32_e32 v42, 1.0, v55
	v_rcp_f32_e32 v54, v54
	v_rcp_f32_e32 v55, v42
	v_and_b32_e32 v135, 0xffff0000, v87
	v_and_b32_e32 v117, 0xffff0000, v79
	v_pk_mul_f32 v[42:43], v[60:61], v[134:135]
	v_and_b32_e32 v47, 0xffff0000, v71
	v_pk_fma_f32 v[42:43], v[52:53], v[116:117], v[42:43]
	v_lshlrev_b32_e32 v46, 16, v71
	v_pk_fma_f32 v[42:43], v[56:57], v[46:47], v[42:43]
	v_pk_add_f32 v[34:35], v[34:35], v[38:39]
	v_pk_add_f32 v[42:43], v[64:65], v[42:43]
	v_pk_mul_f32 v[38:39], v[50:51], v[54:55]
	v_mul_f32_e32 v46, 0xbfb8aa3b, v42
	v_pk_mul_f32 v[34:35], v[38:39], v[34:35]
	v_mul_f32_e32 v39, 0xbfb8aa3b, v43
	v_exp_f32_e32 v46, v46
	v_exp_f32_e32 v39, v39
	v_and_b32_e32 v131, 0xffff0000, v88
	v_and_b32_e32 v109, 0xffff0000, v80
	v_add_f32_e32 v38, 1.0, v46
	v_add_f32_e32 v39, 1.0, v39
	v_pk_mul_f32 v[26:27], v[26:27], v[130:131]
	v_rcp_f32_e32 v38, v38
	v_and_b32_e32 v133, 0xffff0000, v83
	v_rcp_f32_e32 v39, v39
	v_pk_fma_f32 v[18:19], v[18:19], v[108:109], v[26:27]
	v_and_b32_e32 v27, 0xffff0000, v72
	v_lshlrev_b32_e32 v26, 16, v72
	v_and_b32_e32 v111, 0xffff0000, v75
	v_pk_mul_f32 v[46:47], v[48:49], v[132:133]
	v_pk_fma_f32 v[18:19], v[22:23], v[26:27], v[18:19]
	v_pk_fma_f32 v[40:41], v[40:41], v[110:111], v[46:47]
	v_and_b32_e32 v47, 0xffff0000, v67
	v_lshlrev_b32_e32 v46, 16, v67
	v_pk_add_f32 v[18:19], v[30:31], v[18:19]
	v_and_b32_e32 v129, 0xffff0000, v84
	v_pk_fma_f32 v[40:41], v[44:45], v[46:47], v[40:41]
	v_mul_f32_e32 v22, 0xbfb8aa3b, v18
	v_and_b32_e32 v103, 0xffff0000, v76
	v_pk_mul_f32 v[6:7], v[6:7], v[128:129]
	v_exp_f32_e32 v30, v22
	v_pk_add_f32 v[22:23], v[36:37], v[40:41]
	v_pk_mul_f32 v[26:27], v[42:43], v[38:39]
	v_pk_fma_f32 v[2:3], v[2:3], v[102:103], v[6:7]
	v_mul_f32_e32 v6, 0xbfb8aa3b, v19
	v_pk_mul_f32 v[22:23], v[26:27], v[22:23]
	v_exp_f32_e32 v27, v6
	v_and_b32_e32 v7, 0xffff0000, v68
	v_lshlrev_b32_e32 v6, 16, v68
	v_pk_fma_f32 v[2:3], v[10:11], v[6:7], v[2:3]
	v_add_f32_e32 v6, 1.0, v27
	v_and_b32_e32 v127, 0xffff0000, v89
	v_add_f32_e32 v26, 1.0, v30
	v_rcp_f32_e32 v27, v6
	v_and_b32_e32 v99, 0xffff0000, v81
	v_pk_mul_f32 v[6:7], v[28:29], v[126:127]
	v_rcp_f32_e32 v26, v26
	v_pk_fma_f32 v[6:7], v[20:21], v[98:99], v[6:7]
	v_and_b32_e32 v11, 0xffff0000, v73
	v_lshlrev_b32_e32 v10, 16, v73
	v_pk_fma_f32 v[6:7], v[24:25], v[10:11], v[6:7]
	v_pk_add_f32 v[2:3], v[14:15], v[2:3]
	v_pk_add_f32 v[6:7], v[32:33], v[6:7]
	v_and_b32_e32 v125, 0xffff0000, v85
	v_mul_f32_e32 v10, 0xbfb8aa3b, v6
	v_exp_f32_e32 v20, v10
	v_pk_mul_f32 v[10:11], v[18:19], v[26:27]
	v_and_b32_e32 v95, 0xffff0000, v77
	v_pk_mul_f32 v[10:11], v[10:11], v[2:3]
	v_mul_f32_e32 v3, 0xbfb8aa3b, v7
	v_exp_f32_e32 v3, v3
	v_add_f32_e32 v2, 1.0, v20
	v_rcp_f32_e32 v2, v2
	v_pk_mul_f32 v[8:9], v[8:9], v[124:125]
	v_add_f32_e32 v3, 1.0, v3
	v_rcp_f32_e32 v3, v3
	v_pk_fma_f32 v[4:5], v[4:5], v[94:95], v[8:9]
	v_and_b32_e32 v9, 0xffff0000, v69
	v_lshlrev_b32_e32 v8, 16, v69
	v_pk_fma_f32 v[4:5], v[12:13], v[8:9], v[4:5]
	v_pk_mul_f32 v[2:3], v[6:7], v[2:3]
	v_pk_add_f32 v[4:5], v[16:17], v[4:5]
	s_nop 0
	v_pk_mul_f32 v[6:7], v[2:3], v[4:5]
	v_cvt_pk_bf16_f32 v2, v34, v35
	v_cvt_pk_bf16_f32 v5, v6, v7
	v_add_u32_e32 v6, s4, v92
	s_movk_i32 s4, 0x1600
	v_cvt_pk_bf16_f32 v3, v22, v23
	v_cvt_pk_bf16_f32 v4, v10, v11
	v_mad_i64_i32 v[6:7], s[4:5], v6, s4, v[90:91]
	global_store_dwordx4 v[6:7], v[2:5], off sc1

.LBB0_3574:
	global_load_dwordx4 v[20:23], v[20:21], off offset:3072
	s_add_u32 s4, s4, s6
	s_addc_u32 s5, s5, s7
	s_add_u32 s8, s8, s10
	s_addc_u32 s9, s9, s11
	s_cmpk_lt_i32 s4, 0x1800
	s_waitcnt vmcnt(0)
	v_pk_fma_f32 v[2:3], v[18:19], v[22:23], v[2:3]
	v_pk_fma_f32 v[0:1], v[16:17], v[20:21], v[0:1]
	global_store_dwordx4 v[14:15], v[0:3], off offset:3072 sc1
	s_cbranch_scc0 .LBB0_3587

.LBB0_3581:
	s_lshr_b32 s2, s2, 10
	s_mulk_i32 s2, 0x1800
	s_lshl_b64 s[20:21], s[20:21], 10
	s_addk_i32 s2, 0x1800
	s_and_b64 s[18:19], s[18:19], exec
	s_cselect_b32 s2, 0, s2
	v_lshl_add_u64 v[20:21], s[2:3], 2, v[10:11]
	global_load_dwordx4 v[30:33], v[20:21], off
	v_lshl_add_u64 v[14:15], s[20:21], 2, v[12:13]
	v_cndmask_b32_e64 v29, 0, 1, s[16:17]
	s_andn2_b64 vcc, exec, s[16:17]
	s_waitcnt vmcnt(0)
	v_pk_fma_f32 v[2:3], v[24:25], v[32:33], v[2:3]
	v_pk_fma_f32 v[0:1], v[22:23], v[30:31], v[0:1]
	global_store_dwordx4 v[14:15], v[0:3], off sc1
	global_load_dwordx2 v[24:25], v[16:17], off offset:512
	global_load_dwordx2 v[26:27], v[18:19], off offset:512
	v_lshl_add_u64 v[22:23], s[0:1], 0, v[4:5]
	global_load_dwordx4 v[0:3], v[22:23], off offset:1024
	v_cmp_ne_u32_e64 s[0:1], 1, v29
	s_waitcnt vmcnt(2)
	v_lshlrev_b32_e32 v30, 16, v24
	v_and_b32_e32 v31, 0xffff0000, v24
	s_waitcnt vmcnt(1)
	v_lshlrev_b32_e32 v32, 16, v26
	v_and_b32_e32 v33, 0xffff0000, v26
	v_lshlrev_b32_e32 v26, 16, v25
	v_lshlrev_b32_e32 v34, 16, v27
	v_and_b32_e32 v35, 0xffff0000, v27
	v_and_b32_e32 v27, 0xffff0000, v25
	v_pk_add_f32 v[24:25], v[30:31], v[32:33]
	v_pk_add_f32 v[26:27], v[26:27], v[34:35]
	s_cbranch_vccnz .LBB0_3583
	global_load_dwordx2 v[30:31], v28, s[12:13] offset:512
	global_load_dwordx2 v[32:33], v28, s[14:15] offset:512
	s_waitcnt vmcnt(1)
	v_lshlrev_b32_e32 v34, 16, v30
	v_and_b32_e32 v35, 0xffff0000, v30
	s_waitcnt vmcnt(0)
	v_lshlrev_b32_e32 v36, 16, v32
	v_and_b32_e32 v37, 0xffff0000, v32
	v_lshlrev_b32_e32 v30, 16, v31
	v_and_b32_e32 v31, 0xffff0000, v31
	v_lshlrev_b32_e32 v32, 16, v33
	v_and_b32_e32 v33, 0xffff0000, v33
	v_pk_add_f32 v[34:35], v[34:35], v[36:37]
	v_pk_add_f32 v[30:31], v[30:31], v[32:33]
	v_pk_add_f32 v[24:25], v[24:25], v[34:35]
	v_pk_add_f32 v[26:27], v[26:27], v[30:31]
.LBB0_3583:
	global_load_dwordx4 v[30:33], v[20:21], off offset:1024
	s_and_b64 vcc, exec, s[0:1]
	s_waitcnt vmcnt(0)
	v_pk_fma_f32 v[2:3], v[26:27], v[32:33], v[2:3]
	v_pk_fma_f32 v[0:1], v[24:25], v[30:31], v[0:1]
	global_store_dwordx4 v[14:15], v[0:3], off offset:1024 sc1
	global_load_dwordx2 v[24:25], v[16:17], off offset:1024
	global_load_dwordx2 v[26:27], v[18:19], off offset:1024
	s_nop 0
	global_load_dwordx4 v[0:3], v[22:23], off offset:2048
	s_waitcnt vmcnt(2)
	v_lshlrev_b32_e32 v30, 16, v24
	v_and_b32_e32 v31, 0xffff0000, v24
	s_waitcnt vmcnt(1)
	v_lshlrev_b32_e32 v32, 16, v26
	v_and_b32_e32 v33, 0xffff0000, v26
	v_lshlrev_b32_e32 v26, 16, v25
	v_lshlrev_b32_e32 v34, 16, v27
	v_and_b32_e32 v35, 0xffff0000, v27
	v_and_b32_e32 v27, 0xffff0000, v25
	v_pk_add_f32 v[24:25], v[30:31], v[32:33]
	v_pk_add_f32 v[26:27], v[26:27], v[34:35]
	s_cbranch_vccnz .LBB0_3585
	global_load_dwordx2 v[30:31], v28, s[12:13] offset:1024
	global_load_dwordx2 v[32:33], v28, s[14:15] offset:1024
	s_waitcnt vmcnt(1)
	v_lshlrev_b32_e32 v34, 16, v30
	v_and_b32_e32 v35, 0xffff0000, v30
	s_waitcnt vmcnt(0)
	v_lshlrev_b32_e32 v36, 16, v32
	v_and_b32_e32 v37, 0xffff0000, v32
	v_lshlrev_b32_e32 v30, 16, v31
	v_and_b32_e32 v31, 0xffff0000, v31
	v_lshlrev_b32_e32 v32, 16, v33
	v_and_b32_e32 v33, 0xffff0000, v33
	v_pk_add_f32 v[34:35], v[34:35], v[36:37]
	v_pk_add_f32 v[30:31], v[30:31], v[32:33]
	v_pk_add_f32 v[24:25], v[24:25], v[34:35]
	v_pk_add_f32 v[26:27], v[26:27], v[30:31]
.LBB0_3585:
	global_load_dwordx4 v[30:33], v[20:21], off offset:2048
	s_and_b64 vcc, exec, s[0:1]
	s_waitcnt vmcnt(0)
	v_pk_fma_f32 v[2:3], v[26:27], v[32:33], v[2:3]
	v_pk_fma_f32 v[0:1], v[24:25], v[30:31], v[0:1]
	global_store_dwordx4 v[14:15], v[0:3], off offset:2048 sc1
	global_load_dwordx2 v[24:25], v[16:17], off offset:1536
	global_load_dwordx2 v[26:27], v[18:19], off offset:1536
	s_nop 0
	global_load_dwordx4 v[0:3], v[22:23], off offset:3072
	s_waitcnt vmcnt(2)
	v_lshlrev_b32_e32 v16, 16, v24
	v_and_b32_e32 v17, 0xffff0000, v24
	s_waitcnt vmcnt(1)
	v_lshlrev_b32_e32 v18, 16, v26
	v_and_b32_e32 v19, 0xffff0000, v26
	v_lshlrev_b32_e32 v22, 16, v25
	v_lshlrev_b32_e32 v26, 16, v27
	v_and_b32_e32 v27, 0xffff0000, v27
	v_and_b32_e32 v23, 0xffff0000, v25
	v_pk_add_f32 v[16:17], v[16:17], v[18:19]
	v_pk_add_f32 v[18:19], v[22:23], v[26:27]
	s_cbranch_vccnz .LBB0_3574
	global_load_dwordx2 v[22:23], v28, s[12:13] offset:1536
	global_load_dwordx2 v[24:25], v28, s[14:15] offset:1536
	s_waitcnt vmcnt(1)
	v_lshlrev_b32_e32 v26, 16, v22
	v_and_b32_e32 v27, 0xffff0000, v22
	s_waitcnt vmcnt(0)
	v_lshlrev_b32_e32 v30, 16, v24
	v_and_b32_e32 v31, 0xffff0000, v24
	v_lshlrev_b32_e32 v22, 16, v23
	v_and_b32_e32 v23, 0xffff0000, v23
	v_lshlrev_b32_e32 v24, 16, v25
	v_and_b32_e32 v25, 0xffff0000, v25
	v_pk_add_f32 v[26:27], v[26:27], v[30:31]
	v_pk_add_f32 v[22:23], v[22:23], v[24:25]
	v_pk_add_f32 v[16:17], v[16:17], v[26:27]
	v_pk_add_f32 v[18:19], v[18:19], v[22:23]
	s_branch .LBB0_3574
